# v21 + K-loops: the barrier closing each MFMA segment is signalled 4 MFMAs (fp8: 2) before the segment's end, so the other half's MFMAs start while this wave issues its last ones
# baseline (speedup 1.0000x reference)
; #define PG8_STAGE(bufoff, gbase, voff) do { _Pragma("unroll") for (int _i = 0; _i < 2; ++_i) \
;         __builtin_amdgcn_global_load_lds((const unsigned*)((const char*)(gbase) + (voff)[_i]), (PG8_LAS unsigned*)(lds + (bufoff) + ldsw + _i * 8192), 16, 0, 0); } while (0)
; #define PG8_WAIT_V(n) asm volatile("s_waitcnt vmcnt(" #n ")" ::: "memory")
; #define PG8_WAIT_L(n) asm volatile("s_waitcnt lgkmcnt(" #n ")" ::: "memory")
; #define PG8_BAR __builtin_amdgcn_s_barrier()
; #define PG8_SCHED __builtin_amdgcn_sched_barrier(0)
;     __device__ __forceinline__ int nt(const pg8::Unit& u) const { return u.kind == 0 ? ntiles : q_nt(u.kind - 1); }
; template <class Epi, class Sched, bool ALIGN_EPI = true, bool SP2 = true>
; __device__ __forceinline__ void gemm_phase(PG8_LAS unsigned char* lds, const int K  , const Sched& S, const Epi& E) {
;     ...
;             const bool last = (t == nt - 2);
;             const char* a1 = cA + (size_t)(t + 1) * kstep;
;             const char* a2 = last ? nA : cA + (size_t)(t + 2) * kstep; const char* b2 = last ? nB : cB + (size_t)(t + 2) * kstep;
;             const char* a3 = a2 + kstep; const char* b3 = b2 + kstep;
;             if constexpr (SP2) {
;             PG8_LDB(B0, 0, 0); PG8_LDB(B1, 0, 1); PG8_SCHED; PG8_LDA(At, 0, 0); PG8_STAGE(PG8_SA(1, 1), a1 + hstep, voffA);
;             PG8_WAIT_V(8); PG8_WAIT_L(0); PG8_BAR; PG8_MMA(0, 0, At, B0); PG8_MMA(0, 1, At, B1); PG8_BAR; PG8_SCHED;
;             PG8_LDA(At, 0, 1); PG8_STAGE(PG8_SB(0, 0), b2, voffB); PG8_STAGE(PG8_SB(0, 1), b2 + hstep, voffB); PG8_STAGE(PG8_SA(0, 0), a2, voffA);
.LBB0_219:
	ds_read_b128 v[148:151], v154
	ds_read_b128 v[160:163], v154 offset:1024
	ds_read_b128 v[164:167], v154 offset:2048
	ds_read_b128 v[168:171], v154 offset:3072
	ds_read_b128 v[172:175], v155
	ds_read_b128 v[176:179], v155 offset:1024
	ds_read_b128 v[180:183], v155 offset:2048
	ds_read_b128 v[184:187], v155 offset:3072
	s_add_u32 s22, s20, 0xfff80080
	s_addc_u32 s23, s21, -1
	s_cmp_eq_u32 s48, 28
	s_cselect_b32 s25, s13, s23
	s_cselect_b32 s24, s44, s22
	s_cselect_b32 s23, s11, s47
	s_cselect_b32 s22, s45, s46
	v_lshl_add_u64 v[220:221], s[20:21], 0, v[140:141]
	s_add_i32 m0, s19, 0xc000
	ds_read_b128 v[188:191], v156
	ds_read_b128 v[192:195], v156 offset:1024
	ds_read_b128 v[196:199], v156 offset:2048
	ds_read_b128 v[200:203], v156 offset:3072
	ds_read_b128 v[204:207], v156 offset:4096
	ds_read_b128 v[208:211], v156 offset:5120
	ds_read_b128 v[212:215], v156 offset:6144
	ds_read_b128 v[216:219], v156 offset:7168
	global_load_lds_dwordx4 v[220:221], off
	v_lshl_add_u64 v[220:221], s[20:21], 0, v[142:143]
	s_add_i32 m0, s19, 0xe000
	s_nop 0
	global_load_lds_dwordx4 v[220:221], off
	s_waitcnt vmcnt(8)
	s_waitcnt lgkmcnt(0)
	s_setprio 1
	s_barrier
	v_mfma_f32_16x16x32_bf16 v[126:129], v[148:151], v[188:191], v[126:129]
	v_mfma_f32_16x16x32_bf16 v[118:121], v[164:167], v[188:191], v[118:121]
	v_mfma_f32_16x16x32_bf16 v[110:113], v[148:151], v[196:199], v[110:113]
	v_mfma_f32_16x16x32_bf16 v[102:105], v[164:167], v[196:199], v[102:105]
	v_mfma_f32_16x16x32_bf16 v[94:97], v[148:151], v[204:207], v[94:97]
	v_mfma_f32_16x16x32_bf16 v[86:89], v[164:167], v[204:207], v[86:89]
	v_mfma_f32_16x16x32_bf16 v[78:81], v[148:151], v[212:215], v[78:81]
	v_mfma_f32_16x16x32_bf16 v[70:73], v[164:167], v[212:215], v[70:73]
	v_mfma_f32_16x16x32_bf16 v[126:129], v[160:163], v[192:195], v[126:129]
	v_mfma_f32_16x16x32_bf16 v[118:121], v[168:171], v[192:195], v[118:121]
	v_mfma_f32_16x16x32_bf16 v[110:113], v[160:163], v[200:203], v[110:113]
	v_mfma_f32_16x16x32_bf16 v[102:105], v[168:171], v[200:203], v[102:105]
	v_mfma_f32_16x16x32_bf16 v[94:97], v[160:163], v[208:211], v[94:97]
	v_mfma_f32_16x16x32_bf16 v[86:89], v[168:171], v[208:211], v[86:89]
	v_mfma_f32_16x16x32_bf16 v[78:81], v[160:163], v[216:219], v[78:81]
	v_mfma_f32_16x16x32_bf16 v[70:73], v[168:171], v[216:219], v[70:73]
	s_setprio 0
	s_setprio 1
	v_mfma_f32_16x16x32_bf16 v[122:125], v[172:175], v[188:191], v[122:125]
	v_mfma_f32_16x16x32_bf16 v[114:117], v[180:183], v[188:191], v[114:117]
	v_mfma_f32_16x16x32_bf16 v[106:109], v[172:175], v[196:199], v[106:109]
	v_mfma_f32_16x16x32_bf16 v[98:101], v[180:183], v[196:199], v[98:101]
	v_mfma_f32_16x16x32_bf16 v[90:93], v[172:175], v[204:207], v[90:93]
	v_mfma_f32_16x16x32_bf16 v[82:85], v[180:183], v[204:207], v[82:85]
	v_mfma_f32_16x16x32_bf16 v[74:77], v[172:175], v[212:215], v[74:77]
	v_mfma_f32_16x16x32_bf16 v[66:69], v[180:183], v[212:215], v[66:69]
	v_mfma_f32_16x16x32_bf16 v[122:125], v[176:179], v[192:195], v[122:125]
	v_mfma_f32_16x16x32_bf16 v[114:117], v[184:187], v[192:195], v[114:117]
	v_mfma_f32_16x16x32_bf16 v[106:109], v[176:179], v[200:203], v[106:109]
	v_mfma_f32_16x16x32_bf16 v[98:101], v[184:187], v[200:203], v[98:101]
	s_barrier
	v_mfma_f32_16x16x32_bf16 v[90:93], v[176:179], v[208:211], v[90:93]
	v_mfma_f32_16x16x32_bf16 v[82:85], v[184:187], v[208:211], v[82:85]
	v_mfma_f32_16x16x32_bf16 v[74:77], v[176:179], v[216:219], v[74:77]
	v_mfma_f32_16x16x32_bf16 v[66:69], v[184:187], v[216:219], v[66:69]
	s_setprio 0
	s_add_i32 s49, s39, s29
	v_lshl_add_u64 v[220:221], s[22:23], 0, v[136:137]
	s_mov_b32 m0, s49
	ds_read_b128 v[188:191], v156 offset:16384
	ds_read_b128 v[192:195], v156 offset:17408
	ds_read_b128 v[196:199], v156 offset:18432
	ds_read_b128 v[200:203], v156 offset:19456
	ds_read_b128 v[204:207], v156 offset:20480
	ds_read_b128 v[208:211], v156 offset:21504
	ds_read_b128 v[212:215], v156 offset:22528
	ds_read_b128 v[216:219], v156 offset:23552
	global_load_lds_dwordx4 v[220:221], off
	s_add_i32 m0, s49, 0x2000
	s_add_u32 s50, s22, 0x80000
	v_lshl_add_u64 v[222:223], s[22:23], 0, v[132:133]
	s_addc_u32 s51, s23, 0
	s_add_i32 s49, s40, s29
	global_load_lds_dwordx4 v[222:223], off
	v_lshl_add_u64 v[224:225], s[50:51], 0, v[136:137]
	s_mov_b32 m0, s49
	v_lshl_add_u64 v[226:227], s[24:25], 0, v[134:135]
	global_load_lds_dwordx4 v[224:225], off
	v_lshl_add_u64 v[224:225], s[50:51], 0, v[132:133]
	s_add_i32 m0, s49, 0x2000
	s_nop 0
	global_load_lds_dwordx4 v[224:225], off
	v_lshl_add_u64 v[224:225], s[24:25], 0, v[138:139]
	s_mov_b32 m0, s19
	s_nop 0
	global_load_lds_dwordx4 v[224:225], off
	s_mov_b32 m0, s31
	s_nop 0
	global_load_lds_dwordx4 v[226:227], off
	s_waitcnt vmcnt(8)
	s_waitcnt lgkmcnt(0)
	s_setprio 1
	s_barrier
; #define PG8_STAGE(bufoff, gbase, voff) do { _Pragma("unroll") for (int _i = 0; _i < 2; ++_i) \
;         __builtin_amdgcn_global_load_lds((const unsigned*)((const char*)(gbase) + (voff)[_i]), (PG8_LAS unsigned*)(lds + (bufoff) + ldsw + _i * 8192), 16, 0, 0); } while (0)
; #define PG8_WAIT_V(n) asm volatile("s_waitcnt vmcnt(" #n ")" ::: "memory")
; #define PG8_WAIT_L(n) asm volatile("s_waitcnt lgkmcnt(" #n ")" ::: "memory")
; #define PG8_BAR __builtin_amdgcn_s_barrier()
; #define PG8_SCHED __builtin_amdgcn_sched_barrier(0)
; template <class Epi, class Sched, bool ALIGN_EPI = true, bool SP2 = true>
; __device__ __forceinline__ void gemm_phase(PG8_LAS unsigned char* lds, const int K  , const Sched& S, const Epi& E) {
;     ...
;             PG8_WAIT_V(8); PG8_WAIT_L(0); PG8_BAR; PG8_MMA(1, 0, At, B0); PG8_MMA(1, 1, At, B1); PG8_BAR; PG8_SCHED;
;             PG8_LDB(B0, 1, 0); PG8_LDB(B1, 1, 1); PG8_SCHED; PG8_LDA(At, 1, 0); PG8_STAGE(PG8_SA(0, 1), a2 + hstep, voffA);
;             PG8_WAIT_V(8); PG8_WAIT_L(0); PG8_BAR; PG8_MMA(0, 0, At, B0); PG8_MMA(0, 1, At, B1); PG8_BAR; PG8_SCHED;
	v_mfma_f32_16x16x32_bf16 v[62:65], v[148:151], v[188:191], v[62:65]
	v_mfma_f32_16x16x32_bf16 v[54:57], v[164:167], v[188:191], v[54:57]
	v_mfma_f32_16x16x32_bf16 v[46:49], v[148:151], v[196:199], v[46:49]
	v_mfma_f32_16x16x32_bf16 v[38:41], v[164:167], v[196:199], v[38:41]
	v_mfma_f32_16x16x32_bf16 v[30:33], v[148:151], v[204:207], v[30:33]
	v_mfma_f32_16x16x32_bf16 v[22:25], v[164:167], v[204:207], v[22:25]
	v_mfma_f32_16x16x32_bf16 v[14:17], v[148:151], v[212:215], v[14:17]
	v_mfma_f32_16x16x32_bf16 v[6:9], v[164:167], v[212:215], v[6:9]
	v_mfma_f32_16x16x32_bf16 v[62:65], v[160:163], v[192:195], v[62:65]
	v_mfma_f32_16x16x32_bf16 v[54:57], v[168:171], v[192:195], v[54:57]
	v_mfma_f32_16x16x32_bf16 v[46:49], v[160:163], v[200:203], v[46:49]
	v_mfma_f32_16x16x32_bf16 v[38:41], v[168:171], v[200:203], v[38:41]
	v_mfma_f32_16x16x32_bf16 v[30:33], v[160:163], v[208:211], v[30:33]
	v_mfma_f32_16x16x32_bf16 v[22:25], v[168:171], v[208:211], v[22:25]
	v_mfma_f32_16x16x32_bf16 v[14:17], v[160:163], v[216:219], v[14:17]
	v_mfma_f32_16x16x32_bf16 v[6:9], v[168:171], v[216:219], v[6:9]
	s_setprio 0
	s_setprio 1
	v_mfma_f32_16x16x32_bf16 v[58:61], v[172:175], v[188:191], v[58:61]
	v_mfma_f32_16x16x32_bf16 v[50:53], v[180:183], v[188:191], v[50:53]
	v_mfma_f32_16x16x32_bf16 v[42:45], v[172:175], v[196:199], v[42:45]
	v_mfma_f32_16x16x32_bf16 v[34:37], v[180:183], v[196:199], v[34:37]
	v_mfma_f32_16x16x32_bf16 v[26:29], v[172:175], v[204:207], v[26:29]
	v_mfma_f32_16x16x32_bf16 v[18:21], v[180:183], v[204:207], v[18:21]
	v_mfma_f32_16x16x32_bf16 v[10:13], v[172:175], v[212:215], v[10:13]
	v_mfma_f32_16x16x32_bf16 v[2:5], v[180:183], v[212:215], v[2:5]
	v_mfma_f32_16x16x32_bf16 v[58:61], v[176:179], v[192:195], v[58:61]
	v_mfma_f32_16x16x32_bf16 v[50:53], v[184:187], v[192:195], v[50:53]
	v_mfma_f32_16x16x32_bf16 v[42:45], v[176:179], v[200:203], v[42:45]
	v_mfma_f32_16x16x32_bf16 v[34:37], v[184:187], v[200:203], v[34:37]
	s_barrier
	v_mfma_f32_16x16x32_bf16 v[26:29], v[176:179], v[208:211], v[26:29]
	v_mfma_f32_16x16x32_bf16 v[18:21], v[184:187], v[208:211], v[18:21]
	v_mfma_f32_16x16x32_bf16 v[10:13], v[176:179], v[216:219], v[10:13]
	v_mfma_f32_16x16x32_bf16 v[2:5], v[184:187], v[216:219], v[2:5]
	s_setprio 0
	s_add_i32 s49, 0, 0x18000
	v_add_u32_e32 v159, s49, v152
	s_add_i32 s50, 0, 0x1c000
	ds_read_b128 v[148:151], v159
	ds_read_b128 v[160:163], v159 offset:1024
	ds_read_b128 v[164:167], v159 offset:2048
	ds_read_b128 v[168:171], v159 offset:3072
	v_add_u32_e32 v159, s50, v152
	ds_read_b128 v[172:175], v159
	ds_read_b128 v[176:179], v159 offset:1024
	ds_read_b128 v[180:183], v159 offset:2048
	ds_read_b128 v[184:187], v159 offset:3072
	s_add_u32 s24, s24, 0x80000
	s_addc_u32 s25, s25, 0
	s_mov_b32 m0, s33
	v_lshl_add_u64 v[230:231], s[24:25], 0, v[138:139]
	ds_read_b128 v[188:191], v156 offset:32768
	ds_read_b128 v[192:195], v156 offset:33792
	ds_read_b128 v[196:199], v156 offset:34816
	ds_read_b128 v[200:203], v156 offset:35840
	ds_read_b128 v[204:207], v156 offset:36864
	ds_read_b128 v[208:211], v156 offset:37888
	ds_read_b128 v[212:215], v156 offset:38912
	ds_read_b128 v[216:219], v156 offset:39936
	global_load_lds_dwordx4 v[230:231], off
	v_lshl_add_u64 v[230:231], s[24:25], 0, v[134:135]
	s_mov_b32 m0, s34
	s_nop 0
	global_load_lds_dwordx4 v[230:231], off
	s_waitcnt vmcnt(8)
	s_waitcnt lgkmcnt(0)
	s_setprio 1
	s_barrier
	v_mfma_f32_16x16x32_bf16 v[126:129], v[148:151], v[188:191], v[126:129]
	v_mfma_f32_16x16x32_bf16 v[118:121], v[164:167], v[188:191], v[118:121]
	v_mfma_f32_16x16x32_bf16 v[110:113], v[148:151], v[196:199], v[110:113]
	v_mfma_f32_16x16x32_bf16 v[102:105], v[164:167], v[196:199], v[102:105]
	v_mfma_f32_16x16x32_bf16 v[94:97], v[148:151], v[204:207], v[94:97]
	v_mfma_f32_16x16x32_bf16 v[86:89], v[164:167], v[204:207], v[86:89]
	v_mfma_f32_16x16x32_bf16 v[78:81], v[148:151], v[212:215], v[78:81]
	v_mfma_f32_16x16x32_bf16 v[70:73], v[164:167], v[212:215], v[70:73]
	v_mfma_f32_16x16x32_bf16 v[126:129], v[160:163], v[192:195], v[126:129]
	v_mfma_f32_16x16x32_bf16 v[118:121], v[168:171], v[192:195], v[118:121]
	v_mfma_f32_16x16x32_bf16 v[110:113], v[160:163], v[200:203], v[110:113]
	v_mfma_f32_16x16x32_bf16 v[102:105], v[168:171], v[200:203], v[102:105]
	v_mfma_f32_16x16x32_bf16 v[94:97], v[160:163], v[208:211], v[94:97]
	v_mfma_f32_16x16x32_bf16 v[86:89], v[168:171], v[208:211], v[86:89]
	v_mfma_f32_16x16x32_bf16 v[78:81], v[160:163], v[216:219], v[78:81]
	v_mfma_f32_16x16x32_bf16 v[70:73], v[168:171], v[216:219], v[70:73]
	s_setprio 0
	s_setprio 1
	v_mfma_f32_16x16x32_bf16 v[122:125], v[172:175], v[188:191], v[122:125]
	v_mfma_f32_16x16x32_bf16 v[114:117], v[180:183], v[188:191], v[114:117]
	v_mfma_f32_16x16x32_bf16 v[106:109], v[172:175], v[196:199], v[106:109]
	v_mfma_f32_16x16x32_bf16 v[98:101], v[180:183], v[196:199], v[98:101]
	v_mfma_f32_16x16x32_bf16 v[90:93], v[172:175], v[204:207], v[90:93]
	v_mfma_f32_16x16x32_bf16 v[82:85], v[180:183], v[204:207], v[82:85]
	v_mfma_f32_16x16x32_bf16 v[74:77], v[172:175], v[212:215], v[74:77]
	v_mfma_f32_16x16x32_bf16 v[66:69], v[180:183], v[212:215], v[66:69]
	v_mfma_f32_16x16x32_bf16 v[122:125], v[176:179], v[192:195], v[122:125]
	v_mfma_f32_16x16x32_bf16 v[114:117], v[184:187], v[192:195], v[114:117]
	v_mfma_f32_16x16x32_bf16 v[106:109], v[176:179], v[200:203], v[106:109]
	v_mfma_f32_16x16x32_bf16 v[98:101], v[184:187], v[200:203], v[98:101]
	s_barrier
; #define PG8_STAGE(bufoff, gbase, voff) do { _Pragma("unroll") for (int _i = 0; _i < 2; ++_i) \
;         __builtin_amdgcn_global_load_lds((const unsigned*)((const char*)(gbase) + (voff)[_i]), (PG8_LAS unsigned*)(lds + (bufoff) + ldsw + _i * 8192), 16, 0, 0); } while (0)
; #define PG8_WAIT_V(n) asm volatile("s_waitcnt vmcnt(" #n ")" ::: "memory")
; #define PG8_WAIT_L(n) asm volatile("s_waitcnt lgkmcnt(" #n ")" ::: "memory")
; #define PG8_BAR __builtin_amdgcn_s_barrier()
; #define PG8_SCHED __builtin_amdgcn_sched_barrier(0)
; template <class Epi, class Sched, bool ALIGN_EPI = true, bool SP2 = true>
; __device__ __forceinline__ void gemm_phase(PG8_LAS unsigned char* lds, const int K  , const Sched& S, const Epi& E) {
;     ...
;             PG8_WAIT_V(8); PG8_WAIT_L(0); PG8_BAR; PG8_MMA(0, 0, At, B0); PG8_MMA(0, 1, At, B1); PG8_BAR; PG8_SCHED;
;             PG8_LDA(At, 1, 1); PG8_STAGE(PG8_SB(1, 0), b3, voffB); PG8_STAGE(PG8_SB(1, 1), b3 + hstep, voffB); PG8_STAGE(PG8_SA(1, 0), a3, voffA);
;             PG8_WAIT_V(8); PG8_WAIT_L(0); PG8_BAR; PG8_MMA(1, 0, At, B0); PG8_MMA(1, 1, At, B1); PG8_BAR; PG8_SCHED;
	v_mfma_f32_16x16x32_bf16 v[90:93], v[176:179], v[208:211], v[90:93]
	v_mfma_f32_16x16x32_bf16 v[82:85], v[184:187], v[208:211], v[82:85]
	v_mfma_f32_16x16x32_bf16 v[74:77], v[176:179], v[216:219], v[74:77]
	v_mfma_f32_16x16x32_bf16 v[66:69], v[184:187], v[216:219], v[66:69]
	s_setprio 0
	s_add_i32 s24, s49, s29
	v_lshl_add_u64 v[220:221], v[220:221], 0, s[6:7]
	s_mov_b32 m0, s24
	ds_read_b128 v[188:191], v156 offset:49152
	ds_read_b128 v[192:195], v156 offset:50176
	ds_read_b128 v[196:199], v156 offset:51200
	ds_read_b128 v[200:203], v156 offset:52224
	ds_read_b128 v[204:207], v156 offset:53248
	ds_read_b128 v[208:211], v156 offset:54272
	ds_read_b128 v[212:215], v156 offset:55296
	ds_read_b128 v[216:219], v156 offset:56320
	global_load_lds_dwordx4 v[220:221], off
	s_add_i32 m0, s24, 0x2000
	s_add_u32 s22, s22, 0x80080
	v_lshl_add_u64 v[220:221], v[222:223], 0, s[6:7]
	s_addc_u32 s23, s23, 0
	s_add_i32 s24, s50, s29
	global_load_lds_dwordx4 v[220:221], off
	v_lshl_add_u64 v[220:221], s[22:23], 0, v[136:137]
	s_mov_b32 m0, s24
	s_nop 0
	global_load_lds_dwordx4 v[220:221], off
	v_lshl_add_u64 v[220:221], s[22:23], 0, v[132:133]
	s_add_i32 m0, s24, 0x2000
	s_nop 0
	global_load_lds_dwordx4 v[220:221], off
	v_lshl_add_u64 v[220:221], v[224:225], 0, s[6:7]
	s_mov_b32 m0, s36
	s_nop 0
	global_load_lds_dwordx4 v[220:221], off
	v_lshl_add_u64 v[220:221], v[226:227], 0, s[6:7]
	s_mov_b32 m0, s37
	s_nop 0
	global_load_lds_dwordx4 v[220:221], off
	s_waitcnt vmcnt(8)
	s_waitcnt lgkmcnt(0)
	s_setprio 1
	s_barrier
	v_mfma_f32_16x16x32_bf16 v[62:65], v[148:151], v[188:191], v[62:65]
	v_mfma_f32_16x16x32_bf16 v[54:57], v[164:167], v[188:191], v[54:57]
	v_mfma_f32_16x16x32_bf16 v[46:49], v[148:151], v[196:199], v[46:49]
	v_mfma_f32_16x16x32_bf16 v[38:41], v[164:167], v[196:199], v[38:41]
	v_mfma_f32_16x16x32_bf16 v[30:33], v[148:151], v[204:207], v[30:33]
	v_mfma_f32_16x16x32_bf16 v[22:25], v[164:167], v[204:207], v[22:25]
	v_mfma_f32_16x16x32_bf16 v[14:17], v[148:151], v[212:215], v[14:17]
	v_mfma_f32_16x16x32_bf16 v[6:9], v[164:167], v[212:215], v[6:9]
	v_mfma_f32_16x16x32_bf16 v[62:65], v[160:163], v[192:195], v[62:65]
	v_mfma_f32_16x16x32_bf16 v[54:57], v[168:171], v[192:195], v[54:57]
	v_mfma_f32_16x16x32_bf16 v[46:49], v[160:163], v[200:203], v[46:49]
	v_mfma_f32_16x16x32_bf16 v[38:41], v[168:171], v[200:203], v[38:41]
	v_mfma_f32_16x16x32_bf16 v[30:33], v[160:163], v[208:211], v[30:33]
	v_mfma_f32_16x16x32_bf16 v[22:25], v[168:171], v[208:211], v[22:25]
	v_mfma_f32_16x16x32_bf16 v[14:17], v[160:163], v[216:219], v[14:17]
	v_mfma_f32_16x16x32_bf16 v[6:9], v[168:171], v[216:219], v[6:9]
	s_setprio 0
	s_setprio 1
	v_mfma_f32_16x16x32_bf16 v[58:61], v[172:175], v[188:191], v[58:61]
	v_mfma_f32_16x16x32_bf16 v[50:53], v[180:183], v[188:191], v[50:53]
	v_mfma_f32_16x16x32_bf16 v[42:45], v[172:175], v[196:199], v[42:45]
	v_mfma_f32_16x16x32_bf16 v[34:37], v[180:183], v[196:199], v[34:37]
	v_mfma_f32_16x16x32_bf16 v[26:29], v[172:175], v[204:207], v[26:29]
	v_mfma_f32_16x16x32_bf16 v[18:21], v[180:183], v[204:207], v[18:21]
	v_mfma_f32_16x16x32_bf16 v[10:13], v[172:175], v[212:215], v[10:13]
	v_mfma_f32_16x16x32_bf16 v[2:5], v[180:183], v[212:215], v[2:5]
	v_mfma_f32_16x16x32_bf16 v[58:61], v[176:179], v[192:195], v[58:61]
	v_mfma_f32_16x16x32_bf16 v[50:53], v[184:187], v[192:195], v[50:53]
	v_mfma_f32_16x16x32_bf16 v[42:45], v[176:179], v[200:203], v[42:45]
	v_mfma_f32_16x16x32_bf16 v[34:37], v[184:187], v[200:203], v[34:37]
	s_barrier
	v_mfma_f32_16x16x32_bf16 v[26:29], v[176:179], v[208:211], v[26:29]
	v_mfma_f32_16x16x32_bf16 v[18:21], v[184:187], v[208:211], v[18:21]
	v_mfma_f32_16x16x32_bf16 v[10:13], v[176:179], v[216:219], v[10:13]
	v_mfma_f32_16x16x32_bf16 v[2:5], v[184:187], v[216:219], v[2:5]
	s_setprio 0
	s_add_i32 s48, s48, 2
	s_add_u32 s20, s20, 0x100
	s_addc_u32 s21, s21, 0
	s_add_u32 s46, s46, 0x100
	s_addc_u32 s47, s47, 0
	s_cmp_gt_u32 s48, 29
	s_cbranch_scc0 .LBB0_219
	s_and_b64 vcc, exec, s[8:9]
	s_cbranch_vccz .LBB0_222
	s_barrier

; #define PG8_STAGE(bufoff, gbase, voff) do { _Pragma("unroll") for (int _i = 0; _i < 2; ++_i) \
;         __builtin_amdgcn_global_load_lds((const unsigned*)((const char*)(gbase) + (voff)[_i]), (PG8_LAS unsigned*)(lds + (bufoff) + ldsw + _i * 8192), 16, 0, 0); } while (0)
; #define PG8_WAIT_V(n) asm volatile("s_waitcnt vmcnt(" #n ")" ::: "memory")
; #define PG8_WAIT_L(n) asm volatile("s_waitcnt lgkmcnt(" #n ")" ::: "memory")
; #define PG8_BAR __builtin_amdgcn_s_barrier()
; #define PG8_SCHED __builtin_amdgcn_sched_barrier(0)
;     __device__ __forceinline__ int nt(const pg8::Unit& u) const { return u.kind == 0 ? ntiles : q_nt(u.kind - 1); }
; template <class Epi, class Sched, bool ALIGN_EPI = true, bool SP2 = true>
; __device__ __forceinline__ void gemm_phase(PG8_LAS unsigned char* lds, const int K  , const Sched& S, const Epi& E) {
;     ...
;             const bool last = (t == nt - 2);
;             const char* a1 = cA + (size_t)(t + 1) * kstep;
;             const char* a2 = last ? nA : cA + (size_t)(t + 2) * kstep; const char* b2 = last ? nB : cB + (size_t)(t + 2) * kstep;
;             const char* a3 = a2 + kstep; const char* b3 = b2 + kstep;
;             if constexpr (SP2) {
;             PG8_LDB(B0, 0, 0); PG8_LDB(B1, 0, 1); PG8_SCHED; PG8_LDA(At, 0, 0); PG8_STAGE(PG8_SA(1, 1), a1 + hstep, voffA);
;             PG8_WAIT_V(8); PG8_WAIT_L(0); PG8_BAR; PG8_MMA(0, 0, At, B0); PG8_MMA(0, 1, At, B1); PG8_BAR; PG8_SCHED;
;             PG8_LDA(At, 0, 1); PG8_STAGE(PG8_SB(0, 0), b2, voffB); PG8_STAGE(PG8_SB(0, 1), b2 + hstep, voffB); PG8_STAGE(PG8_SA(0, 0), a2, voffA);
;             PG8_WAIT_V(8); PG8_WAIT_L(0); PG8_BAR; PG8_MMA(1, 0, At, B0); PG8_MMA(1, 1, At, B1); PG8_BAR; PG8_SCHED;
.LBB0_393:
	ds_read_b128 v[18:21], v190
	ds_read_b128 v[22:25], v190 offset:1024
	ds_read_b128 v[26:29], v190 offset:2048
	ds_read_b128 v[30:33], v190 offset:3072
	ds_read_b128 v[2:5], v191
	ds_read_b128 v[6:9], v191 offset:1024
	ds_read_b128 v[10:13], v191 offset:2048
	ds_read_b128 v[14:17], v191 offset:3072
	s_add_i32 s50, s22, 2
	s_add_u32 s20, s18, 0xfff50080
	s_addc_u32 s21, s19, -1
	s_cmp_eq_u32 s47, s22
	s_cselect_b32 s22, s14, s20
	s_cselect_b32 s23, s15, s21
	s_cselect_b32 s21, s17, s49
	s_cselect_b32 s20, s16, s48
	v_lshl_add_u64 v[218:219], s[18:19], 0, v[170:171]
	s_add_i32 m0, s26, 0xc000
	ds_read_b128 v[178:181], v192
	ds_read_b128 v[182:185], v192 offset:1024
	ds_read_b128 v[194:197], v192 offset:2048
	ds_read_b128 v[198:201], v192 offset:3072
	ds_read_b128 v[202:205], v192 offset:4096
	ds_read_b128 v[206:209], v192 offset:5120
	ds_read_b128 v[210:213], v192 offset:6144
	ds_read_b128 v[214:217], v192 offset:7168
	global_load_lds_dwordx4 v[218:219], off
	v_lshl_add_u64 v[218:219], s[18:19], 0, v[172:173]
	s_add_i32 m0, s26, 0xe000
	s_nop 0
	global_load_lds_dwordx4 v[218:219], off
	s_waitcnt vmcnt(8)
	s_waitcnt lgkmcnt(0)
	s_setprio 1
	s_barrier
	v_mfma_scale_f32_16x16x128_f8f6f4 v[158:161], v[18:25], v[178:185], v[158:161], v186, v186 op_sel_hi:[0,0,0]
	v_mfma_scale_f32_16x16x128_f8f6f4 v[154:157], v[26:33], v[178:185], v[154:157], v186, v186 op_sel_hi:[0,0,0]
	v_mfma_scale_f32_16x16x128_f8f6f4 v[150:153], v[18:25], v[194:201], v[150:153], v186, v186 op_sel_hi:[0,0,0]
	v_mfma_scale_f32_16x16x128_f8f6f4 v[142:145], v[26:33], v[194:201], v[142:145], v186, v186 op_sel_hi:[0,0,0]
	v_mfma_scale_f32_16x16x128_f8f6f4 v[134:137], v[18:25], v[202:209], v[134:137], v186, v186 op_sel_hi:[0,0,0]
	v_mfma_scale_f32_16x16x128_f8f6f4 v[126:129], v[26:33], v[202:209], v[126:129], v186, v186 op_sel_hi:[0,0,0]
	v_mfma_scale_f32_16x16x128_f8f6f4 v[118:121], v[18:25], v[210:217], v[118:121], v186, v186 op_sel_hi:[0,0,0]
	v_mfma_scale_f32_16x16x128_f8f6f4 v[110:113], v[26:33], v[210:217], v[110:113], v186, v186 op_sel_hi:[0,0,0]
	s_setprio 0
	s_setprio 1
	v_mfma_scale_f32_16x16x128_f8f6f4 v[146:149], v[2:9], v[178:185], v[146:149], v186, v186 op_sel_hi:[0,0,0]
	v_mfma_scale_f32_16x16x128_f8f6f4 v[138:141], v[10:17], v[178:185], v[138:141], v186, v186 op_sel_hi:[0,0,0]
	v_mfma_scale_f32_16x16x128_f8f6f4 v[130:133], v[2:9], v[194:201], v[130:133], v186, v186 op_sel_hi:[0,0,0]
	v_mfma_scale_f32_16x16x128_f8f6f4 v[122:125], v[10:17], v[194:201], v[122:125], v186, v186 op_sel_hi:[0,0,0]
	v_mfma_scale_f32_16x16x128_f8f6f4 v[114:117], v[2:9], v[202:209], v[114:117], v186, v186 op_sel_hi:[0,0,0]
	v_mfma_scale_f32_16x16x128_f8f6f4 v[106:109], v[10:17], v[202:209], v[106:109], v186, v186 op_sel_hi:[0,0,0]
	s_barrier
	v_mfma_scale_f32_16x16x128_f8f6f4 v[102:105], v[2:9], v[210:217], v[102:105], v186, v186 op_sel_hi:[0,0,0]
	v_mfma_scale_f32_16x16x128_f8f6f4 v[98:101], v[10:17], v[210:217], v[98:101], v186, v186 op_sel_hi:[0,0,0]
	s_setprio 0
	s_add_i32 s51, s37, s25
	v_lshl_add_u64 v[178:179], s[20:21], 0, v[164:165]
	s_mov_b32 m0, s51
	ds_read_b128 v[194:197], v192 offset:16384
	ds_read_b128 v[198:201], v192 offset:17408
	ds_read_b128 v[202:205], v192 offset:18432
	ds_read_b128 v[206:209], v192 offset:19456
	ds_read_b128 v[210:213], v192 offset:20480
	ds_read_b128 v[214:217], v192 offset:21504
	ds_read_b128 v[218:221], v192 offset:22528
	ds_read_b128 v[222:225], v192 offset:23552
	global_load_lds_dwordx4 v[178:179], off
	s_add_i32 m0, s51, 0x2000
	s_add_u32 s68, s20, 0xb0000
	v_lshl_add_u64 v[180:181], s[20:21], 0, v[168:169]
	s_addc_u32 s69, s21, 0
	s_add_i32 s51, s38, s25
	global_load_lds_dwordx4 v[180:181], off
	v_lshl_add_u64 v[182:183], s[68:69], 0, v[164:165]
	s_mov_b32 m0, s51
	v_lshl_add_u64 v[184:185], s[22:23], 0, v[166:167]
	global_load_lds_dwordx4 v[182:183], off
	v_lshl_add_u64 v[182:183], s[68:69], 0, v[168:169]
	s_add_i32 m0, s51, 0x2000
	s_nop 0
	global_load_lds_dwordx4 v[182:183], off
	v_lshl_add_u64 v[182:183], s[22:23], 0, v[162:163]
	s_mov_b32 m0, s26
	s_nop 0
	global_load_lds_dwordx4 v[182:183], off
	s_mov_b32 m0, s27
	s_nop 0
	global_load_lds_dwordx4 v[184:185], off
	s_waitcnt vmcnt(8)
	s_waitcnt lgkmcnt(0)
	s_setprio 1
	s_barrier
	v_mfma_scale_f32_16x16x128_f8f6f4 v[94:97], v[18:25], v[194:201], v[94:97], v186, v186 op_sel_hi:[0,0,0]
	v_mfma_scale_f32_16x16x128_f8f6f4 v[90:93], v[26:33], v[194:201], v[90:93], v186, v186 op_sel_hi:[0,0,0]
	v_mfma_scale_f32_16x16x128_f8f6f4 v[86:89], v[18:25], v[202:209], v[86:89], v186, v186 op_sel_hi:[0,0,0]
	v_mfma_scale_f32_16x16x128_f8f6f4 v[78:81], v[26:33], v[202:209], v[78:81], v186, v186 op_sel_hi:[0,0,0]
	v_mfma_scale_f32_16x16x128_f8f6f4 v[70:73], v[18:25], v[210:217], v[70:73], v186, v186 op_sel_hi:[0,0,0]
	v_mfma_scale_f32_16x16x128_f8f6f4 v[62:65], v[26:33], v[210:217], v[62:65], v186, v186 op_sel_hi:[0,0,0]
	v_mfma_scale_f32_16x16x128_f8f6f4 v[54:57], v[18:25], v[218:225], v[54:57], v186, v186 op_sel_hi:[0,0,0]
	v_mfma_scale_f32_16x16x128_f8f6f4 v[46:49], v[26:33], v[218:225], v[46:49], v186, v186 op_sel_hi:[0,0,0]
	s_setprio 0
	s_setprio 1
	v_mfma_scale_f32_16x16x128_f8f6f4 v[82:85], v[2:9], v[194:201], v[82:85], v186, v186 op_sel_hi:[0,0,0]
	v_mfma_scale_f32_16x16x128_f8f6f4 v[74:77], v[10:17], v[194:201], v[74:77], v186, v186 op_sel_hi:[0,0,0]
	v_mfma_scale_f32_16x16x128_f8f6f4 v[66:69], v[2:9], v[202:209], v[66:69], v186, v186 op_sel_hi:[0,0,0]
	v_mfma_scale_f32_16x16x128_f8f6f4 v[58:61], v[10:17], v[202:209], v[58:61], v186, v186 op_sel_hi:[0,0,0]
	v_mfma_scale_f32_16x16x128_f8f6f4 v[50:53], v[2:9], v[210:217], v[50:53], v186, v186 op_sel_hi:[0,0,0]
	v_mfma_scale_f32_16x16x128_f8f6f4 v[42:45], v[10:17], v[210:217], v[42:45], v186, v186 op_sel_hi:[0,0,0]
	s_barrier
; #define PG8_WAIT_V(n) asm volatile("s_waitcnt vmcnt(" #n ")" ::: "memory")
; template <class Epi, class Sched, bool ALIGN_EPI = true, bool SP2 = true>
; __device__ __forceinline__ void gemm_phase(PG8_LAS unsigned char* lds, const int K  , const Sched& S, const Epi& E) {
;     ...
;             PG8_WAIT_V(8); PG8_WAIT_L(0); PG8_BAR; PG8_MMA(1, 0, At, B0); PG8_MMA(1, 1, At, B1); PG8_BAR; PG8_SCHED;
;             PG8_LDB(B0, 1, 0); PG8_LDB(B1, 1, 1); PG8_SCHED; PG8_LDA(At, 1, 0); PG8_STAGE(PG8_SA(0, 1), a2 + hstep, voffA);
;             PG8_WAIT_V(8); PG8_WAIT_L(0); PG8_BAR; PG8_MMA(0, 0, At, B0); PG8_MMA(0, 1, At, B1); PG8_BAR; PG8_SCHED;
;             PG8_LDA(At, 1, 1); PG8_STAGE(PG8_SB(1, 0), b3, voffB); PG8_STAGE(PG8_SB(1, 1), b3 + hstep, voffB); PG8_STAGE(PG8_SA(1, 0), a3, voffA);
;             PG8_WAIT_V(8); PG8_WAIT_L(0); PG8_BAR; PG8_MMA(1, 0, At, B0); PG8_MMA(1, 1, At, B1); PG8_BAR; PG8_SCHED;
;             } else {
;             PG8_LDB(B0, 0, 0); PG8_SCHED; PG8_LDA(At, 0, 0); PG8_STAGE(PG8_SA(1, 1), a1 + hstep, voffA);
;             PG8_WAIT_L(8); PG8_BAR; PG8_WAIT_L(0); PG8_MMA(0, 0, At, B0); PG8_BAR; PG8_SCHED;
;             PG8_LDB(B1, 0, 1); PG8_STAGE(PG8_SB(0, 0), b2, voffB);
;             PG8_BAR; PG8_WAIT_L(0); PG8_MMA(0, 1, At, B1); PG8_BAR;
;             PG8_LDA(At, 0, 1); PG8_STAGE(PG8_SA(0, 0), a2, voffA);
;             PG8_BAR; PG8_WAIT_L(0); PG8_MMA(1, 0, At, B0); PG8_BAR; PG8_SCHED;
;             PG8_STAGE(PG8_SB(0, 1), b2 + hstep, voffB);
;             PG8_WAIT_V(6); PG8_BAR; PG8_MMA(1, 1, At, B1); PG8_BAR;
;             PG8_LDB(B0, 1, 0); PG8_SCHED; PG8_LDA(At, 1, 0); PG8_STAGE(PG8_SA(0, 1), a2 + hstep, voffA);
;             PG8_WAIT_L(8); PG8_BAR; PG8_WAIT_L(0); PG8_MMA(0, 0, At, B0); PG8_BAR; PG8_SCHED;
;             PG8_LDB(B1, 1, 1); PG8_STAGE(PG8_SB(1, 0), b3, voffB);
;             PG8_BAR; PG8_WAIT_L(0); PG8_MMA(0, 1, At, B1); PG8_BAR;
;             PG8_LDA(At, 1, 1); PG8_STAGE(PG8_SA(1, 0), a3, voffA);
;             PG8_BAR; PG8_WAIT_L(0); PG8_MMA(1, 0, At, B0); PG8_BAR; PG8_SCHED;
;             PG8_STAGE(PG8_SB(1, 1), b3 + hstep, voffB);
;             PG8_WAIT_V(6); PG8_BAR; PG8_MMA(1, 1, At, B1); PG8_BAR;
;             }
;         }
;         if constexpr (Epi::FP8) asm volatile("s_nop 15\n\ts_nop 15\n\ts_nop 15\n\ts_nop 15\n\ts_nop 15" ::: "memory");
;         if constexpr (ALIGN_EPI) { if (wr == 0) PG8_BAR; }
	v_mfma_scale_f32_16x16x128_f8f6f4 v[38:41], v[2:9], v[218:225], v[38:41], v186, v186 op_sel_hi:[0,0,0]
	v_mfma_scale_f32_16x16x128_f8f6f4 v[34:37], v[10:17], v[218:225], v[34:37], v186, v186 op_sel_hi:[0,0,0]
	s_setprio 0
	s_add_i32 s51, 0, 0x18000
	s_add_i32 s68, 0, 0x1c000
	v_add_u32_e32 v14, s51, v188
	v_add_u32_e32 v30, s68, v188
	ds_read_b128 v[2:5], v14
	ds_read_b128 v[6:9], v14 offset:1024
	ds_read_b128 v[10:13], v14 offset:2048
	ds_read_b128 v[14:17], v14 offset:3072
	ds_read_b128 v[18:21], v30
	ds_read_b128 v[22:25], v30 offset:1024
	ds_read_b128 v[26:29], v30 offset:2048
	ds_read_b128 v[30:33], v30 offset:3072
	s_add_u32 s22, s22, 0xb0000
	s_addc_u32 s23, s23, 0
	s_mov_b32 m0, s28
	v_lshl_add_u64 v[226:227], s[22:23], 0, v[162:163]
	ds_read_b128 v[194:197], v192 offset:32768
	ds_read_b128 v[198:201], v192 offset:33792
	ds_read_b128 v[202:205], v192 offset:34816
	ds_read_b128 v[206:209], v192 offset:35840
	ds_read_b128 v[210:213], v192 offset:36864
	ds_read_b128 v[214:217], v192 offset:37888
	ds_read_b128 v[218:221], v192 offset:38912
	ds_read_b128 v[222:225], v192 offset:39936
	global_load_lds_dwordx4 v[226:227], off
	v_lshl_add_u64 v[226:227], s[22:23], 0, v[166:167]
	s_mov_b32 m0, s29
	s_nop 0
	global_load_lds_dwordx4 v[226:227], off
	s_waitcnt vmcnt(8)
	s_waitcnt lgkmcnt(0)
	s_setprio 1
	s_barrier
	v_mfma_scale_f32_16x16x128_f8f6f4 v[158:161], v[2:9], v[194:201], v[158:161], v186, v186 op_sel_hi:[0,0,0]
	v_mfma_scale_f32_16x16x128_f8f6f4 v[154:157], v[10:17], v[194:201], v[154:157], v186, v186 op_sel_hi:[0,0,0]
	v_mfma_scale_f32_16x16x128_f8f6f4 v[150:153], v[2:9], v[202:209], v[150:153], v186, v186 op_sel_hi:[0,0,0]
	v_mfma_scale_f32_16x16x128_f8f6f4 v[142:145], v[10:17], v[202:209], v[142:145], v186, v186 op_sel_hi:[0,0,0]
	v_mfma_scale_f32_16x16x128_f8f6f4 v[134:137], v[2:9], v[210:217], v[134:137], v186, v186 op_sel_hi:[0,0,0]
	v_mfma_scale_f32_16x16x128_f8f6f4 v[126:129], v[10:17], v[210:217], v[126:129], v186, v186 op_sel_hi:[0,0,0]
	v_mfma_scale_f32_16x16x128_f8f6f4 v[118:121], v[2:9], v[218:225], v[118:121], v186, v186 op_sel_hi:[0,0,0]
	v_mfma_scale_f32_16x16x128_f8f6f4 v[110:113], v[10:17], v[218:225], v[110:113], v186, v186 op_sel_hi:[0,0,0]
	s_setprio 0
	s_setprio 1
	v_mfma_scale_f32_16x16x128_f8f6f4 v[146:149], v[18:25], v[194:201], v[146:149], v186, v186 op_sel_hi:[0,0,0]
	v_mfma_scale_f32_16x16x128_f8f6f4 v[138:141], v[26:33], v[194:201], v[138:141], v186, v186 op_sel_hi:[0,0,0]
	v_mfma_scale_f32_16x16x128_f8f6f4 v[130:133], v[18:25], v[202:209], v[130:133], v186, v186 op_sel_hi:[0,0,0]
	v_mfma_scale_f32_16x16x128_f8f6f4 v[122:125], v[26:33], v[202:209], v[122:125], v186, v186 op_sel_hi:[0,0,0]
	v_mfma_scale_f32_16x16x128_f8f6f4 v[114:117], v[18:25], v[210:217], v[114:117], v186, v186 op_sel_hi:[0,0,0]
	v_mfma_scale_f32_16x16x128_f8f6f4 v[106:109], v[26:33], v[210:217], v[106:109], v186, v186 op_sel_hi:[0,0,0]
	s_barrier
	v_mfma_scale_f32_16x16x128_f8f6f4 v[102:105], v[18:25], v[218:225], v[102:105], v186, v186 op_sel_hi:[0,0,0]
	v_mfma_scale_f32_16x16x128_f8f6f4 v[98:101], v[26:33], v[218:225], v[98:101], v186, v186 op_sel_hi:[0,0,0]
	s_setprio 0
	s_add_i32 s22, s51, s25
	v_lshl_add_u64 v[178:179], v[178:179], 0, s[8:9]
	s_mov_b32 m0, s22
	ds_read_b128 v[194:197], v192 offset:49152
	ds_read_b128 v[198:201], v192 offset:50176
	ds_read_b128 v[202:205], v192 offset:51200
	ds_read_b128 v[206:209], v192 offset:52224
	ds_read_b128 v[210:213], v192 offset:53248
	ds_read_b128 v[214:217], v192 offset:54272
	ds_read_b128 v[218:221], v192 offset:55296
	ds_read_b128 v[222:225], v192 offset:56320
	global_load_lds_dwordx4 v[178:179], off
	s_add_i32 m0, s22, 0x2000
	s_add_u32 s20, s20, 0xb0080
	v_lshl_add_u64 v[178:179], v[180:181], 0, s[8:9]
	s_addc_u32 s21, s21, 0
	s_add_i32 s22, s68, s25
	global_load_lds_dwordx4 v[178:179], off
	v_lshl_add_u64 v[178:179], s[20:21], 0, v[164:165]
	s_mov_b32 m0, s22
	s_nop 0
	global_load_lds_dwordx4 v[178:179], off
	v_lshl_add_u64 v[178:179], s[20:21], 0, v[168:169]
	s_add_i32 m0, s22, 0x2000
	s_nop 0
	global_load_lds_dwordx4 v[178:179], off
	v_lshl_add_u64 v[178:179], v[182:183], 0, s[8:9]
	s_mov_b32 m0, s33
	s_nop 0
	global_load_lds_dwordx4 v[178:179], off
	v_lshl_add_u64 v[178:179], v[184:185], 0, s[8:9]
	s_mov_b32 m0, s34
	s_nop 0
	global_load_lds_dwordx4 v[178:179], off
	s_waitcnt vmcnt(8)
	s_waitcnt lgkmcnt(0)
	s_setprio 1
	s_barrier
	v_mfma_scale_f32_16x16x128_f8f6f4 v[94:97], v[2:9], v[194:201], v[94:97], v186, v186 op_sel_hi:[0,0,0]
	v_mfma_scale_f32_16x16x128_f8f6f4 v[90:93], v[10:17], v[194:201], v[90:93], v186, v186 op_sel_hi:[0,0,0]
	v_mfma_scale_f32_16x16x128_f8f6f4 v[86:89], v[2:9], v[202:209], v[86:89], v186, v186 op_sel_hi:[0,0,0]
	v_mfma_scale_f32_16x16x128_f8f6f4 v[78:81], v[10:17], v[202:209], v[78:81], v186, v186 op_sel_hi:[0,0,0]
	v_mfma_scale_f32_16x16x128_f8f6f4 v[70:73], v[2:9], v[210:217], v[70:73], v186, v186 op_sel_hi:[0,0,0]
	v_mfma_scale_f32_16x16x128_f8f6f4 v[62:65], v[10:17], v[210:217], v[62:65], v186, v186 op_sel_hi:[0,0,0]
	v_mfma_scale_f32_16x16x128_f8f6f4 v[54:57], v[2:9], v[218:225], v[54:57], v186, v186 op_sel_hi:[0,0,0]
	v_mfma_scale_f32_16x16x128_f8f6f4 v[46:49], v[10:17], v[218:225], v[46:49], v186, v186 op_sel_hi:[0,0,0]
	s_setprio 0
	s_setprio 1
	v_mfma_scale_f32_16x16x128_f8f6f4 v[82:85], v[18:25], v[194:201], v[82:85], v186, v186 op_sel_hi:[0,0,0]
	v_mfma_scale_f32_16x16x128_f8f6f4 v[74:77], v[26:33], v[194:201], v[74:77], v186, v186 op_sel_hi:[0,0,0]
	v_mfma_scale_f32_16x16x128_f8f6f4 v[66:69], v[18:25], v[202:209], v[66:69], v186, v186 op_sel_hi:[0,0,0]
	v_mfma_scale_f32_16x16x128_f8f6f4 v[58:61], v[26:33], v[202:209], v[58:61], v186, v186 op_sel_hi:[0,0,0]
	v_mfma_scale_f32_16x16x128_f8f6f4 v[50:53], v[18:25], v[210:217], v[50:53], v186, v186 op_sel_hi:[0,0,0]
	v_mfma_scale_f32_16x16x128_f8f6f4 v[42:45], v[26:33], v[210:217], v[42:45], v186, v186 op_sel_hi:[0,0,0]
	s_barrier
	v_mfma_scale_f32_16x16x128_f8f6f4 v[38:41], v[18:25], v[218:225], v[38:41], v186, v186 op_sel_hi:[0,0,0]
	v_mfma_scale_f32_16x16x128_f8f6f4 v[34:37], v[26:33], v[218:225], v[34:37], v186, v186 op_sel_hi:[0,0,0]
	s_setprio 0
	s_add_u32 s18, s18, 0x100
	s_addc_u32 s19, s19, 0
	s_add_u32 s48, s48, 0x100
	s_addc_u32 s49, s49, 0
	s_cmp_ge_u32 s50, s4
	s_mov_b32 s22, s50
	s_cbranch_scc0 .LBB0_393
	s_nop 15
	s_nop 15
	s_nop 15
	s_nop 15
	s_nop 15
	s_and_b64 vcc, exec, s[10:11]
	s_cbranch_vccz .LBB0_396
	s_barrier

; #define PG8_STAGE(bufoff, gbase, voff) do { _Pragma("unroll") for (int _i = 0; _i < 2; ++_i) \
;         __builtin_amdgcn_global_load_lds((const unsigned*)((const char*)(gbase) + (voff)[_i]), (PG8_LAS unsigned*)(lds + (bufoff) + ldsw + _i * 8192), 16, 0, 0); } while (0)
; #define PG8_WAIT_V(n) asm volatile("s_waitcnt vmcnt(" #n ")" ::: "memory")
; #define PG8_WAIT_L(n) asm volatile("s_waitcnt lgkmcnt(" #n ")" ::: "memory")
; #define PG8_BAR __builtin_amdgcn_s_barrier()
; #define PG8_SCHED __builtin_amdgcn_sched_barrier(0)
;     __device__ __forceinline__ int nt(const pg8::Unit& u) const { return u.kind == 0 ? ntiles : q_nt(u.kind - 1); }
; template <class Epi, class Sched, bool ALIGN_EPI = true, bool SP2 = true>
; __device__ __forceinline__ void gemm_phase(PG8_LAS unsigned char* lds, const int K  , const Sched& S, const Epi& E) {
;     ...
;             const bool last = (t == nt - 2);
;             const char* a1 = cA + (size_t)(t + 1) * kstep;
;             const char* a2 = last ? nA : cA + (size_t)(t + 2) * kstep; const char* b2 = last ? nB : cB + (size_t)(t + 2) * kstep;
;             const char* a3 = a2 + kstep; const char* b3 = b2 + kstep;
;             if constexpr (SP2) {
;             PG8_LDB(B0, 0, 0); PG8_LDB(B1, 0, 1); PG8_SCHED; PG8_LDA(At, 0, 0); PG8_STAGE(PG8_SA(1, 1), a1 + hstep, voffA);
;             PG8_WAIT_V(8); PG8_WAIT_L(0); PG8_BAR; PG8_MMA(0, 0, At, B0); PG8_MMA(0, 1, At, B1); PG8_BAR; PG8_SCHED;
;             PG8_LDA(At, 0, 1); PG8_STAGE(PG8_SB(0, 0), b2, voffB); PG8_STAGE(PG8_SB(0, 1), b2 + hstep, voffB); PG8_STAGE(PG8_SA(0, 0), a2, voffA);
.LBB0_537:
	ds_read_b128 v[150:153], v156
	ds_read_b128 v[160:163], v156 offset:1024
	ds_read_b128 v[164:167], v156 offset:2048
	ds_read_b128 v[168:171], v156 offset:3072
	ds_read_b128 v[172:175], v157
	ds_read_b128 v[176:179], v157 offset:1024
	ds_read_b128 v[180:183], v157 offset:2048
	ds_read_b128 v[184:187], v157 offset:3072
	s_add_u32 s22, s20, 0xfff80080
	s_addc_u32 s23, s21, -1
	s_cmp_eq_u32 s47, 28
	s_cselect_b32 s25, s13, s23
	s_cselect_b32 s24, s19, s22
	s_cselect_b32 s23, s11, s46
	s_cselect_b32 s22, s44, s45
	v_lshl_add_u64 v[220:221], s[20:21], 0, v[142:143]
	s_add_i32 m0, s31, 0xc000
	ds_read_b128 v[188:191], v158
	ds_read_b128 v[192:195], v158 offset:1024
	ds_read_b128 v[196:199], v158 offset:2048
	ds_read_b128 v[200:203], v158 offset:3072
	ds_read_b128 v[204:207], v158 offset:4096
	ds_read_b128 v[208:211], v158 offset:5120
	ds_read_b128 v[212:215], v158 offset:6144
	ds_read_b128 v[216:219], v158 offset:7168
	global_load_lds_dwordx4 v[220:221], off
	v_lshl_add_u64 v[220:221], s[20:21], 0, v[144:145]
	s_add_i32 m0, s31, 0xe000
	s_nop 0
	global_load_lds_dwordx4 v[220:221], off
	s_waitcnt vmcnt(8)
	s_waitcnt lgkmcnt(0)
	s_setprio 1
	s_barrier
	v_mfma_f32_16x16x32_bf16 v[126:129], v[150:153], v[188:191], v[126:129]
	v_mfma_f32_16x16x32_bf16 v[122:125], v[164:167], v[188:191], v[122:125]
	v_mfma_f32_16x16x32_bf16 v[118:121], v[150:153], v[196:199], v[118:121]
	v_mfma_f32_16x16x32_bf16 v[110:113], v[164:167], v[196:199], v[110:113]
	v_mfma_f32_16x16x32_bf16 v[102:105], v[150:153], v[204:207], v[102:105]
	v_mfma_f32_16x16x32_bf16 v[94:97], v[164:167], v[204:207], v[94:97]
	v_mfma_f32_16x16x32_bf16 v[86:89], v[150:153], v[212:215], v[86:89]
	v_mfma_f32_16x16x32_bf16 v[78:81], v[164:167], v[212:215], v[78:81]
	v_mfma_f32_16x16x32_bf16 v[126:129], v[160:163], v[192:195], v[126:129]
	v_mfma_f32_16x16x32_bf16 v[122:125], v[168:171], v[192:195], v[122:125]
	v_mfma_f32_16x16x32_bf16 v[118:121], v[160:163], v[200:203], v[118:121]
	v_mfma_f32_16x16x32_bf16 v[110:113], v[168:171], v[200:203], v[110:113]
	v_mfma_f32_16x16x32_bf16 v[102:105], v[160:163], v[208:211], v[102:105]
	v_mfma_f32_16x16x32_bf16 v[94:97], v[168:171], v[208:211], v[94:97]
	v_mfma_f32_16x16x32_bf16 v[86:89], v[160:163], v[216:219], v[86:89]
	v_mfma_f32_16x16x32_bf16 v[78:81], v[168:171], v[216:219], v[78:81]
	s_setprio 0
	s_setprio 1
	v_mfma_f32_16x16x32_bf16 v[114:117], v[172:175], v[188:191], v[114:117]
	v_mfma_f32_16x16x32_bf16 v[106:109], v[180:183], v[188:191], v[106:109]
	v_mfma_f32_16x16x32_bf16 v[98:101], v[172:175], v[196:199], v[98:101]
	v_mfma_f32_16x16x32_bf16 v[90:93], v[180:183], v[196:199], v[90:93]
	v_mfma_f32_16x16x32_bf16 v[82:85], v[172:175], v[204:207], v[82:85]
	v_mfma_f32_16x16x32_bf16 v[74:77], v[180:183], v[204:207], v[74:77]
	v_mfma_f32_16x16x32_bf16 v[70:73], v[172:175], v[212:215], v[70:73]
	v_mfma_f32_16x16x32_bf16 v[66:69], v[180:183], v[212:215], v[66:69]
	v_mfma_f32_16x16x32_bf16 v[114:117], v[176:179], v[192:195], v[114:117]
	v_mfma_f32_16x16x32_bf16 v[106:109], v[184:187], v[192:195], v[106:109]
	v_mfma_f32_16x16x32_bf16 v[98:101], v[176:179], v[200:203], v[98:101]
	v_mfma_f32_16x16x32_bf16 v[90:93], v[184:187], v[200:203], v[90:93]
	s_barrier
	v_mfma_f32_16x16x32_bf16 v[82:85], v[176:179], v[208:211], v[82:85]
	v_mfma_f32_16x16x32_bf16 v[74:77], v[184:187], v[208:211], v[74:77]
	v_mfma_f32_16x16x32_bf16 v[70:73], v[176:179], v[216:219], v[70:73]
	v_mfma_f32_16x16x32_bf16 v[66:69], v[184:187], v[216:219], v[66:69]
	s_setprio 0
	s_add_i32 s48, s40, s29
	v_lshl_add_u64 v[220:221], s[22:23], 0, v[136:137]
	s_mov_b32 m0, s48
	ds_read_b128 v[188:191], v158 offset:16384
	ds_read_b128 v[192:195], v158 offset:17408
	ds_read_b128 v[196:199], v158 offset:18432
	ds_read_b128 v[200:203], v158 offset:19456
	ds_read_b128 v[204:207], v158 offset:20480
	ds_read_b128 v[208:211], v158 offset:21504
	ds_read_b128 v[212:215], v158 offset:22528
	ds_read_b128 v[216:219], v158 offset:23552
	global_load_lds_dwordx4 v[220:221], off
	s_add_i32 m0, s48, 0x2000
	s_add_u32 s48, s22, 0x80000
	v_lshl_add_u64 v[222:223], s[22:23], 0, v[132:133]
	s_addc_u32 s49, s23, 0
	s_add_i32 s50, s41, s29
	global_load_lds_dwordx4 v[222:223], off
	v_lshl_add_u64 v[224:225], s[48:49], 0, v[136:137]
	s_mov_b32 m0, s50
	v_lshl_add_u64 v[226:227], s[24:25], 0, v[134:135]
	global_load_lds_dwordx4 v[224:225], off
	v_lshl_add_u64 v[224:225], s[48:49], 0, v[132:133]
	s_add_i32 m0, s50, 0x2000
	s_nop 0
	global_load_lds_dwordx4 v[224:225], off
	v_lshl_add_u64 v[224:225], s[24:25], 0, v[138:139]
	s_mov_b32 m0, s31
	s_nop 0
	global_load_lds_dwordx4 v[224:225], off
	s_mov_b32 m0, s33
	s_nop 0
	global_load_lds_dwordx4 v[226:227], off
	s_waitcnt vmcnt(8)
	s_waitcnt lgkmcnt(0)
	s_setprio 1
	s_barrier
; #define PG8_STAGE(bufoff, gbase, voff) do { _Pragma("unroll") for (int _i = 0; _i < 2; ++_i) \
;         __builtin_amdgcn_global_load_lds((const unsigned*)((const char*)(gbase) + (voff)[_i]), (PG8_LAS unsigned*)(lds + (bufoff) + ldsw + _i * 8192), 16, 0, 0); } while (0)
; #define PG8_WAIT_V(n) asm volatile("s_waitcnt vmcnt(" #n ")" ::: "memory")
; #define PG8_WAIT_L(n) asm volatile("s_waitcnt lgkmcnt(" #n ")" ::: "memory")
; #define PG8_BAR __builtin_amdgcn_s_barrier()
; #define PG8_SCHED __builtin_amdgcn_sched_barrier(0)
; template <class Epi, class Sched, bool ALIGN_EPI = true, bool SP2 = true>
; __device__ __forceinline__ void gemm_phase(PG8_LAS unsigned char* lds, const int K  , const Sched& S, const Epi& E) {
;     ...
;             PG8_WAIT_V(8); PG8_WAIT_L(0); PG8_BAR; PG8_MMA(1, 0, At, B0); PG8_MMA(1, 1, At, B1); PG8_BAR; PG8_SCHED;
;             PG8_LDB(B0, 1, 0); PG8_LDB(B1, 1, 1); PG8_SCHED; PG8_LDA(At, 1, 0); PG8_STAGE(PG8_SA(0, 1), a2 + hstep, voffA);
;             PG8_WAIT_V(8); PG8_WAIT_L(0); PG8_BAR; PG8_MMA(0, 0, At, B0); PG8_MMA(0, 1, At, B1); PG8_BAR; PG8_SCHED;
	v_mfma_f32_16x16x32_bf16 v[62:65], v[150:153], v[188:191], v[62:65]
	v_mfma_f32_16x16x32_bf16 v[58:61], v[164:167], v[188:191], v[58:61]
	v_mfma_f32_16x16x32_bf16 v[54:57], v[150:153], v[196:199], v[54:57]
	v_mfma_f32_16x16x32_bf16 v[46:49], v[164:167], v[196:199], v[46:49]
	v_mfma_f32_16x16x32_bf16 v[38:41], v[150:153], v[204:207], v[38:41]
	v_mfma_f32_16x16x32_bf16 v[30:33], v[164:167], v[204:207], v[30:33]
	v_mfma_f32_16x16x32_bf16 v[22:25], v[150:153], v[212:215], v[22:25]
	v_mfma_f32_16x16x32_bf16 v[14:17], v[164:167], v[212:215], v[14:17]
	v_mfma_f32_16x16x32_bf16 v[62:65], v[160:163], v[192:195], v[62:65]
	v_mfma_f32_16x16x32_bf16 v[58:61], v[168:171], v[192:195], v[58:61]
	v_mfma_f32_16x16x32_bf16 v[54:57], v[160:163], v[200:203], v[54:57]
	v_mfma_f32_16x16x32_bf16 v[46:49], v[168:171], v[200:203], v[46:49]
	v_mfma_f32_16x16x32_bf16 v[38:41], v[160:163], v[208:211], v[38:41]
	v_mfma_f32_16x16x32_bf16 v[30:33], v[168:171], v[208:211], v[30:33]
	v_mfma_f32_16x16x32_bf16 v[22:25], v[160:163], v[216:219], v[22:25]
	v_mfma_f32_16x16x32_bf16 v[14:17], v[168:171], v[216:219], v[14:17]
	s_setprio 0
	s_setprio 1
	v_mfma_f32_16x16x32_bf16 v[50:53], v[172:175], v[188:191], v[50:53]
	v_mfma_f32_16x16x32_bf16 v[42:45], v[180:183], v[188:191], v[42:45]
	v_mfma_f32_16x16x32_bf16 v[34:37], v[172:175], v[196:199], v[34:37]
	v_mfma_f32_16x16x32_bf16 v[26:29], v[180:183], v[196:199], v[26:29]
	v_mfma_f32_16x16x32_bf16 v[18:21], v[172:175], v[204:207], v[18:21]
	v_mfma_f32_16x16x32_bf16 v[10:13], v[180:183], v[204:207], v[10:13]
	v_mfma_f32_16x16x32_bf16 v[6:9], v[172:175], v[212:215], v[6:9]
	v_mfma_f32_16x16x32_bf16 v[2:5], v[180:183], v[212:215], v[2:5]
	v_mfma_f32_16x16x32_bf16 v[50:53], v[176:179], v[192:195], v[50:53]
	v_mfma_f32_16x16x32_bf16 v[42:45], v[184:187], v[192:195], v[42:45]
	v_mfma_f32_16x16x32_bf16 v[34:37], v[176:179], v[200:203], v[34:37]
	v_mfma_f32_16x16x32_bf16 v[26:29], v[184:187], v[200:203], v[26:29]
	s_barrier
	v_mfma_f32_16x16x32_bf16 v[18:21], v[176:179], v[208:211], v[18:21]
	v_mfma_f32_16x16x32_bf16 v[10:13], v[184:187], v[208:211], v[10:13]
	v_mfma_f32_16x16x32_bf16 v[6:9], v[176:179], v[216:219], v[6:9]
	v_mfma_f32_16x16x32_bf16 v[2:5], v[184:187], v[216:219], v[2:5]
	s_setprio 0
	s_add_i32 s48, 0, 0x18000
	v_add_u32_e32 v140, s48, v154
	s_add_i32 s49, 0, 0x1c000
	ds_read_b128 v[150:153], v140
	ds_read_b128 v[160:163], v140 offset:1024
	ds_read_b128 v[164:167], v140 offset:2048
	ds_read_b128 v[168:171], v140 offset:3072
	v_add_u32_e32 v140, s49, v154
	ds_read_b128 v[172:175], v140
	ds_read_b128 v[176:179], v140 offset:1024
	ds_read_b128 v[180:183], v140 offset:2048
	ds_read_b128 v[184:187], v140 offset:3072
	s_add_u32 s24, s24, 0x80000
	s_addc_u32 s25, s25, 0
	s_mov_b32 m0, s34
	v_lshl_add_u64 v[230:231], s[24:25], 0, v[138:139]
	ds_read_b128 v[188:191], v158 offset:32768
	ds_read_b128 v[192:195], v158 offset:33792
	ds_read_b128 v[196:199], v158 offset:34816
	ds_read_b128 v[200:203], v158 offset:35840
	ds_read_b128 v[204:207], v158 offset:36864
	ds_read_b128 v[208:211], v158 offset:37888
	ds_read_b128 v[212:215], v158 offset:38912
	ds_read_b128 v[216:219], v158 offset:39936
	global_load_lds_dwordx4 v[230:231], off
	v_lshl_add_u64 v[230:231], s[24:25], 0, v[134:135]
	s_mov_b32 m0, s35
	s_nop 0
	global_load_lds_dwordx4 v[230:231], off
	s_waitcnt vmcnt(8)
	s_waitcnt lgkmcnt(0)
	s_setprio 1
	s_barrier
	v_mfma_f32_16x16x32_bf16 v[126:129], v[150:153], v[188:191], v[126:129]
	v_mfma_f32_16x16x32_bf16 v[122:125], v[164:167], v[188:191], v[122:125]
	v_mfma_f32_16x16x32_bf16 v[118:121], v[150:153], v[196:199], v[118:121]
	v_mfma_f32_16x16x32_bf16 v[110:113], v[164:167], v[196:199], v[110:113]
	v_mfma_f32_16x16x32_bf16 v[102:105], v[150:153], v[204:207], v[102:105]
	v_mfma_f32_16x16x32_bf16 v[94:97], v[164:167], v[204:207], v[94:97]
	v_mfma_f32_16x16x32_bf16 v[86:89], v[150:153], v[212:215], v[86:89]
	v_mfma_f32_16x16x32_bf16 v[78:81], v[164:167], v[212:215], v[78:81]
	v_mfma_f32_16x16x32_bf16 v[126:129], v[160:163], v[192:195], v[126:129]
	v_mfma_f32_16x16x32_bf16 v[122:125], v[168:171], v[192:195], v[122:125]
	v_mfma_f32_16x16x32_bf16 v[118:121], v[160:163], v[200:203], v[118:121]
	v_mfma_f32_16x16x32_bf16 v[110:113], v[168:171], v[200:203], v[110:113]
	v_mfma_f32_16x16x32_bf16 v[102:105], v[160:163], v[208:211], v[102:105]
	v_mfma_f32_16x16x32_bf16 v[94:97], v[168:171], v[208:211], v[94:97]
	v_mfma_f32_16x16x32_bf16 v[86:89], v[160:163], v[216:219], v[86:89]
	v_mfma_f32_16x16x32_bf16 v[78:81], v[168:171], v[216:219], v[78:81]
	s_setprio 0
	s_setprio 1
	v_mfma_f32_16x16x32_bf16 v[114:117], v[172:175], v[188:191], v[114:117]
	v_mfma_f32_16x16x32_bf16 v[106:109], v[180:183], v[188:191], v[106:109]
	v_mfma_f32_16x16x32_bf16 v[98:101], v[172:175], v[196:199], v[98:101]
	v_mfma_f32_16x16x32_bf16 v[90:93], v[180:183], v[196:199], v[90:93]
	v_mfma_f32_16x16x32_bf16 v[82:85], v[172:175], v[204:207], v[82:85]
	v_mfma_f32_16x16x32_bf16 v[74:77], v[180:183], v[204:207], v[74:77]
	v_mfma_f32_16x16x32_bf16 v[70:73], v[172:175], v[212:215], v[70:73]
	v_mfma_f32_16x16x32_bf16 v[66:69], v[180:183], v[212:215], v[66:69]
	v_mfma_f32_16x16x32_bf16 v[114:117], v[176:179], v[192:195], v[114:117]
	v_mfma_f32_16x16x32_bf16 v[106:109], v[184:187], v[192:195], v[106:109]
	v_mfma_f32_16x16x32_bf16 v[98:101], v[176:179], v[200:203], v[98:101]
	v_mfma_f32_16x16x32_bf16 v[90:93], v[184:187], v[200:203], v[90:93]
	s_barrier
; #define PG8_STAGE(bufoff, gbase, voff) do { _Pragma("unroll") for (int _i = 0; _i < 2; ++_i) \
;         __builtin_amdgcn_global_load_lds((const unsigned*)((const char*)(gbase) + (voff)[_i]), (PG8_LAS unsigned*)(lds + (bufoff) + ldsw + _i * 8192), 16, 0, 0); } while (0)
; #define PG8_WAIT_V(n) asm volatile("s_waitcnt vmcnt(" #n ")" ::: "memory")
; #define PG8_WAIT_L(n) asm volatile("s_waitcnt lgkmcnt(" #n ")" ::: "memory")
; #define PG8_BAR __builtin_amdgcn_s_barrier()
; #define PG8_SCHED __builtin_amdgcn_sched_barrier(0)
; template <class Epi, class Sched, bool ALIGN_EPI = true, bool SP2 = true>
; __device__ __forceinline__ void gemm_phase(PG8_LAS unsigned char* lds, const int K  , const Sched& S, const Epi& E) {
;     ...
;             PG8_WAIT_V(8); PG8_WAIT_L(0); PG8_BAR; PG8_MMA(0, 0, At, B0); PG8_MMA(0, 1, At, B1); PG8_BAR; PG8_SCHED;
;             PG8_LDA(At, 1, 1); PG8_STAGE(PG8_SB(1, 0), b3, voffB); PG8_STAGE(PG8_SB(1, 1), b3 + hstep, voffB); PG8_STAGE(PG8_SA(1, 0), a3, voffA);
;             PG8_WAIT_V(8); PG8_WAIT_L(0); PG8_BAR; PG8_MMA(1, 0, At, B0); PG8_MMA(1, 1, At, B1); PG8_BAR; PG8_SCHED;
	v_mfma_f32_16x16x32_bf16 v[82:85], v[176:179], v[208:211], v[82:85]
	v_mfma_f32_16x16x32_bf16 v[74:77], v[184:187], v[208:211], v[74:77]
	v_mfma_f32_16x16x32_bf16 v[70:73], v[176:179], v[216:219], v[70:73]
	v_mfma_f32_16x16x32_bf16 v[66:69], v[184:187], v[216:219], v[66:69]
	s_setprio 0
	s_add_i32 s24, s48, s29
	v_lshl_add_u64 v[220:221], v[220:221], 0, s[6:7]
	s_mov_b32 m0, s24
	ds_read_b128 v[188:191], v158 offset:49152
	ds_read_b128 v[192:195], v158 offset:50176
	ds_read_b128 v[196:199], v158 offset:51200
	ds_read_b128 v[200:203], v158 offset:52224
	ds_read_b128 v[204:207], v158 offset:53248
	ds_read_b128 v[208:211], v158 offset:54272
	ds_read_b128 v[212:215], v158 offset:55296
	ds_read_b128 v[216:219], v158 offset:56320
	global_load_lds_dwordx4 v[220:221], off
	s_add_i32 m0, s24, 0x2000
	s_add_u32 s22, s22, 0x80080
	v_lshl_add_u64 v[220:221], v[222:223], 0, s[6:7]
	s_addc_u32 s23, s23, 0
	s_add_i32 s24, s49, s29
	global_load_lds_dwordx4 v[220:221], off
	v_lshl_add_u64 v[220:221], s[22:23], 0, v[136:137]
	s_mov_b32 m0, s24
	s_nop 0
	global_load_lds_dwordx4 v[220:221], off
	v_lshl_add_u64 v[220:221], s[22:23], 0, v[132:133]
	s_add_i32 m0, s24, 0x2000
	s_nop 0
	global_load_lds_dwordx4 v[220:221], off
	v_lshl_add_u64 v[220:221], v[224:225], 0, s[6:7]
	s_mov_b32 m0, s37
	s_nop 0
	global_load_lds_dwordx4 v[220:221], off
	v_lshl_add_u64 v[220:221], v[226:227], 0, s[6:7]
	s_mov_b32 m0, s38
	s_nop 0
	global_load_lds_dwordx4 v[220:221], off
	s_waitcnt vmcnt(8)
	s_waitcnt lgkmcnt(0)
	s_setprio 1
	s_barrier
	v_mfma_f32_16x16x32_bf16 v[62:65], v[150:153], v[188:191], v[62:65]
	v_mfma_f32_16x16x32_bf16 v[58:61], v[164:167], v[188:191], v[58:61]
	v_mfma_f32_16x16x32_bf16 v[54:57], v[150:153], v[196:199], v[54:57]
	v_mfma_f32_16x16x32_bf16 v[46:49], v[164:167], v[196:199], v[46:49]
	v_mfma_f32_16x16x32_bf16 v[38:41], v[150:153], v[204:207], v[38:41]
	v_mfma_f32_16x16x32_bf16 v[30:33], v[164:167], v[204:207], v[30:33]
	v_mfma_f32_16x16x32_bf16 v[22:25], v[150:153], v[212:215], v[22:25]
	v_mfma_f32_16x16x32_bf16 v[14:17], v[164:167], v[212:215], v[14:17]
	v_mfma_f32_16x16x32_bf16 v[62:65], v[160:163], v[192:195], v[62:65]
	v_mfma_f32_16x16x32_bf16 v[58:61], v[168:171], v[192:195], v[58:61]
	v_mfma_f32_16x16x32_bf16 v[54:57], v[160:163], v[200:203], v[54:57]
	v_mfma_f32_16x16x32_bf16 v[46:49], v[168:171], v[200:203], v[46:49]
	v_mfma_f32_16x16x32_bf16 v[38:41], v[160:163], v[208:211], v[38:41]
	v_mfma_f32_16x16x32_bf16 v[30:33], v[168:171], v[208:211], v[30:33]
	v_mfma_f32_16x16x32_bf16 v[22:25], v[160:163], v[216:219], v[22:25]
	v_mfma_f32_16x16x32_bf16 v[14:17], v[168:171], v[216:219], v[14:17]
	s_setprio 0
	s_setprio 1
	v_mfma_f32_16x16x32_bf16 v[50:53], v[172:175], v[188:191], v[50:53]
	v_mfma_f32_16x16x32_bf16 v[42:45], v[180:183], v[188:191], v[42:45]
	v_mfma_f32_16x16x32_bf16 v[34:37], v[172:175], v[196:199], v[34:37]
	v_mfma_f32_16x16x32_bf16 v[26:29], v[180:183], v[196:199], v[26:29]
	v_mfma_f32_16x16x32_bf16 v[18:21], v[172:175], v[204:207], v[18:21]
	v_mfma_f32_16x16x32_bf16 v[10:13], v[180:183], v[204:207], v[10:13]
	v_mfma_f32_16x16x32_bf16 v[6:9], v[172:175], v[212:215], v[6:9]
	v_mfma_f32_16x16x32_bf16 v[2:5], v[180:183], v[212:215], v[2:5]
	v_mfma_f32_16x16x32_bf16 v[50:53], v[176:179], v[192:195], v[50:53]
	v_mfma_f32_16x16x32_bf16 v[42:45], v[184:187], v[192:195], v[42:45]
	v_mfma_f32_16x16x32_bf16 v[34:37], v[176:179], v[200:203], v[34:37]
	v_mfma_f32_16x16x32_bf16 v[26:29], v[184:187], v[200:203], v[26:29]
	s_barrier
	v_mfma_f32_16x16x32_bf16 v[18:21], v[176:179], v[208:211], v[18:21]
	v_mfma_f32_16x16x32_bf16 v[10:13], v[184:187], v[208:211], v[10:13]
	v_mfma_f32_16x16x32_bf16 v[6:9], v[176:179], v[216:219], v[6:9]
	v_mfma_f32_16x16x32_bf16 v[2:5], v[184:187], v[216:219], v[2:5]
	s_setprio 0
	s_add_i32 s47, s47, 2
	s_add_u32 s20, s20, 0x100
	s_addc_u32 s21, s21, 0
	s_add_u32 s45, s45, 0x100
	s_addc_u32 s46, s46, 0
	s_cmp_gt_u32 s47, 29
	s_cbranch_scc0 .LBB0_537
	s_and_b64 vcc, exec, s[8:9]
	s_cbranch_vccz .LBB0_540
	s_barrier

; #define PG8_STAGE(bufoff, gbase, voff) do { _Pragma("unroll") for (int _i = 0; _i < 2; ++_i) \
;         __builtin_amdgcn_global_load_lds((const unsigned*)((const char*)(gbase) + (voff)[_i]), (PG8_LAS unsigned*)(lds + (bufoff) + ldsw + _i * 8192), 16, 0, 0); } while (0)
; #define PG8_WAIT_V(n) asm volatile("s_waitcnt vmcnt(" #n ")" ::: "memory")
; #define PG8_WAIT_L(n) asm volatile("s_waitcnt lgkmcnt(" #n ")" ::: "memory")
; #define PG8_BAR __builtin_amdgcn_s_barrier()
; #define PG8_SCHED __builtin_amdgcn_sched_barrier(0)
;     __device__ __forceinline__ int nt(const pg8::Unit& u) const { return u.kind == 0 ? ntiles : q_nt(u.kind - 1); }
; template <class Epi, class Sched, bool ALIGN_EPI = true, bool SP2 = true>
; __device__ __forceinline__ void gemm_phase(PG8_LAS unsigned char* lds, const int K  , const Sched& S, const Epi& E) {
;     ...
;             const bool last = (t == nt - 2);
;             const char* a1 = cA + (size_t)(t + 1) * kstep;
;             const char* a2 = last ? nA : cA + (size_t)(t + 2) * kstep; const char* b2 = last ? nB : cB + (size_t)(t + 2) * kstep;
;             const char* a3 = a2 + kstep; const char* b3 = b2 + kstep;
;             if constexpr (SP2) {
;             PG8_LDB(B0, 0, 0); PG8_LDB(B1, 0, 1); PG8_SCHED; PG8_LDA(At, 0, 0); PG8_STAGE(PG8_SA(1, 1), a1 + hstep, voffA);
;             PG8_WAIT_V(8); PG8_WAIT_L(0); PG8_BAR; PG8_MMA(0, 0, At, B0); PG8_MMA(0, 1, At, B1); PG8_BAR; PG8_SCHED;
;             PG8_LDA(At, 0, 1); PG8_STAGE(PG8_SB(0, 0), b2, voffB); PG8_STAGE(PG8_SB(0, 1), b2 + hstep, voffB); PG8_STAGE(PG8_SA(0, 0), a2, voffA);
.LBB0_955:
	s_waitcnt vmcnt(0)
	ds_read_b128 v[130:133], v232
	ds_read_b128 v[134:137], v232 offset:1024
	ds_read_b128 v[138:141], v232 offset:2048
	ds_read_b128 v[142:145], v232 offset:3072
	ds_read_b128 v[146:149], v233
	ds_read_b128 v[150:153], v233 offset:1024
	ds_read_b128 v[154:157], v233 offset:2048
	ds_read_b128 v[158:161], v233 offset:3072
	s_add_i32 s73, s28, 2
	s_add_u32 s26, s24, 0xfff80080
	s_addc_u32 s27, s25, -1
	s_cmp_eq_u32 s13, s28
	s_cselect_b32 s28, s16, s26
	s_cselect_b32 s29, s17, s27
	s_cselect_b32 s27, s19, s21
	s_cselect_b32 s26, s18, s15
	v_lshl_add_u64 v[194:195], s[24:25], 0, v[214:215]
	s_add_i32 m0, s23, 0xc000
	ds_read_b128 v[162:165], v234
	ds_read_b128 v[166:169], v234 offset:1024
	ds_read_b128 v[170:173], v234 offset:2048
	ds_read_b128 v[174:177], v234 offset:3072
	ds_read_b128 v[178:181], v234 offset:4096
	ds_read_b128 v[182:185], v234 offset:5120
	ds_read_b128 v[186:189], v234 offset:6144
	ds_read_b128 v[190:193], v234 offset:7168
	global_load_lds_dwordx4 v[194:195], off
	v_lshl_add_u64 v[194:195], s[24:25], 0, v[216:217]
	s_add_i32 m0, s23, 0xe000
	s_nop 0
	global_load_lds_dwordx4 v[194:195], off
	s_waitcnt vmcnt(8)
	s_waitcnt lgkmcnt(0)
	s_setprio 1
	s_barrier
	v_mfma_f32_16x16x32_bf16 v[126:129], v[130:133], v[162:165], v[126:129]
	v_mfma_f32_16x16x32_bf16 v[122:125], v[138:141], v[162:165], v[122:125]
	v_mfma_f32_16x16x32_bf16 v[118:121], v[130:133], v[170:173], v[118:121]
	v_mfma_f32_16x16x32_bf16 v[110:113], v[138:141], v[170:173], v[110:113]
	v_mfma_f32_16x16x32_bf16 v[102:105], v[130:133], v[178:181], v[102:105]
	v_mfma_f32_16x16x32_bf16 v[94:97], v[138:141], v[178:181], v[94:97]
	v_mfma_f32_16x16x32_bf16 v[86:89], v[130:133], v[186:189], v[86:89]
	v_mfma_f32_16x16x32_bf16 v[78:81], v[138:141], v[186:189], v[78:81]
	v_mfma_f32_16x16x32_bf16 v[126:129], v[134:137], v[166:169], v[126:129]
	v_mfma_f32_16x16x32_bf16 v[122:125], v[142:145], v[166:169], v[122:125]
	v_mfma_f32_16x16x32_bf16 v[118:121], v[134:137], v[174:177], v[118:121]
	v_mfma_f32_16x16x32_bf16 v[110:113], v[142:145], v[174:177], v[110:113]
	v_mfma_f32_16x16x32_bf16 v[102:105], v[134:137], v[182:185], v[102:105]
	v_mfma_f32_16x16x32_bf16 v[94:97], v[142:145], v[182:185], v[94:97]
	v_mfma_f32_16x16x32_bf16 v[86:89], v[134:137], v[190:193], v[86:89]
	v_mfma_f32_16x16x32_bf16 v[78:81], v[142:145], v[190:193], v[78:81]
	s_setprio 0
	s_setprio 1
	v_mfma_f32_16x16x32_bf16 v[114:117], v[146:149], v[162:165], v[114:117]
	v_mfma_f32_16x16x32_bf16 v[106:109], v[154:157], v[162:165], v[106:109]
	v_mfma_f32_16x16x32_bf16 v[98:101], v[146:149], v[170:173], v[98:101]
	v_mfma_f32_16x16x32_bf16 v[90:93], v[154:157], v[170:173], v[90:93]
	v_mfma_f32_16x16x32_bf16 v[82:85], v[146:149], v[178:181], v[82:85]
	v_mfma_f32_16x16x32_bf16 v[74:77], v[154:157], v[178:181], v[74:77]
	v_mfma_f32_16x16x32_bf16 v[70:73], v[146:149], v[186:189], v[70:73]
	v_mfma_f32_16x16x32_bf16 v[66:69], v[154:157], v[186:189], v[66:69]
	v_mfma_f32_16x16x32_bf16 v[114:117], v[150:153], v[166:169], v[114:117]
	v_mfma_f32_16x16x32_bf16 v[106:109], v[158:161], v[166:169], v[106:109]
	v_mfma_f32_16x16x32_bf16 v[98:101], v[150:153], v[174:177], v[98:101]
	v_mfma_f32_16x16x32_bf16 v[90:93], v[158:161], v[174:177], v[90:93]
	s_barrier
	v_mfma_f32_16x16x32_bf16 v[82:85], v[150:153], v[182:185], v[82:85]
	v_mfma_f32_16x16x32_bf16 v[74:77], v[158:161], v[182:185], v[74:77]
	v_mfma_f32_16x16x32_bf16 v[70:73], v[150:153], v[190:193], v[70:73]
	v_mfma_f32_16x16x32_bf16 v[66:69], v[158:161], v[190:193], v[66:69]
	s_setprio 0
	s_add_i32 s74, s47, s33
	v_lshl_add_u64 v[194:195], s[26:27], 0, v[208:209]
	s_mov_b32 m0, s74
	ds_read_b128 v[162:165], v234 offset:16384
	ds_read_b128 v[166:169], v234 offset:17408
	ds_read_b128 v[170:173], v234 offset:18432
	ds_read_b128 v[174:177], v234 offset:19456
	ds_read_b128 v[178:181], v234 offset:20480
	ds_read_b128 v[182:185], v234 offset:21504
	ds_read_b128 v[186:189], v234 offset:22528
	ds_read_b128 v[190:193], v234 offset:23552
	global_load_lds_dwordx4 v[194:195], off
	s_add_i32 m0, s74, 0x2000
	s_add_u32 s74, s26, 0x80000
	v_lshl_add_u64 v[196:197], s[26:27], 0, v[212:213]
	s_addc_u32 s75, s27, 0
	s_add_i32 s76, s48, s33
	global_load_lds_dwordx4 v[196:197], off
	v_lshl_add_u64 v[198:199], s[74:75], 0, v[208:209]
	s_mov_b32 m0, s76
	v_lshl_add_u64 v[200:201], s[28:29], 0, v[210:211]
	global_load_lds_dwordx4 v[198:199], off
	v_lshl_add_u64 v[198:199], s[74:75], 0, v[212:213]
	s_add_i32 m0, s76, 0x2000
	s_nop 0
	global_load_lds_dwordx4 v[198:199], off
	v_lshl_add_u64 v[198:199], s[28:29], 0, v[206:207]
	s_mov_b32 m0, s23
	s_nop 0
	global_load_lds_dwordx4 v[198:199], off
	s_mov_b32 m0, s34
	s_nop 0
	global_load_lds_dwordx4 v[200:201], off
	s_waitcnt vmcnt(8)
	s_waitcnt lgkmcnt(0)
	s_setprio 1
	s_barrier
; #define PG8_STAGE(bufoff, gbase, voff) do { _Pragma("unroll") for (int _i = 0; _i < 2; ++_i) \
;         __builtin_amdgcn_global_load_lds((const unsigned*)((const char*)(gbase) + (voff)[_i]), (PG8_LAS unsigned*)(lds + (bufoff) + ldsw + _i * 8192), 16, 0, 0); } while (0)
; #define PG8_WAIT_V(n) asm volatile("s_waitcnt vmcnt(" #n ")" ::: "memory")
; #define PG8_WAIT_L(n) asm volatile("s_waitcnt lgkmcnt(" #n ")" ::: "memory")
; #define PG8_BAR __builtin_amdgcn_s_barrier()
; #define PG8_SCHED __builtin_amdgcn_sched_barrier(0)
; template <class Epi, class Sched, bool ALIGN_EPI = true, bool SP2 = true>
; __device__ __forceinline__ void gemm_phase(PG8_LAS unsigned char* lds, const int K  , const Sched& S, const Epi& E) {
;     ...
;             PG8_WAIT_V(8); PG8_WAIT_L(0); PG8_BAR; PG8_MMA(1, 0, At, B0); PG8_MMA(1, 1, At, B1); PG8_BAR; PG8_SCHED;
;             PG8_LDB(B0, 1, 0); PG8_LDB(B1, 1, 1); PG8_SCHED; PG8_LDA(At, 1, 0); PG8_STAGE(PG8_SA(0, 1), a2 + hstep, voffA);
;             PG8_WAIT_V(8); PG8_WAIT_L(0); PG8_BAR; PG8_MMA(0, 0, At, B0); PG8_MMA(0, 1, At, B1); PG8_BAR; PG8_SCHED;
	v_mfma_f32_16x16x32_bf16 v[62:65], v[130:133], v[162:165], v[62:65]
	v_mfma_f32_16x16x32_bf16 v[58:61], v[138:141], v[162:165], v[58:61]
	v_mfma_f32_16x16x32_bf16 v[54:57], v[130:133], v[170:173], v[54:57]
	v_mfma_f32_16x16x32_bf16 v[46:49], v[138:141], v[170:173], v[46:49]
	v_mfma_f32_16x16x32_bf16 v[38:41], v[130:133], v[178:181], v[38:41]
	v_mfma_f32_16x16x32_bf16 v[30:33], v[138:141], v[178:181], v[30:33]
	v_mfma_f32_16x16x32_bf16 v[22:25], v[130:133], v[186:189], v[22:25]
	v_mfma_f32_16x16x32_bf16 v[14:17], v[138:141], v[186:189], v[14:17]
	v_mfma_f32_16x16x32_bf16 v[62:65], v[134:137], v[166:169], v[62:65]
	v_mfma_f32_16x16x32_bf16 v[58:61], v[142:145], v[166:169], v[58:61]
	v_mfma_f32_16x16x32_bf16 v[54:57], v[134:137], v[174:177], v[54:57]
	v_mfma_f32_16x16x32_bf16 v[46:49], v[142:145], v[174:177], v[46:49]
	v_mfma_f32_16x16x32_bf16 v[38:41], v[134:137], v[182:185], v[38:41]
	v_mfma_f32_16x16x32_bf16 v[30:33], v[142:145], v[182:185], v[30:33]
	v_mfma_f32_16x16x32_bf16 v[22:25], v[134:137], v[190:193], v[22:25]
	v_mfma_f32_16x16x32_bf16 v[14:17], v[142:145], v[190:193], v[14:17]
	s_setprio 0
	s_setprio 1
	v_mfma_f32_16x16x32_bf16 v[50:53], v[146:149], v[162:165], v[50:53]
	v_mfma_f32_16x16x32_bf16 v[42:45], v[154:157], v[162:165], v[42:45]
	v_mfma_f32_16x16x32_bf16 v[34:37], v[146:149], v[170:173], v[34:37]
	v_mfma_f32_16x16x32_bf16 v[26:29], v[154:157], v[170:173], v[26:29]
	v_mfma_f32_16x16x32_bf16 v[18:21], v[146:149], v[178:181], v[18:21]
	v_mfma_f32_16x16x32_bf16 v[10:13], v[154:157], v[178:181], v[10:13]
	v_mfma_f32_16x16x32_bf16 v[6:9], v[146:149], v[186:189], v[6:9]
	v_mfma_f32_16x16x32_bf16 v[2:5], v[154:157], v[186:189], v[2:5]
	v_mfma_f32_16x16x32_bf16 v[50:53], v[150:153], v[166:169], v[50:53]
	v_mfma_f32_16x16x32_bf16 v[42:45], v[158:161], v[166:169], v[42:45]
	v_mfma_f32_16x16x32_bf16 v[34:37], v[150:153], v[174:177], v[34:37]
	v_mfma_f32_16x16x32_bf16 v[26:29], v[158:161], v[174:177], v[26:29]
	s_barrier
	v_mfma_f32_16x16x32_bf16 v[18:21], v[150:153], v[182:185], v[18:21]
	v_mfma_f32_16x16x32_bf16 v[10:13], v[158:161], v[182:185], v[10:13]
	v_mfma_f32_16x16x32_bf16 v[6:9], v[150:153], v[190:193], v[6:9]
	v_mfma_f32_16x16x32_bf16 v[2:5], v[158:161], v[190:193], v[2:5]
	s_setprio 0
	s_add_i32 s74, 0, 0x18000
	s_add_i32 s75, 0, 0x1c000
	v_add_u32_e32 v142, s74, v230
	v_add_u32_e32 v158, s75, v230
	ds_read_b128 v[130:133], v142
	ds_read_b128 v[134:137], v142 offset:1024
	ds_read_b128 v[138:141], v142 offset:2048
	ds_read_b128 v[142:145], v142 offset:3072
	ds_read_b128 v[146:149], v158
	ds_read_b128 v[150:153], v158 offset:1024
	ds_read_b128 v[154:157], v158 offset:2048
	ds_read_b128 v[158:161], v158 offset:3072
	s_add_u32 s28, s28, 0x80000
	s_addc_u32 s29, s29, 0
	s_mov_b32 m0, s35
	v_lshl_add_u64 v[202:203], s[28:29], 0, v[206:207]
	ds_read_b128 v[162:165], v234 offset:32768
	ds_read_b128 v[166:169], v234 offset:33792
	ds_read_b128 v[170:173], v234 offset:34816
	ds_read_b128 v[174:177], v234 offset:35840
	ds_read_b128 v[178:181], v234 offset:36864
	ds_read_b128 v[182:185], v234 offset:37888
	ds_read_b128 v[186:189], v234 offset:38912
	ds_read_b128 v[190:193], v234 offset:39936
	global_load_lds_dwordx4 v[202:203], off
	v_lshl_add_u64 v[202:203], s[28:29], 0, v[210:211]
	s_mov_b32 m0, s36
	s_nop 0
	global_load_lds_dwordx4 v[202:203], off
	s_waitcnt vmcnt(8)
	s_waitcnt lgkmcnt(0)
	s_setprio 1
	s_barrier
	v_mfma_f32_16x16x32_bf16 v[126:129], v[130:133], v[162:165], v[126:129]
	v_mfma_f32_16x16x32_bf16 v[122:125], v[138:141], v[162:165], v[122:125]
	v_mfma_f32_16x16x32_bf16 v[118:121], v[130:133], v[170:173], v[118:121]
	v_mfma_f32_16x16x32_bf16 v[110:113], v[138:141], v[170:173], v[110:113]
	v_mfma_f32_16x16x32_bf16 v[102:105], v[130:133], v[178:181], v[102:105]
	v_mfma_f32_16x16x32_bf16 v[94:97], v[138:141], v[178:181], v[94:97]
	v_mfma_f32_16x16x32_bf16 v[86:89], v[130:133], v[186:189], v[86:89]
	v_mfma_f32_16x16x32_bf16 v[78:81], v[138:141], v[186:189], v[78:81]
	v_mfma_f32_16x16x32_bf16 v[126:129], v[134:137], v[166:169], v[126:129]
	v_mfma_f32_16x16x32_bf16 v[122:125], v[142:145], v[166:169], v[122:125]
	v_mfma_f32_16x16x32_bf16 v[118:121], v[134:137], v[174:177], v[118:121]
	v_mfma_f32_16x16x32_bf16 v[110:113], v[142:145], v[174:177], v[110:113]
	v_mfma_f32_16x16x32_bf16 v[102:105], v[134:137], v[182:185], v[102:105]
	v_mfma_f32_16x16x32_bf16 v[94:97], v[142:145], v[182:185], v[94:97]
	v_mfma_f32_16x16x32_bf16 v[86:89], v[134:137], v[190:193], v[86:89]
	v_mfma_f32_16x16x32_bf16 v[78:81], v[142:145], v[190:193], v[78:81]
	s_setprio 0
	s_setprio 1
	v_mfma_f32_16x16x32_bf16 v[114:117], v[146:149], v[162:165], v[114:117]
	v_mfma_f32_16x16x32_bf16 v[106:109], v[154:157], v[162:165], v[106:109]
	v_mfma_f32_16x16x32_bf16 v[98:101], v[146:149], v[170:173], v[98:101]
	v_mfma_f32_16x16x32_bf16 v[90:93], v[154:157], v[170:173], v[90:93]
	v_mfma_f32_16x16x32_bf16 v[82:85], v[146:149], v[178:181], v[82:85]
	v_mfma_f32_16x16x32_bf16 v[74:77], v[154:157], v[178:181], v[74:77]
	v_mfma_f32_16x16x32_bf16 v[70:73], v[146:149], v[186:189], v[70:73]
	v_mfma_f32_16x16x32_bf16 v[66:69], v[154:157], v[186:189], v[66:69]
	v_mfma_f32_16x16x32_bf16 v[114:117], v[150:153], v[166:169], v[114:117]
	v_mfma_f32_16x16x32_bf16 v[106:109], v[158:161], v[166:169], v[106:109]
	v_mfma_f32_16x16x32_bf16 v[98:101], v[150:153], v[174:177], v[98:101]
	v_mfma_f32_16x16x32_bf16 v[90:93], v[158:161], v[174:177], v[90:93]
	s_barrier
; #define PG8_STAGE(bufoff, gbase, voff) do { _Pragma("unroll") for (int _i = 0; _i < 2; ++_i) \
;         __builtin_amdgcn_global_load_lds((const unsigned*)((const char*)(gbase) + (voff)[_i]), (PG8_LAS unsigned*)(lds + (bufoff) + ldsw + _i * 8192), 16, 0, 0); } while (0)
; #define PG8_WAIT_V(n) asm volatile("s_waitcnt vmcnt(" #n ")" ::: "memory")
; #define PG8_WAIT_L(n) asm volatile("s_waitcnt lgkmcnt(" #n ")" ::: "memory")
; #define PG8_BAR __builtin_amdgcn_s_barrier()
; #define PG8_SCHED __builtin_amdgcn_sched_barrier(0)
; template <class Epi, class Sched, bool ALIGN_EPI = true, bool SP2 = true>
; __device__ __forceinline__ void gemm_phase(PG8_LAS unsigned char* lds, const int K  , const Sched& S, const Epi& E) {
;     ...
;             PG8_WAIT_V(8); PG8_WAIT_L(0); PG8_BAR; PG8_MMA(0, 0, At, B0); PG8_MMA(0, 1, At, B1); PG8_BAR; PG8_SCHED;
;             PG8_LDA(At, 1, 1); PG8_STAGE(PG8_SB(1, 0), b3, voffB); PG8_STAGE(PG8_SB(1, 1), b3 + hstep, voffB); PG8_STAGE(PG8_SA(1, 0), a3, voffA);
;             PG8_WAIT_V(8); PG8_WAIT_L(0); PG8_BAR; PG8_MMA(1, 0, At, B0); PG8_MMA(1, 1, At, B1); PG8_BAR; PG8_SCHED;
	v_mfma_f32_16x16x32_bf16 v[82:85], v[150:153], v[182:185], v[82:85]
	v_mfma_f32_16x16x32_bf16 v[74:77], v[158:161], v[182:185], v[74:77]
	v_mfma_f32_16x16x32_bf16 v[70:73], v[150:153], v[190:193], v[70:73]
	v_mfma_f32_16x16x32_bf16 v[66:69], v[158:161], v[190:193], v[66:69]
	s_setprio 0
	s_add_i32 s28, s74, s33
	v_lshl_add_u64 v[194:195], v[194:195], 0, s[8:9]
	s_mov_b32 m0, s28
	ds_read_b128 v[162:165], v234 offset:49152
	ds_read_b128 v[166:169], v234 offset:50176
	ds_read_b128 v[170:173], v234 offset:51200
	ds_read_b128 v[174:177], v234 offset:52224
	ds_read_b128 v[178:181], v234 offset:53248
	ds_read_b128 v[182:185], v234 offset:54272
	ds_read_b128 v[186:189], v234 offset:55296
	ds_read_b128 v[190:193], v234 offset:56320
	global_load_lds_dwordx4 v[194:195], off
	s_add_i32 m0, s28, 0x2000
	s_add_u32 s26, s26, 0x80080
	v_lshl_add_u64 v[194:195], v[196:197], 0, s[8:9]
	s_addc_u32 s27, s27, 0
	s_add_i32 s28, s75, s33
	global_load_lds_dwordx4 v[194:195], off
	v_lshl_add_u64 v[194:195], s[26:27], 0, v[208:209]
	s_mov_b32 m0, s28
	s_nop 0
	global_load_lds_dwordx4 v[194:195], off
	v_lshl_add_u64 v[194:195], s[26:27], 0, v[212:213]
	s_add_i32 m0, s28, 0x2000
	s_nop 0
	global_load_lds_dwordx4 v[194:195], off
	v_lshl_add_u64 v[194:195], v[198:199], 0, s[8:9]
	s_mov_b32 m0, s42
	s_nop 0
	global_load_lds_dwordx4 v[194:195], off
	v_lshl_add_u64 v[194:195], v[200:201], 0, s[8:9]
	s_mov_b32 m0, s43
	s_nop 0
	global_load_lds_dwordx4 v[194:195], off
	s_waitcnt vmcnt(8)
	s_waitcnt lgkmcnt(0)
	s_setprio 1
	s_barrier
	v_mfma_f32_16x16x32_bf16 v[62:65], v[130:133], v[162:165], v[62:65]
	v_mfma_f32_16x16x32_bf16 v[58:61], v[138:141], v[162:165], v[58:61]
	v_mfma_f32_16x16x32_bf16 v[54:57], v[130:133], v[170:173], v[54:57]
	v_mfma_f32_16x16x32_bf16 v[46:49], v[138:141], v[170:173], v[46:49]
	v_mfma_f32_16x16x32_bf16 v[38:41], v[130:133], v[178:181], v[38:41]
	v_mfma_f32_16x16x32_bf16 v[30:33], v[138:141], v[178:181], v[30:33]
	v_mfma_f32_16x16x32_bf16 v[22:25], v[130:133], v[186:189], v[22:25]
	v_mfma_f32_16x16x32_bf16 v[14:17], v[138:141], v[186:189], v[14:17]
	v_mfma_f32_16x16x32_bf16 v[62:65], v[134:137], v[166:169], v[62:65]
	v_mfma_f32_16x16x32_bf16 v[58:61], v[142:145], v[166:169], v[58:61]
	v_mfma_f32_16x16x32_bf16 v[54:57], v[134:137], v[174:177], v[54:57]
	v_mfma_f32_16x16x32_bf16 v[46:49], v[142:145], v[174:177], v[46:49]
	v_mfma_f32_16x16x32_bf16 v[38:41], v[134:137], v[182:185], v[38:41]
	v_mfma_f32_16x16x32_bf16 v[30:33], v[142:145], v[182:185], v[30:33]
	v_mfma_f32_16x16x32_bf16 v[22:25], v[134:137], v[190:193], v[22:25]
	v_mfma_f32_16x16x32_bf16 v[14:17], v[142:145], v[190:193], v[14:17]
	s_setprio 0
	s_setprio 1
	v_mfma_f32_16x16x32_bf16 v[50:53], v[146:149], v[162:165], v[50:53]
	v_mfma_f32_16x16x32_bf16 v[42:45], v[154:157], v[162:165], v[42:45]
	v_mfma_f32_16x16x32_bf16 v[34:37], v[146:149], v[170:173], v[34:37]
	v_mfma_f32_16x16x32_bf16 v[26:29], v[154:157], v[170:173], v[26:29]
	v_mfma_f32_16x16x32_bf16 v[18:21], v[146:149], v[178:181], v[18:21]
	v_mfma_f32_16x16x32_bf16 v[10:13], v[154:157], v[178:181], v[10:13]
	v_mfma_f32_16x16x32_bf16 v[6:9], v[146:149], v[186:189], v[6:9]
	v_mfma_f32_16x16x32_bf16 v[2:5], v[154:157], v[186:189], v[2:5]
	v_mfma_f32_16x16x32_bf16 v[50:53], v[150:153], v[166:169], v[50:53]
	v_mfma_f32_16x16x32_bf16 v[42:45], v[158:161], v[166:169], v[42:45]
	v_mfma_f32_16x16x32_bf16 v[34:37], v[150:153], v[174:177], v[34:37]
	v_mfma_f32_16x16x32_bf16 v[26:29], v[158:161], v[174:177], v[26:29]
	s_barrier
	v_mfma_f32_16x16x32_bf16 v[18:21], v[150:153], v[182:185], v[18:21]
	v_mfma_f32_16x16x32_bf16 v[10:13], v[158:161], v[182:185], v[10:13]
	v_mfma_f32_16x16x32_bf16 v[6:9], v[150:153], v[190:193], v[6:9]
	v_mfma_f32_16x16x32_bf16 v[2:5], v[158:161], v[190:193], v[2:5]
	s_setprio 0
	s_add_u32 s24, s24, 0x100
	s_addc_u32 s25, s25, 0
	s_add_u32 s15, s15, 0x100
	s_addc_u32 s21, s21, 0
	s_cmp_ge_u32 s73, s4
	s_mov_b32 s28, s73
	s_cbranch_scc0 .LBB0_955
	s_and_b64 vcc, exec, s[10:11]
	s_cbranch_vccz .LBB0_958
	s_barrier

; #define PG8_STAGE(bufoff, gbase, voff) do { _Pragma("unroll") for (int _i = 0; _i < 2; ++_i) \
;         __builtin_amdgcn_global_load_lds((const unsigned*)((const char*)(gbase) + (voff)[_i]), (PG8_LAS unsigned*)(lds + (bufoff) + ldsw + _i * 8192), 16, 0, 0); } while (0)
; #define PG8_WAIT_V(n) asm volatile("s_waitcnt vmcnt(" #n ")" ::: "memory")
; #define PG8_WAIT_L(n) asm volatile("s_waitcnt lgkmcnt(" #n ")" ::: "memory")
; #define PG8_BAR __builtin_amdgcn_s_barrier()
; #define PG8_SCHED __builtin_amdgcn_sched_barrier(0)
;     __device__ __forceinline__ int nt(const pg8::Unit& u) const { return u.kind == 0 ? ntiles : q_nt(u.kind - 1); }
; template <class Epi, class Sched, bool ALIGN_EPI = true, bool SP2 = true>
; __device__ __forceinline__ void gemm_phase(PG8_LAS unsigned char* lds, const int K  , const Sched& S, const Epi& E) {
;     ...
;             const bool last = (t == nt - 2);
;             const char* a1 = cA + (size_t)(t + 1) * kstep;
;             const char* a2 = last ? nA : cA + (size_t)(t + 2) * kstep; const char* b2 = last ? nB : cB + (size_t)(t + 2) * kstep;
;             const char* a3 = a2 + kstep; const char* b3 = b2 + kstep;
;             if constexpr (SP2) {
;             PG8_LDB(B0, 0, 0); PG8_LDB(B1, 0, 1); PG8_SCHED; PG8_LDA(At, 0, 0); PG8_STAGE(PG8_SA(1, 1), a1 + hstep, voffA);
;             PG8_WAIT_V(8); PG8_WAIT_L(0); PG8_BAR; PG8_MMA(0, 0, At, B0); PG8_MMA(0, 1, At, B1); PG8_BAR; PG8_SCHED;
;             PG8_LDA(At, 0, 1); PG8_STAGE(PG8_SB(0, 0), b2, voffB); PG8_STAGE(PG8_SB(0, 1), b2 + hstep, voffB); PG8_STAGE(PG8_SA(0, 0), a2, voffA);
.LBB0_1099:
	ds_read_b128 v[148:151], v154
	ds_read_b128 v[160:163], v154 offset:1024
	ds_read_b128 v[164:167], v154 offset:2048
	ds_read_b128 v[168:171], v154 offset:3072
	ds_read_b128 v[172:175], v155
	ds_read_b128 v[176:179], v155 offset:1024
	ds_read_b128 v[180:183], v155 offset:2048
	ds_read_b128 v[184:187], v155 offset:3072
	s_add_u32 s24, s22, 0xfff80080
	s_addc_u32 s25, s23, -1
	s_cmp_eq_u32 s48, 28
	s_cselect_b32 s27, s15, s25
	s_cselect_b32 s26, s44, s24
	s_cselect_b32 s25, s11, s47
	s_cselect_b32 s24, s45, s46
	v_lshl_add_u64 v[220:221], s[22:23], 0, v[140:141]
	s_add_i32 m0, s21, 0xc000
	ds_read_b128 v[188:191], v156
	ds_read_b128 v[192:195], v156 offset:1024
	ds_read_b128 v[196:199], v156 offset:2048
	ds_read_b128 v[200:203], v156 offset:3072
	ds_read_b128 v[204:207], v156 offset:4096
	ds_read_b128 v[208:211], v156 offset:5120
	ds_read_b128 v[212:215], v156 offset:6144
	ds_read_b128 v[216:219], v156 offset:7168
	global_load_lds_dwordx4 v[220:221], off
	v_lshl_add_u64 v[220:221], s[22:23], 0, v[142:143]
	s_add_i32 m0, s21, 0xe000
	s_nop 0
	global_load_lds_dwordx4 v[220:221], off
	s_waitcnt vmcnt(8)
	s_waitcnt lgkmcnt(0)
	s_setprio 1
	s_barrier
	v_mfma_f32_16x16x32_bf16 v[126:129], v[148:151], v[188:191], v[126:129]
	v_mfma_f32_16x16x32_bf16 v[118:121], v[164:167], v[188:191], v[118:121]
	v_mfma_f32_16x16x32_bf16 v[110:113], v[148:151], v[196:199], v[110:113]
	v_mfma_f32_16x16x32_bf16 v[102:105], v[164:167], v[196:199], v[102:105]
	v_mfma_f32_16x16x32_bf16 v[94:97], v[148:151], v[204:207], v[94:97]
	v_mfma_f32_16x16x32_bf16 v[86:89], v[164:167], v[204:207], v[86:89]
	v_mfma_f32_16x16x32_bf16 v[78:81], v[148:151], v[212:215], v[78:81]
	v_mfma_f32_16x16x32_bf16 v[70:73], v[164:167], v[212:215], v[70:73]
	v_mfma_f32_16x16x32_bf16 v[126:129], v[160:163], v[192:195], v[126:129]
	v_mfma_f32_16x16x32_bf16 v[118:121], v[168:171], v[192:195], v[118:121]
	v_mfma_f32_16x16x32_bf16 v[110:113], v[160:163], v[200:203], v[110:113]
	v_mfma_f32_16x16x32_bf16 v[102:105], v[168:171], v[200:203], v[102:105]
	v_mfma_f32_16x16x32_bf16 v[94:97], v[160:163], v[208:211], v[94:97]
	v_mfma_f32_16x16x32_bf16 v[86:89], v[168:171], v[208:211], v[86:89]
	v_mfma_f32_16x16x32_bf16 v[78:81], v[160:163], v[216:219], v[78:81]
	v_mfma_f32_16x16x32_bf16 v[70:73], v[168:171], v[216:219], v[70:73]
	s_setprio 0
	s_setprio 1
	v_mfma_f32_16x16x32_bf16 v[122:125], v[172:175], v[188:191], v[122:125]
	v_mfma_f32_16x16x32_bf16 v[114:117], v[180:183], v[188:191], v[114:117]
	v_mfma_f32_16x16x32_bf16 v[106:109], v[172:175], v[196:199], v[106:109]
	v_mfma_f32_16x16x32_bf16 v[98:101], v[180:183], v[196:199], v[98:101]
	v_mfma_f32_16x16x32_bf16 v[90:93], v[172:175], v[204:207], v[90:93]
	v_mfma_f32_16x16x32_bf16 v[82:85], v[180:183], v[204:207], v[82:85]
	v_mfma_f32_16x16x32_bf16 v[74:77], v[172:175], v[212:215], v[74:77]
	v_mfma_f32_16x16x32_bf16 v[66:69], v[180:183], v[212:215], v[66:69]
	v_mfma_f32_16x16x32_bf16 v[122:125], v[176:179], v[192:195], v[122:125]
	v_mfma_f32_16x16x32_bf16 v[114:117], v[184:187], v[192:195], v[114:117]
	v_mfma_f32_16x16x32_bf16 v[106:109], v[176:179], v[200:203], v[106:109]
	v_mfma_f32_16x16x32_bf16 v[98:101], v[184:187], v[200:203], v[98:101]
	s_barrier
	v_mfma_f32_16x16x32_bf16 v[90:93], v[176:179], v[208:211], v[90:93]
	v_mfma_f32_16x16x32_bf16 v[82:85], v[184:187], v[208:211], v[82:85]
	v_mfma_f32_16x16x32_bf16 v[74:77], v[176:179], v[216:219], v[74:77]
	v_mfma_f32_16x16x32_bf16 v[66:69], v[184:187], v[216:219], v[66:69]
	s_setprio 0
	s_add_i32 s49, s39, s29
	v_lshl_add_u64 v[220:221], s[24:25], 0, v[136:137]
	s_mov_b32 m0, s49
	ds_read_b128 v[188:191], v156 offset:16384
	ds_read_b128 v[192:195], v156 offset:17408
	ds_read_b128 v[196:199], v156 offset:18432
	ds_read_b128 v[200:203], v156 offset:19456
	ds_read_b128 v[204:207], v156 offset:20480
	ds_read_b128 v[208:211], v156 offset:21504
	ds_read_b128 v[212:215], v156 offset:22528
	ds_read_b128 v[216:219], v156 offset:23552
	global_load_lds_dwordx4 v[220:221], off
	s_add_i32 m0, s49, 0x2000
	s_add_u32 s50, s24, 0x80000
	v_lshl_add_u64 v[222:223], s[24:25], 0, v[132:133]
	s_addc_u32 s51, s25, 0
	s_add_i32 s49, s40, s29
	global_load_lds_dwordx4 v[222:223], off
	v_lshl_add_u64 v[224:225], s[50:51], 0, v[136:137]
	s_mov_b32 m0, s49
	v_lshl_add_u64 v[226:227], s[26:27], 0, v[134:135]
	global_load_lds_dwordx4 v[224:225], off
	v_lshl_add_u64 v[224:225], s[50:51], 0, v[132:133]
	s_add_i32 m0, s49, 0x2000
	s_nop 0
	global_load_lds_dwordx4 v[224:225], off
	v_lshl_add_u64 v[224:225], s[26:27], 0, v[138:139]
	s_mov_b32 m0, s21
	s_nop 0
	global_load_lds_dwordx4 v[224:225], off
	s_mov_b32 m0, s31
	s_nop 0
	global_load_lds_dwordx4 v[226:227], off
	s_waitcnt vmcnt(8)
	s_waitcnt lgkmcnt(0)
	s_setprio 1
	s_barrier
; #define PG8_STAGE(bufoff, gbase, voff) do { _Pragma("unroll") for (int _i = 0; _i < 2; ++_i) \
;         __builtin_amdgcn_global_load_lds((const unsigned*)((const char*)(gbase) + (voff)[_i]), (PG8_LAS unsigned*)(lds + (bufoff) + ldsw + _i * 8192), 16, 0, 0); } while (0)
; #define PG8_WAIT_V(n) asm volatile("s_waitcnt vmcnt(" #n ")" ::: "memory")
; #define PG8_WAIT_L(n) asm volatile("s_waitcnt lgkmcnt(" #n ")" ::: "memory")
; #define PG8_BAR __builtin_amdgcn_s_barrier()
; #define PG8_SCHED __builtin_amdgcn_sched_barrier(0)
; template <class Epi, class Sched, bool ALIGN_EPI = true, bool SP2 = true>
; __device__ __forceinline__ void gemm_phase(PG8_LAS unsigned char* lds, const int K  , const Sched& S, const Epi& E) {
;     ...
;             PG8_WAIT_V(8); PG8_WAIT_L(0); PG8_BAR; PG8_MMA(1, 0, At, B0); PG8_MMA(1, 1, At, B1); PG8_BAR; PG8_SCHED;
;             PG8_LDB(B0, 1, 0); PG8_LDB(B1, 1, 1); PG8_SCHED; PG8_LDA(At, 1, 0); PG8_STAGE(PG8_SA(0, 1), a2 + hstep, voffA);
;             PG8_WAIT_V(8); PG8_WAIT_L(0); PG8_BAR; PG8_MMA(0, 0, At, B0); PG8_MMA(0, 1, At, B1); PG8_BAR; PG8_SCHED;
	v_mfma_f32_16x16x32_bf16 v[62:65], v[148:151], v[188:191], v[62:65]
	v_mfma_f32_16x16x32_bf16 v[54:57], v[164:167], v[188:191], v[54:57]
	v_mfma_f32_16x16x32_bf16 v[46:49], v[148:151], v[196:199], v[46:49]
	v_mfma_f32_16x16x32_bf16 v[38:41], v[164:167], v[196:199], v[38:41]
	v_mfma_f32_16x16x32_bf16 v[30:33], v[148:151], v[204:207], v[30:33]
	v_mfma_f32_16x16x32_bf16 v[22:25], v[164:167], v[204:207], v[22:25]
	v_mfma_f32_16x16x32_bf16 v[14:17], v[148:151], v[212:215], v[14:17]
	v_mfma_f32_16x16x32_bf16 v[6:9], v[164:167], v[212:215], v[6:9]
	v_mfma_f32_16x16x32_bf16 v[62:65], v[160:163], v[192:195], v[62:65]
	v_mfma_f32_16x16x32_bf16 v[54:57], v[168:171], v[192:195], v[54:57]
	v_mfma_f32_16x16x32_bf16 v[46:49], v[160:163], v[200:203], v[46:49]
	v_mfma_f32_16x16x32_bf16 v[38:41], v[168:171], v[200:203], v[38:41]
	v_mfma_f32_16x16x32_bf16 v[30:33], v[160:163], v[208:211], v[30:33]
	v_mfma_f32_16x16x32_bf16 v[22:25], v[168:171], v[208:211], v[22:25]
	v_mfma_f32_16x16x32_bf16 v[14:17], v[160:163], v[216:219], v[14:17]
	v_mfma_f32_16x16x32_bf16 v[6:9], v[168:171], v[216:219], v[6:9]
	s_setprio 0
	s_setprio 1
	v_mfma_f32_16x16x32_bf16 v[58:61], v[172:175], v[188:191], v[58:61]
	v_mfma_f32_16x16x32_bf16 v[50:53], v[180:183], v[188:191], v[50:53]
	v_mfma_f32_16x16x32_bf16 v[42:45], v[172:175], v[196:199], v[42:45]
	v_mfma_f32_16x16x32_bf16 v[34:37], v[180:183], v[196:199], v[34:37]
	v_mfma_f32_16x16x32_bf16 v[26:29], v[172:175], v[204:207], v[26:29]
	v_mfma_f32_16x16x32_bf16 v[18:21], v[180:183], v[204:207], v[18:21]
	v_mfma_f32_16x16x32_bf16 v[10:13], v[172:175], v[212:215], v[10:13]
	v_mfma_f32_16x16x32_bf16 v[2:5], v[180:183], v[212:215], v[2:5]
	v_mfma_f32_16x16x32_bf16 v[58:61], v[176:179], v[192:195], v[58:61]
	v_mfma_f32_16x16x32_bf16 v[50:53], v[184:187], v[192:195], v[50:53]
	v_mfma_f32_16x16x32_bf16 v[42:45], v[176:179], v[200:203], v[42:45]
	v_mfma_f32_16x16x32_bf16 v[34:37], v[184:187], v[200:203], v[34:37]
	s_barrier
	v_mfma_f32_16x16x32_bf16 v[26:29], v[176:179], v[208:211], v[26:29]
	v_mfma_f32_16x16x32_bf16 v[18:21], v[184:187], v[208:211], v[18:21]
	v_mfma_f32_16x16x32_bf16 v[10:13], v[176:179], v[216:219], v[10:13]
	v_mfma_f32_16x16x32_bf16 v[2:5], v[184:187], v[216:219], v[2:5]
	s_setprio 0
	s_add_i32 s49, 0, 0x18000
	v_add_u32_e32 v159, s49, v152
	s_add_i32 s50, 0, 0x1c000
	ds_read_b128 v[148:151], v159
	ds_read_b128 v[160:163], v159 offset:1024
	ds_read_b128 v[164:167], v159 offset:2048
	ds_read_b128 v[168:171], v159 offset:3072
	v_add_u32_e32 v159, s50, v152
	ds_read_b128 v[172:175], v159
	ds_read_b128 v[176:179], v159 offset:1024
	ds_read_b128 v[180:183], v159 offset:2048
	ds_read_b128 v[184:187], v159 offset:3072
	s_add_u32 s26, s26, 0x80000
	s_addc_u32 s27, s27, 0
	s_mov_b32 m0, s33
	v_lshl_add_u64 v[230:231], s[26:27], 0, v[138:139]
	ds_read_b128 v[188:191], v156 offset:32768
	ds_read_b128 v[192:195], v156 offset:33792
	ds_read_b128 v[196:199], v156 offset:34816
	ds_read_b128 v[200:203], v156 offset:35840
	ds_read_b128 v[204:207], v156 offset:36864
	ds_read_b128 v[208:211], v156 offset:37888
	ds_read_b128 v[212:215], v156 offset:38912
	ds_read_b128 v[216:219], v156 offset:39936
	global_load_lds_dwordx4 v[230:231], off
	v_lshl_add_u64 v[230:231], s[26:27], 0, v[134:135]
	s_mov_b32 m0, s34
	s_nop 0
	global_load_lds_dwordx4 v[230:231], off
	s_waitcnt vmcnt(8)
	s_waitcnt lgkmcnt(0)
	s_setprio 1
	s_barrier
	v_mfma_f32_16x16x32_bf16 v[126:129], v[148:151], v[188:191], v[126:129]
	v_mfma_f32_16x16x32_bf16 v[118:121], v[164:167], v[188:191], v[118:121]
	v_mfma_f32_16x16x32_bf16 v[110:113], v[148:151], v[196:199], v[110:113]
	v_mfma_f32_16x16x32_bf16 v[102:105], v[164:167], v[196:199], v[102:105]
	v_mfma_f32_16x16x32_bf16 v[94:97], v[148:151], v[204:207], v[94:97]
	v_mfma_f32_16x16x32_bf16 v[86:89], v[164:167], v[204:207], v[86:89]
	v_mfma_f32_16x16x32_bf16 v[78:81], v[148:151], v[212:215], v[78:81]
	v_mfma_f32_16x16x32_bf16 v[70:73], v[164:167], v[212:215], v[70:73]
	v_mfma_f32_16x16x32_bf16 v[126:129], v[160:163], v[192:195], v[126:129]
	v_mfma_f32_16x16x32_bf16 v[118:121], v[168:171], v[192:195], v[118:121]
	v_mfma_f32_16x16x32_bf16 v[110:113], v[160:163], v[200:203], v[110:113]
	v_mfma_f32_16x16x32_bf16 v[102:105], v[168:171], v[200:203], v[102:105]
	v_mfma_f32_16x16x32_bf16 v[94:97], v[160:163], v[208:211], v[94:97]
	v_mfma_f32_16x16x32_bf16 v[86:89], v[168:171], v[208:211], v[86:89]
	v_mfma_f32_16x16x32_bf16 v[78:81], v[160:163], v[216:219], v[78:81]
	v_mfma_f32_16x16x32_bf16 v[70:73], v[168:171], v[216:219], v[70:73]
	s_setprio 0
	s_setprio 1
	v_mfma_f32_16x16x32_bf16 v[122:125], v[172:175], v[188:191], v[122:125]
	v_mfma_f32_16x16x32_bf16 v[114:117], v[180:183], v[188:191], v[114:117]
	v_mfma_f32_16x16x32_bf16 v[106:109], v[172:175], v[196:199], v[106:109]
	v_mfma_f32_16x16x32_bf16 v[98:101], v[180:183], v[196:199], v[98:101]
	v_mfma_f32_16x16x32_bf16 v[90:93], v[172:175], v[204:207], v[90:93]
	v_mfma_f32_16x16x32_bf16 v[82:85], v[180:183], v[204:207], v[82:85]
	v_mfma_f32_16x16x32_bf16 v[74:77], v[172:175], v[212:215], v[74:77]
	v_mfma_f32_16x16x32_bf16 v[66:69], v[180:183], v[212:215], v[66:69]
	v_mfma_f32_16x16x32_bf16 v[122:125], v[176:179], v[192:195], v[122:125]
	v_mfma_f32_16x16x32_bf16 v[114:117], v[184:187], v[192:195], v[114:117]
	v_mfma_f32_16x16x32_bf16 v[106:109], v[176:179], v[200:203], v[106:109]
	v_mfma_f32_16x16x32_bf16 v[98:101], v[184:187], v[200:203], v[98:101]
	s_barrier
; #define PG8_STAGE(bufoff, gbase, voff) do { _Pragma("unroll") for (int _i = 0; _i < 2; ++_i) \
;         __builtin_amdgcn_global_load_lds((const unsigned*)((const char*)(gbase) + (voff)[_i]), (PG8_LAS unsigned*)(lds + (bufoff) + ldsw + _i * 8192), 16, 0, 0); } while (0)
; #define PG8_WAIT_V(n) asm volatile("s_waitcnt vmcnt(" #n ")" ::: "memory")
; #define PG8_WAIT_L(n) asm volatile("s_waitcnt lgkmcnt(" #n ")" ::: "memory")
; #define PG8_BAR __builtin_amdgcn_s_barrier()
; #define PG8_SCHED __builtin_amdgcn_sched_barrier(0)
; template <class Epi, class Sched, bool ALIGN_EPI = true, bool SP2 = true>
; __device__ __forceinline__ void gemm_phase(PG8_LAS unsigned char* lds, const int K  , const Sched& S, const Epi& E) {
;     ...
;             PG8_WAIT_V(8); PG8_WAIT_L(0); PG8_BAR; PG8_MMA(0, 0, At, B0); PG8_MMA(0, 1, At, B1); PG8_BAR; PG8_SCHED;
;             PG8_LDA(At, 1, 1); PG8_STAGE(PG8_SB(1, 0), b3, voffB); PG8_STAGE(PG8_SB(1, 1), b3 + hstep, voffB); PG8_STAGE(PG8_SA(1, 0), a3, voffA);
;             PG8_WAIT_V(8); PG8_WAIT_L(0); PG8_BAR; PG8_MMA(1, 0, At, B0); PG8_MMA(1, 1, At, B1); PG8_BAR; PG8_SCHED;
	v_mfma_f32_16x16x32_bf16 v[90:93], v[176:179], v[208:211], v[90:93]
	v_mfma_f32_16x16x32_bf16 v[82:85], v[184:187], v[208:211], v[82:85]
	v_mfma_f32_16x16x32_bf16 v[74:77], v[176:179], v[216:219], v[74:77]
	v_mfma_f32_16x16x32_bf16 v[66:69], v[184:187], v[216:219], v[66:69]
	s_setprio 0
	s_add_i32 s26, s49, s29
	v_lshl_add_u64 v[220:221], v[220:221], 0, s[4:5]
	s_mov_b32 m0, s26
	ds_read_b128 v[188:191], v156 offset:49152
	ds_read_b128 v[192:195], v156 offset:50176
	ds_read_b128 v[196:199], v156 offset:51200
	ds_read_b128 v[200:203], v156 offset:52224
	ds_read_b128 v[204:207], v156 offset:53248
	ds_read_b128 v[208:211], v156 offset:54272
	ds_read_b128 v[212:215], v156 offset:55296
	ds_read_b128 v[216:219], v156 offset:56320
	global_load_lds_dwordx4 v[220:221], off
	s_add_i32 m0, s26, 0x2000
	s_add_u32 s24, s24, 0x80080
	v_lshl_add_u64 v[220:221], v[222:223], 0, s[4:5]
	s_addc_u32 s25, s25, 0
	s_add_i32 s26, s50, s29
	global_load_lds_dwordx4 v[220:221], off
	v_lshl_add_u64 v[220:221], s[24:25], 0, v[136:137]
	s_mov_b32 m0, s26
	s_nop 0
	global_load_lds_dwordx4 v[220:221], off
	v_lshl_add_u64 v[220:221], s[24:25], 0, v[132:133]
	s_add_i32 m0, s26, 0x2000
	s_nop 0
	global_load_lds_dwordx4 v[220:221], off
	v_lshl_add_u64 v[220:221], v[224:225], 0, s[4:5]
	s_mov_b32 m0, s36
	s_nop 0
	global_load_lds_dwordx4 v[220:221], off
	v_lshl_add_u64 v[220:221], v[226:227], 0, s[4:5]
	s_mov_b32 m0, s37
	s_nop 0
	global_load_lds_dwordx4 v[220:221], off
	s_waitcnt vmcnt(8)
	s_waitcnt lgkmcnt(0)
	s_setprio 1
	s_barrier
	v_mfma_f32_16x16x32_bf16 v[62:65], v[148:151], v[188:191], v[62:65]
	v_mfma_f32_16x16x32_bf16 v[54:57], v[164:167], v[188:191], v[54:57]
	v_mfma_f32_16x16x32_bf16 v[46:49], v[148:151], v[196:199], v[46:49]
	v_mfma_f32_16x16x32_bf16 v[38:41], v[164:167], v[196:199], v[38:41]
	v_mfma_f32_16x16x32_bf16 v[30:33], v[148:151], v[204:207], v[30:33]
	v_mfma_f32_16x16x32_bf16 v[22:25], v[164:167], v[204:207], v[22:25]
	v_mfma_f32_16x16x32_bf16 v[14:17], v[148:151], v[212:215], v[14:17]
	v_mfma_f32_16x16x32_bf16 v[6:9], v[164:167], v[212:215], v[6:9]
	v_mfma_f32_16x16x32_bf16 v[62:65], v[160:163], v[192:195], v[62:65]
	v_mfma_f32_16x16x32_bf16 v[54:57], v[168:171], v[192:195], v[54:57]
	v_mfma_f32_16x16x32_bf16 v[46:49], v[160:163], v[200:203], v[46:49]
	v_mfma_f32_16x16x32_bf16 v[38:41], v[168:171], v[200:203], v[38:41]
	v_mfma_f32_16x16x32_bf16 v[30:33], v[160:163], v[208:211], v[30:33]
	v_mfma_f32_16x16x32_bf16 v[22:25], v[168:171], v[208:211], v[22:25]
	v_mfma_f32_16x16x32_bf16 v[14:17], v[160:163], v[216:219], v[14:17]
	v_mfma_f32_16x16x32_bf16 v[6:9], v[168:171], v[216:219], v[6:9]
	s_setprio 0
	s_setprio 1
	v_mfma_f32_16x16x32_bf16 v[58:61], v[172:175], v[188:191], v[58:61]
	v_mfma_f32_16x16x32_bf16 v[50:53], v[180:183], v[188:191], v[50:53]
	v_mfma_f32_16x16x32_bf16 v[42:45], v[172:175], v[196:199], v[42:45]
	v_mfma_f32_16x16x32_bf16 v[34:37], v[180:183], v[196:199], v[34:37]
	v_mfma_f32_16x16x32_bf16 v[26:29], v[172:175], v[204:207], v[26:29]
	v_mfma_f32_16x16x32_bf16 v[18:21], v[180:183], v[204:207], v[18:21]
	v_mfma_f32_16x16x32_bf16 v[10:13], v[172:175], v[212:215], v[10:13]
	v_mfma_f32_16x16x32_bf16 v[2:5], v[180:183], v[212:215], v[2:5]
	v_mfma_f32_16x16x32_bf16 v[58:61], v[176:179], v[192:195], v[58:61]
	v_mfma_f32_16x16x32_bf16 v[50:53], v[184:187], v[192:195], v[50:53]
	v_mfma_f32_16x16x32_bf16 v[42:45], v[176:179], v[200:203], v[42:45]
	v_mfma_f32_16x16x32_bf16 v[34:37], v[184:187], v[200:203], v[34:37]
	s_barrier
	v_mfma_f32_16x16x32_bf16 v[26:29], v[176:179], v[208:211], v[26:29]
	v_mfma_f32_16x16x32_bf16 v[18:21], v[184:187], v[208:211], v[18:21]
	v_mfma_f32_16x16x32_bf16 v[10:13], v[176:179], v[216:219], v[10:13]
	v_mfma_f32_16x16x32_bf16 v[2:5], v[184:187], v[216:219], v[2:5]
	s_setprio 0
	s_add_i32 s48, s48, 2
	s_add_u32 s22, s22, 0x100
	s_addc_u32 s23, s23, 0
	s_add_u32 s46, s46, 0x100
	s_addc_u32 s47, s47, 0
	s_cmp_gt_u32 s48, 29
	s_cbranch_scc0 .LBB0_1099
	s_and_b64 vcc, exec, s[8:9]
	s_cbranch_vccz .LBB0_1102
	s_barrier

; #define PG8_STAGE(bufoff, gbase, voff) do { _Pragma("unroll") for (int _i = 0; _i < 2; ++_i) \
;         __builtin_amdgcn_global_load_lds((const unsigned*)((const char*)(gbase) + (voff)[_i]), (PG8_LAS unsigned*)(lds + (bufoff) + ldsw + _i * 8192), 16, 0, 0); } while (0)
; #define PG8_WAIT_V(n) asm volatile("s_waitcnt vmcnt(" #n ")" ::: "memory")
; #define PG8_WAIT_L(n) asm volatile("s_waitcnt lgkmcnt(" #n ")" ::: "memory")
; #define PG8_BAR __builtin_amdgcn_s_barrier()
; #define PG8_SCHED __builtin_amdgcn_sched_barrier(0)
;     __device__ __forceinline__ int nt(const pg8::Unit& u) const { return u.kind == 0 ? ntiles : q_nt(u.kind - 1); }
; template <class Epi, class Sched, bool ALIGN_EPI = true, bool SP2 = true>
; __device__ __forceinline__ void gemm_phase(PG8_LAS unsigned char* lds, const int K  , const Sched& S, const Epi& E) {
;     ...
;             const bool last = (t == nt - 2);
;             const char* a1 = cA + (size_t)(t + 1) * kstep;
;             const char* a2 = last ? nA : cA + (size_t)(t + 2) * kstep; const char* b2 = last ? nB : cB + (size_t)(t + 2) * kstep;
;             const char* a3 = a2 + kstep; const char* b3 = b2 + kstep;
;             if constexpr (SP2) {
;             PG8_LDB(B0, 0, 0); PG8_LDB(B1, 0, 1); PG8_SCHED; PG8_LDA(At, 0, 0); PG8_STAGE(PG8_SA(1, 1), a1 + hstep, voffA);
;             PG8_WAIT_V(8); PG8_WAIT_L(0); PG8_BAR; PG8_MMA(0, 0, At, B0); PG8_MMA(0, 1, At, B1); PG8_BAR; PG8_SCHED;
;             PG8_LDA(At, 0, 1); PG8_STAGE(PG8_SB(0, 0), b2, voffB); PG8_STAGE(PG8_SB(0, 1), b2 + hstep, voffB); PG8_STAGE(PG8_SA(0, 0), a2, voffA);
;             PG8_WAIT_V(8); PG8_WAIT_L(0); PG8_BAR; PG8_MMA(1, 0, At, B0); PG8_MMA(1, 1, At, B1); PG8_BAR; PG8_SCHED;
.LBB0_1304:
	ds_read_b128 v[18:21], v233
	ds_read_b128 v[22:25], v233 offset:1024
	ds_read_b128 v[26:29], v233 offset:2048
	ds_read_b128 v[30:33], v233 offset:3072
	ds_read_b128 v[2:5], v234
	ds_read_b128 v[6:9], v234 offset:1024
	ds_read_b128 v[10:13], v234 offset:2048
	ds_read_b128 v[14:17], v234 offset:3072
	s_add_i32 s74, s22, 2
	s_add_u32 s20, s18, 0xfff50080
	s_addc_u32 s21, s19, -1
	s_cmp_eq_u32 s71, s22
	s_cselect_b32 s22, s14, s20
	s_cselect_b32 s23, s15, s21
	s_cselect_b32 s21, s17, s73
	s_cselect_b32 s20, s16, s72
	v_lshl_add_u64 v[186:187], s[18:19], 0, v[198:199]
	s_add_i32 m0, s26, 0xc000
	ds_read_b128 v[162:165], v235
	ds_read_b128 v[166:169], v235 offset:1024
	ds_read_b128 v[170:173], v235 offset:2048
	ds_read_b128 v[174:177], v235 offset:3072
	ds_read_b128 v[178:181], v235 offset:4096
	ds_read_b128 v[182:185], v235 offset:5120
	ds_read_b128 v[206:209], v235 offset:6144
	ds_read_b128 v[210:213], v235 offset:7168
	global_load_lds_dwordx4 v[186:187], off
	v_lshl_add_u64 v[186:187], s[18:19], 0, v[200:201]
	s_add_i32 m0, s26, 0xe000
	s_nop 0
	global_load_lds_dwordx4 v[186:187], off
	s_waitcnt vmcnt(8)
	s_waitcnt lgkmcnt(0)
	s_setprio 1
	s_barrier
	v_mfma_scale_f32_16x16x128_f8f6f4 v[158:161], v[18:25], v[162:169], v[158:161], v229, v229 op_sel_hi:[0,0,0]
	v_mfma_scale_f32_16x16x128_f8f6f4 v[154:157], v[26:33], v[162:169], v[154:157], v229, v229 op_sel_hi:[0,0,0]
	v_mfma_scale_f32_16x16x128_f8f6f4 v[150:153], v[18:25], v[170:177], v[150:153], v229, v229 op_sel_hi:[0,0,0]
	v_mfma_scale_f32_16x16x128_f8f6f4 v[142:145], v[26:33], v[170:177], v[142:145], v229, v229 op_sel_hi:[0,0,0]
	v_mfma_scale_f32_16x16x128_f8f6f4 v[134:137], v[18:25], v[178:185], v[134:137], v229, v229 op_sel_hi:[0,0,0]
	v_mfma_scale_f32_16x16x128_f8f6f4 v[126:129], v[26:33], v[178:185], v[126:129], v229, v229 op_sel_hi:[0,0,0]
	v_mfma_scale_f32_16x16x128_f8f6f4 v[118:121], v[18:25], v[206:213], v[118:121], v229, v229 op_sel_hi:[0,0,0]
	v_mfma_scale_f32_16x16x128_f8f6f4 v[110:113], v[26:33], v[206:213], v[110:113], v229, v229 op_sel_hi:[0,0,0]
	s_setprio 0
	s_setprio 1
	v_mfma_scale_f32_16x16x128_f8f6f4 v[146:149], v[2:9], v[162:169], v[146:149], v229, v229 op_sel_hi:[0,0,0]
	v_mfma_scale_f32_16x16x128_f8f6f4 v[138:141], v[10:17], v[162:169], v[138:141], v229, v229 op_sel_hi:[0,0,0]
	v_mfma_scale_f32_16x16x128_f8f6f4 v[130:133], v[2:9], v[170:177], v[130:133], v229, v229 op_sel_hi:[0,0,0]
	v_mfma_scale_f32_16x16x128_f8f6f4 v[122:125], v[10:17], v[170:177], v[122:125], v229, v229 op_sel_hi:[0,0,0]
	v_mfma_scale_f32_16x16x128_f8f6f4 v[114:117], v[2:9], v[178:185], v[114:117], v229, v229 op_sel_hi:[0,0,0]
	v_mfma_scale_f32_16x16x128_f8f6f4 v[106:109], v[10:17], v[178:185], v[106:109], v229, v229 op_sel_hi:[0,0,0]
	s_barrier
	v_mfma_scale_f32_16x16x128_f8f6f4 v[102:105], v[2:9], v[206:213], v[102:105], v229, v229 op_sel_hi:[0,0,0]
	v_mfma_scale_f32_16x16x128_f8f6f4 v[98:101], v[10:17], v[206:213], v[98:101], v229, v229 op_sel_hi:[0,0,0]
	s_setprio 0
	s_add_i32 s75, s40, s25
	v_lshl_add_u64 v[162:163], s[20:21], 0, v[192:193]
	s_mov_b32 m0, s75
	ds_read_b128 v[170:173], v235 offset:16384
	ds_read_b128 v[174:177], v235 offset:17408
	ds_read_b128 v[178:181], v235 offset:18432
	ds_read_b128 v[182:185], v235 offset:19456
	ds_read_b128 v[206:209], v235 offset:20480
	ds_read_b128 v[210:213], v235 offset:21504
	ds_read_b128 v[214:217], v235 offset:22528
	ds_read_b128 v[218:221], v235 offset:23552
	global_load_lds_dwordx4 v[162:163], off
	s_add_i32 m0, s75, 0x2000
	s_add_u32 s76, s20, 0xb0000
	v_lshl_add_u64 v[164:165], s[20:21], 0, v[196:197]
	s_addc_u32 s77, s21, 0
	s_add_i32 s75, s41, s25
	global_load_lds_dwordx4 v[164:165], off
	v_lshl_add_u64 v[166:167], s[76:77], 0, v[192:193]
	s_mov_b32 m0, s75
	v_lshl_add_u64 v[168:169], s[22:23], 0, v[194:195]
	global_load_lds_dwordx4 v[166:167], off
	v_lshl_add_u64 v[166:167], s[76:77], 0, v[196:197]
	s_add_i32 m0, s75, 0x2000
	s_nop 0
	global_load_lds_dwordx4 v[166:167], off
	v_lshl_add_u64 v[166:167], s[22:23], 0, v[190:191]
	s_mov_b32 m0, s26
	s_nop 0
	global_load_lds_dwordx4 v[166:167], off
	s_mov_b32 m0, s27
	s_nop 0
	global_load_lds_dwordx4 v[168:169], off
	s_waitcnt vmcnt(8)
	s_waitcnt lgkmcnt(0)
	s_setprio 1
	s_barrier
	v_mfma_scale_f32_16x16x128_f8f6f4 v[94:97], v[18:25], v[170:177], v[94:97], v229, v229 op_sel_hi:[0,0,0]
	v_mfma_scale_f32_16x16x128_f8f6f4 v[90:93], v[26:33], v[170:177], v[90:93], v229, v229 op_sel_hi:[0,0,0]
	v_mfma_scale_f32_16x16x128_f8f6f4 v[86:89], v[18:25], v[178:185], v[86:89], v229, v229 op_sel_hi:[0,0,0]
	v_mfma_scale_f32_16x16x128_f8f6f4 v[78:81], v[26:33], v[178:185], v[78:81], v229, v229 op_sel_hi:[0,0,0]
	v_mfma_scale_f32_16x16x128_f8f6f4 v[70:73], v[18:25], v[206:213], v[70:73], v229, v229 op_sel_hi:[0,0,0]
	v_mfma_scale_f32_16x16x128_f8f6f4 v[62:65], v[26:33], v[206:213], v[62:65], v229, v229 op_sel_hi:[0,0,0]
	v_mfma_scale_f32_16x16x128_f8f6f4 v[54:57], v[18:25], v[214:221], v[54:57], v229, v229 op_sel_hi:[0,0,0]
	v_mfma_scale_f32_16x16x128_f8f6f4 v[46:49], v[26:33], v[214:221], v[46:49], v229, v229 op_sel_hi:[0,0,0]
	s_setprio 0
	s_setprio 1
	v_mfma_scale_f32_16x16x128_f8f6f4 v[82:85], v[2:9], v[170:177], v[82:85], v229, v229 op_sel_hi:[0,0,0]
	v_mfma_scale_f32_16x16x128_f8f6f4 v[74:77], v[10:17], v[170:177], v[74:77], v229, v229 op_sel_hi:[0,0,0]
	v_mfma_scale_f32_16x16x128_f8f6f4 v[66:69], v[2:9], v[178:185], v[66:69], v229, v229 op_sel_hi:[0,0,0]
	v_mfma_scale_f32_16x16x128_f8f6f4 v[58:61], v[10:17], v[178:185], v[58:61], v229, v229 op_sel_hi:[0,0,0]
	v_mfma_scale_f32_16x16x128_f8f6f4 v[50:53], v[2:9], v[206:213], v[50:53], v229, v229 op_sel_hi:[0,0,0]
	v_mfma_scale_f32_16x16x128_f8f6f4 v[42:45], v[10:17], v[206:213], v[42:45], v229, v229 op_sel_hi:[0,0,0]
	s_barrier
; #define PG8_WAIT_V(n) asm volatile("s_waitcnt vmcnt(" #n ")" ::: "memory")
; template <class Epi, class Sched, bool ALIGN_EPI = true, bool SP2 = true>
; __device__ __forceinline__ void gemm_phase(PG8_LAS unsigned char* lds, const int K  , const Sched& S, const Epi& E) {
;     ...
;             PG8_WAIT_V(8); PG8_WAIT_L(0); PG8_BAR; PG8_MMA(1, 0, At, B0); PG8_MMA(1, 1, At, B1); PG8_BAR; PG8_SCHED;
;             PG8_LDB(B0, 1, 0); PG8_LDB(B1, 1, 1); PG8_SCHED; PG8_LDA(At, 1, 0); PG8_STAGE(PG8_SA(0, 1), a2 + hstep, voffA);
;             PG8_WAIT_V(8); PG8_WAIT_L(0); PG8_BAR; PG8_MMA(0, 0, At, B0); PG8_MMA(0, 1, At, B1); PG8_BAR; PG8_SCHED;
;             PG8_LDA(At, 1, 1); PG8_STAGE(PG8_SB(1, 0), b3, voffB); PG8_STAGE(PG8_SB(1, 1), b3 + hstep, voffB); PG8_STAGE(PG8_SA(1, 0), a3, voffA);
;             PG8_WAIT_V(8); PG8_WAIT_L(0); PG8_BAR; PG8_MMA(1, 0, At, B0); PG8_MMA(1, 1, At, B1); PG8_BAR; PG8_SCHED;
;             } else {
;             PG8_LDB(B0, 0, 0); PG8_SCHED; PG8_LDA(At, 0, 0); PG8_STAGE(PG8_SA(1, 1), a1 + hstep, voffA);
;             PG8_WAIT_L(8); PG8_BAR; PG8_WAIT_L(0); PG8_MMA(0, 0, At, B0); PG8_BAR; PG8_SCHED;
;             PG8_LDB(B1, 0, 1); PG8_STAGE(PG8_SB(0, 0), b2, voffB);
;             PG8_BAR; PG8_WAIT_L(0); PG8_MMA(0, 1, At, B1); PG8_BAR;
;             PG8_LDA(At, 0, 1); PG8_STAGE(PG8_SA(0, 0), a2, voffA);
;             PG8_BAR; PG8_WAIT_L(0); PG8_MMA(1, 0, At, B0); PG8_BAR; PG8_SCHED;
;             PG8_STAGE(PG8_SB(0, 1), b2 + hstep, voffB);
;             PG8_WAIT_V(6); PG8_BAR; PG8_MMA(1, 1, At, B1); PG8_BAR;
;             PG8_LDB(B0, 1, 0); PG8_SCHED; PG8_LDA(At, 1, 0); PG8_STAGE(PG8_SA(0, 1), a2 + hstep, voffA);
;             PG8_WAIT_L(8); PG8_BAR; PG8_WAIT_L(0); PG8_MMA(0, 0, At, B0); PG8_BAR; PG8_SCHED;
;             PG8_LDB(B1, 1, 1); PG8_STAGE(PG8_SB(1, 0), b3, voffB);
;             PG8_BAR; PG8_WAIT_L(0); PG8_MMA(0, 1, At, B1); PG8_BAR;
;             PG8_LDA(At, 1, 1); PG8_STAGE(PG8_SA(1, 0), a3, voffA);
;             PG8_BAR; PG8_WAIT_L(0); PG8_MMA(1, 0, At, B0); PG8_BAR; PG8_SCHED;
;             PG8_STAGE(PG8_SB(1, 1), b3 + hstep, voffB);
;             PG8_WAIT_V(6); PG8_BAR; PG8_MMA(1, 1, At, B1); PG8_BAR;
;             }
;         }
;         if constexpr (Epi::FP8) asm volatile("s_nop 15\n\ts_nop 15\n\ts_nop 15\n\ts_nop 15\n\ts_nop 15" ::: "memory");
;         if constexpr (ALIGN_EPI) { if (wr == 0) PG8_BAR; }
	v_mfma_scale_f32_16x16x128_f8f6f4 v[38:41], v[2:9], v[214:221], v[38:41], v229, v229 op_sel_hi:[0,0,0]
	v_mfma_scale_f32_16x16x128_f8f6f4 v[34:37], v[10:17], v[214:221], v[34:37], v229, v229 op_sel_hi:[0,0,0]
	s_setprio 0
	s_add_i32 s75, 0, 0x18000
	s_add_i32 s76, 0, 0x1c000
	v_add_u32_e32 v14, s75, v231
	v_add_u32_e32 v30, s76, v231
	ds_read_b128 v[2:5], v14
	ds_read_b128 v[6:9], v14 offset:1024
	ds_read_b128 v[10:13], v14 offset:2048
	ds_read_b128 v[14:17], v14 offset:3072
	ds_read_b128 v[18:21], v30
	ds_read_b128 v[22:25], v30 offset:1024
	ds_read_b128 v[26:29], v30 offset:2048
	ds_read_b128 v[30:33], v30 offset:3072
	s_add_u32 s22, s22, 0xb0000
	s_addc_u32 s23, s23, 0
	s_mov_b32 m0, s28
	v_lshl_add_u64 v[186:187], s[22:23], 0, v[190:191]
	ds_read_b128 v[170:173], v235 offset:32768
	ds_read_b128 v[174:177], v235 offset:33792
	ds_read_b128 v[178:181], v235 offset:34816
	ds_read_b128 v[182:185], v235 offset:35840
	ds_read_b128 v[206:209], v235 offset:36864
	ds_read_b128 v[210:213], v235 offset:37888
	ds_read_b128 v[214:217], v235 offset:38912
	ds_read_b128 v[218:221], v235 offset:39936
	global_load_lds_dwordx4 v[186:187], off
	v_lshl_add_u64 v[186:187], s[22:23], 0, v[194:195]
	s_mov_b32 m0, s29
	s_nop 0
	global_load_lds_dwordx4 v[186:187], off
	s_waitcnt vmcnt(8)
	s_waitcnt lgkmcnt(0)
	s_setprio 1
	s_barrier
	v_mfma_scale_f32_16x16x128_f8f6f4 v[158:161], v[2:9], v[170:177], v[158:161], v229, v229 op_sel_hi:[0,0,0]
	v_mfma_scale_f32_16x16x128_f8f6f4 v[154:157], v[10:17], v[170:177], v[154:157], v229, v229 op_sel_hi:[0,0,0]
	v_mfma_scale_f32_16x16x128_f8f6f4 v[150:153], v[2:9], v[178:185], v[150:153], v229, v229 op_sel_hi:[0,0,0]
	v_mfma_scale_f32_16x16x128_f8f6f4 v[142:145], v[10:17], v[178:185], v[142:145], v229, v229 op_sel_hi:[0,0,0]
	v_mfma_scale_f32_16x16x128_f8f6f4 v[134:137], v[2:9], v[206:213], v[134:137], v229, v229 op_sel_hi:[0,0,0]
	v_mfma_scale_f32_16x16x128_f8f6f4 v[126:129], v[10:17], v[206:213], v[126:129], v229, v229 op_sel_hi:[0,0,0]
	v_mfma_scale_f32_16x16x128_f8f6f4 v[118:121], v[2:9], v[214:221], v[118:121], v229, v229 op_sel_hi:[0,0,0]
	v_mfma_scale_f32_16x16x128_f8f6f4 v[110:113], v[10:17], v[214:221], v[110:113], v229, v229 op_sel_hi:[0,0,0]
	s_setprio 0
	s_setprio 1
	v_mfma_scale_f32_16x16x128_f8f6f4 v[146:149], v[18:25], v[170:177], v[146:149], v229, v229 op_sel_hi:[0,0,0]
	v_mfma_scale_f32_16x16x128_f8f6f4 v[138:141], v[26:33], v[170:177], v[138:141], v229, v229 op_sel_hi:[0,0,0]
	v_mfma_scale_f32_16x16x128_f8f6f4 v[130:133], v[18:25], v[178:185], v[130:133], v229, v229 op_sel_hi:[0,0,0]
	v_mfma_scale_f32_16x16x128_f8f6f4 v[122:125], v[26:33], v[178:185], v[122:125], v229, v229 op_sel_hi:[0,0,0]
	v_mfma_scale_f32_16x16x128_f8f6f4 v[114:117], v[18:25], v[206:213], v[114:117], v229, v229 op_sel_hi:[0,0,0]
	v_mfma_scale_f32_16x16x128_f8f6f4 v[106:109], v[26:33], v[206:213], v[106:109], v229, v229 op_sel_hi:[0,0,0]
	s_barrier
	v_mfma_scale_f32_16x16x128_f8f6f4 v[102:105], v[18:25], v[214:221], v[102:105], v229, v229 op_sel_hi:[0,0,0]
	v_mfma_scale_f32_16x16x128_f8f6f4 v[98:101], v[26:33], v[214:221], v[98:101], v229, v229 op_sel_hi:[0,0,0]
	s_setprio 0
	s_add_i32 s22, s75, s25
	v_lshl_add_u64 v[162:163], v[162:163], 0, s[8:9]
	s_mov_b32 m0, s22
	ds_read_b128 v[170:173], v235 offset:49152
	ds_read_b128 v[174:177], v235 offset:50176
	ds_read_b128 v[178:181], v235 offset:51200
	ds_read_b128 v[182:185], v235 offset:52224
	ds_read_b128 v[206:209], v235 offset:53248
	ds_read_b128 v[210:213], v235 offset:54272
	ds_read_b128 v[214:217], v235 offset:55296
	ds_read_b128 v[218:221], v235 offset:56320
	global_load_lds_dwordx4 v[162:163], off
	s_add_i32 m0, s22, 0x2000
	s_add_u32 s20, s20, 0xb0080
	v_lshl_add_u64 v[162:163], v[164:165], 0, s[8:9]
	s_addc_u32 s21, s21, 0
	s_add_i32 s22, s76, s25
	global_load_lds_dwordx4 v[162:163], off
	v_lshl_add_u64 v[162:163], s[20:21], 0, v[192:193]
	s_mov_b32 m0, s22
	s_nop 0
	global_load_lds_dwordx4 v[162:163], off
	v_lshl_add_u64 v[162:163], s[20:21], 0, v[196:197]
	s_add_i32 m0, s22, 0x2000
	s_nop 0
	global_load_lds_dwordx4 v[162:163], off
	v_lshl_add_u64 v[162:163], v[166:167], 0, s[8:9]
	s_mov_b32 m0, s36
	s_nop 0
	global_load_lds_dwordx4 v[162:163], off
	v_lshl_add_u64 v[162:163], v[168:169], 0, s[8:9]
	s_mov_b32 m0, s37
	s_nop 0
	global_load_lds_dwordx4 v[162:163], off
	s_waitcnt vmcnt(8)
	s_waitcnt lgkmcnt(0)
	s_setprio 1
	s_barrier
	v_mfma_scale_f32_16x16x128_f8f6f4 v[94:97], v[2:9], v[170:177], v[94:97], v229, v229 op_sel_hi:[0,0,0]
	v_mfma_scale_f32_16x16x128_f8f6f4 v[90:93], v[10:17], v[170:177], v[90:93], v229, v229 op_sel_hi:[0,0,0]
	v_mfma_scale_f32_16x16x128_f8f6f4 v[86:89], v[2:9], v[178:185], v[86:89], v229, v229 op_sel_hi:[0,0,0]
	v_mfma_scale_f32_16x16x128_f8f6f4 v[78:81], v[10:17], v[178:185], v[78:81], v229, v229 op_sel_hi:[0,0,0]
	v_mfma_scale_f32_16x16x128_f8f6f4 v[70:73], v[2:9], v[206:213], v[70:73], v229, v229 op_sel_hi:[0,0,0]
	v_mfma_scale_f32_16x16x128_f8f6f4 v[62:65], v[10:17], v[206:213], v[62:65], v229, v229 op_sel_hi:[0,0,0]
	v_mfma_scale_f32_16x16x128_f8f6f4 v[54:57], v[2:9], v[214:221], v[54:57], v229, v229 op_sel_hi:[0,0,0]
	v_mfma_scale_f32_16x16x128_f8f6f4 v[46:49], v[10:17], v[214:221], v[46:49], v229, v229 op_sel_hi:[0,0,0]
	s_setprio 0
	s_setprio 1
	v_mfma_scale_f32_16x16x128_f8f6f4 v[82:85], v[18:25], v[170:177], v[82:85], v229, v229 op_sel_hi:[0,0,0]
	v_mfma_scale_f32_16x16x128_f8f6f4 v[74:77], v[26:33], v[170:177], v[74:77], v229, v229 op_sel_hi:[0,0,0]
	v_mfma_scale_f32_16x16x128_f8f6f4 v[66:69], v[18:25], v[178:185], v[66:69], v229, v229 op_sel_hi:[0,0,0]
	v_mfma_scale_f32_16x16x128_f8f6f4 v[58:61], v[26:33], v[178:185], v[58:61], v229, v229 op_sel_hi:[0,0,0]
	v_mfma_scale_f32_16x16x128_f8f6f4 v[50:53], v[18:25], v[206:213], v[50:53], v229, v229 op_sel_hi:[0,0,0]
	v_mfma_scale_f32_16x16x128_f8f6f4 v[42:45], v[26:33], v[206:213], v[42:45], v229, v229 op_sel_hi:[0,0,0]
	s_barrier
	v_mfma_scale_f32_16x16x128_f8f6f4 v[38:41], v[18:25], v[214:221], v[38:41], v229, v229 op_sel_hi:[0,0,0]
	v_mfma_scale_f32_16x16x128_f8f6f4 v[34:37], v[26:33], v[214:221], v[34:37], v229, v229 op_sel_hi:[0,0,0]
	s_setprio 0
	s_add_u32 s18, s18, 0x100
	s_addc_u32 s19, s19, 0
	s_add_u32 s72, s72, 0x100
	s_addc_u32 s73, s73, 0
	s_cmp_ge_u32 s74, s4
	s_mov_b32 s22, s74
	s_cbranch_scc0 .LBB0_1304
	s_nop 15
	s_nop 15
	s_nop 15
	s_nop 15
	s_nop 15
	s_and_b64 vcc, exec, s[10:11]
	s_cbranch_vccz .LBB0_1307
	s_barrier

; #define PG8_STAGE(bufoff, gbase, voff) do { _Pragma("unroll") for (int _i = 0; _i < 2; ++_i) \
;         __builtin_amdgcn_global_load_lds((const unsigned*)((const char*)(gbase) + (voff)[_i]), (PG8_LAS unsigned*)(lds + (bufoff) + ldsw + _i * 8192), 16, 0, 0); } while (0)
; #define PG8_WAIT_V(n) asm volatile("s_waitcnt vmcnt(" #n ")" ::: "memory")
; #define PG8_WAIT_L(n) asm volatile("s_waitcnt lgkmcnt(" #n ")" ::: "memory")
; #define PG8_BAR __builtin_amdgcn_s_barrier()
; #define PG8_SCHED __builtin_amdgcn_sched_barrier(0)
;     __device__ __forceinline__ int nt(const pg8::Unit& u) const { return u.kind == 0 ? ntiles : q_nt(u.kind - 1); }
; template <class Epi, class Sched, bool ALIGN_EPI = true, bool SP2 = true>
; __device__ __forceinline__ void gemm_phase(PG8_LAS unsigned char* lds, const int K  , const Sched& S, const Epi& E) {
;     ...
;             const bool last = (t == nt - 2);
;             const char* a1 = cA + (size_t)(t + 1) * kstep;
;             const char* a2 = last ? nA : cA + (size_t)(t + 2) * kstep; const char* b2 = last ? nB : cB + (size_t)(t + 2) * kstep;
;             const char* a3 = a2 + kstep; const char* b3 = b2 + kstep;
;             if constexpr (SP2) {
;             PG8_LDB(B0, 0, 0); PG8_LDB(B1, 0, 1); PG8_SCHED; PG8_LDA(At, 0, 0); PG8_STAGE(PG8_SA(1, 1), a1 + hstep, voffA);
;             PG8_WAIT_V(8); PG8_WAIT_L(0); PG8_BAR; PG8_MMA(0, 0, At, B0); PG8_MMA(0, 1, At, B1); PG8_BAR; PG8_SCHED;
;             PG8_LDA(At, 0, 1); PG8_STAGE(PG8_SB(0, 0), b2, voffB); PG8_STAGE(PG8_SB(0, 1), b2 + hstep, voffB); PG8_STAGE(PG8_SA(0, 0), a2, voffA);
.LBB0_1448:
	ds_read_b128 v[148:151], v154
	ds_read_b128 v[160:163], v154 offset:1024
	ds_read_b128 v[164:167], v154 offset:2048
	ds_read_b128 v[168:171], v154 offset:3072
	ds_read_b128 v[172:175], v155
	ds_read_b128 v[176:179], v155 offset:1024
	ds_read_b128 v[180:183], v155 offset:2048
	ds_read_b128 v[184:187], v155 offset:3072
	s_add_u32 s26, s24, 0xfff80080
	s_addc_u32 s27, s25, -1
	s_cmp_eq_u32 s50, 28
	s_cselect_b32 s29, s17, s27
	s_cselect_b32 s28, s46, s26
	s_cselect_b32 s27, s11, s49
	s_cselect_b32 s26, s47, s48
	v_lshl_add_u64 v[220:221], s[24:25], 0, v[140:141]
	s_add_i32 m0, s23, 0xc000
	ds_read_b128 v[188:191], v156
	ds_read_b128 v[192:195], v156 offset:1024
	ds_read_b128 v[196:199], v156 offset:2048
	ds_read_b128 v[200:203], v156 offset:3072
	ds_read_b128 v[204:207], v156 offset:4096
	ds_read_b128 v[208:211], v156 offset:5120
	ds_read_b128 v[212:215], v156 offset:6144
	ds_read_b128 v[216:219], v156 offset:7168
	global_load_lds_dwordx4 v[220:221], off
	v_lshl_add_u64 v[220:221], s[24:25], 0, v[142:143]
	s_add_i32 m0, s23, 0xe000
	s_nop 0
	global_load_lds_dwordx4 v[220:221], off
	s_waitcnt vmcnt(8)
	s_waitcnt lgkmcnt(0)
	s_setprio 1
	s_barrier
	v_mfma_f32_16x16x32_bf16 v[126:129], v[148:151], v[188:191], v[126:129]
	v_mfma_f32_16x16x32_bf16 v[118:121], v[164:167], v[188:191], v[118:121]
	v_mfma_f32_16x16x32_bf16 v[110:113], v[148:151], v[196:199], v[110:113]
	v_mfma_f32_16x16x32_bf16 v[102:105], v[164:167], v[196:199], v[102:105]
	v_mfma_f32_16x16x32_bf16 v[94:97], v[148:151], v[204:207], v[94:97]
	v_mfma_f32_16x16x32_bf16 v[86:89], v[164:167], v[204:207], v[86:89]
	v_mfma_f32_16x16x32_bf16 v[78:81], v[148:151], v[212:215], v[78:81]
	v_mfma_f32_16x16x32_bf16 v[70:73], v[164:167], v[212:215], v[70:73]
	v_mfma_f32_16x16x32_bf16 v[126:129], v[160:163], v[192:195], v[126:129]
	v_mfma_f32_16x16x32_bf16 v[118:121], v[168:171], v[192:195], v[118:121]
	v_mfma_f32_16x16x32_bf16 v[110:113], v[160:163], v[200:203], v[110:113]
	v_mfma_f32_16x16x32_bf16 v[102:105], v[168:171], v[200:203], v[102:105]
	v_mfma_f32_16x16x32_bf16 v[94:97], v[160:163], v[208:211], v[94:97]
	v_mfma_f32_16x16x32_bf16 v[86:89], v[168:171], v[208:211], v[86:89]
	v_mfma_f32_16x16x32_bf16 v[78:81], v[160:163], v[216:219], v[78:81]
	v_mfma_f32_16x16x32_bf16 v[70:73], v[168:171], v[216:219], v[70:73]
	s_setprio 0
	s_setprio 1
	v_mfma_f32_16x16x32_bf16 v[122:125], v[172:175], v[188:191], v[122:125]
	v_mfma_f32_16x16x32_bf16 v[114:117], v[180:183], v[188:191], v[114:117]
	v_mfma_f32_16x16x32_bf16 v[106:109], v[172:175], v[196:199], v[106:109]
	v_mfma_f32_16x16x32_bf16 v[98:101], v[180:183], v[196:199], v[98:101]
	v_mfma_f32_16x16x32_bf16 v[90:93], v[172:175], v[204:207], v[90:93]
	v_mfma_f32_16x16x32_bf16 v[82:85], v[180:183], v[204:207], v[82:85]
	v_mfma_f32_16x16x32_bf16 v[74:77], v[172:175], v[212:215], v[74:77]
	v_mfma_f32_16x16x32_bf16 v[66:69], v[180:183], v[212:215], v[66:69]
	v_mfma_f32_16x16x32_bf16 v[122:125], v[176:179], v[192:195], v[122:125]
	v_mfma_f32_16x16x32_bf16 v[114:117], v[184:187], v[192:195], v[114:117]
	v_mfma_f32_16x16x32_bf16 v[106:109], v[176:179], v[200:203], v[106:109]
	v_mfma_f32_16x16x32_bf16 v[98:101], v[184:187], v[200:203], v[98:101]
	s_barrier
	v_mfma_f32_16x16x32_bf16 v[90:93], v[176:179], v[208:211], v[90:93]
	v_mfma_f32_16x16x32_bf16 v[82:85], v[184:187], v[208:211], v[82:85]
	v_mfma_f32_16x16x32_bf16 v[74:77], v[176:179], v[216:219], v[74:77]
	v_mfma_f32_16x16x32_bf16 v[66:69], v[184:187], v[216:219], v[66:69]
	s_setprio 0
	s_add_i32 s51, s41, s31
	v_lshl_add_u64 v[220:221], s[26:27], 0, v[136:137]
	s_mov_b32 m0, s51
	ds_read_b128 v[188:191], v156 offset:16384
	ds_read_b128 v[192:195], v156 offset:17408
	ds_read_b128 v[196:199], v156 offset:18432
	ds_read_b128 v[200:203], v156 offset:19456
	ds_read_b128 v[204:207], v156 offset:20480
	ds_read_b128 v[208:211], v156 offset:21504
	ds_read_b128 v[212:215], v156 offset:22528
	ds_read_b128 v[216:219], v156 offset:23552
	global_load_lds_dwordx4 v[220:221], off
	s_add_i32 m0, s51, 0x2000
	s_add_u32 s68, s26, 0x80000
	v_lshl_add_u64 v[222:223], s[26:27], 0, v[132:133]
	s_addc_u32 s69, s27, 0
	s_add_i32 s51, s42, s31
	global_load_lds_dwordx4 v[222:223], off
	v_lshl_add_u64 v[224:225], s[68:69], 0, v[136:137]
	s_mov_b32 m0, s51
	v_lshl_add_u64 v[226:227], s[28:29], 0, v[134:135]
	global_load_lds_dwordx4 v[224:225], off
	v_lshl_add_u64 v[224:225], s[68:69], 0, v[132:133]
	s_add_i32 m0, s51, 0x2000
	s_nop 0
	global_load_lds_dwordx4 v[224:225], off
	v_lshl_add_u64 v[224:225], s[28:29], 0, v[138:139]
	s_mov_b32 m0, s23
	s_nop 0
	global_load_lds_dwordx4 v[224:225], off
	s_mov_b32 m0, s34
	s_nop 0
	global_load_lds_dwordx4 v[226:227], off
	s_waitcnt vmcnt(8)
	s_waitcnt lgkmcnt(0)
	s_setprio 1
	s_barrier
; #define PG8_STAGE(bufoff, gbase, voff) do { _Pragma("unroll") for (int _i = 0; _i < 2; ++_i) \
;         __builtin_amdgcn_global_load_lds((const unsigned*)((const char*)(gbase) + (voff)[_i]), (PG8_LAS unsigned*)(lds + (bufoff) + ldsw + _i * 8192), 16, 0, 0); } while (0)
; #define PG8_WAIT_V(n) asm volatile("s_waitcnt vmcnt(" #n ")" ::: "memory")
; #define PG8_WAIT_L(n) asm volatile("s_waitcnt lgkmcnt(" #n ")" ::: "memory")
; #define PG8_BAR __builtin_amdgcn_s_barrier()
; #define PG8_SCHED __builtin_amdgcn_sched_barrier(0)
; template <class Epi, class Sched, bool ALIGN_EPI = true, bool SP2 = true>
; __device__ __forceinline__ void gemm_phase(PG8_LAS unsigned char* lds, const int K  , const Sched& S, const Epi& E) {
;     ...
;             PG8_WAIT_V(8); PG8_WAIT_L(0); PG8_BAR; PG8_MMA(1, 0, At, B0); PG8_MMA(1, 1, At, B1); PG8_BAR; PG8_SCHED;
;             PG8_LDB(B0, 1, 0); PG8_LDB(B1, 1, 1); PG8_SCHED; PG8_LDA(At, 1, 0); PG8_STAGE(PG8_SA(0, 1), a2 + hstep, voffA);
;             PG8_WAIT_V(8); PG8_WAIT_L(0); PG8_BAR; PG8_MMA(0, 0, At, B0); PG8_MMA(0, 1, At, B1); PG8_BAR; PG8_SCHED;
	v_mfma_f32_16x16x32_bf16 v[62:65], v[148:151], v[188:191], v[62:65]
	v_mfma_f32_16x16x32_bf16 v[54:57], v[164:167], v[188:191], v[54:57]
	v_mfma_f32_16x16x32_bf16 v[46:49], v[148:151], v[196:199], v[46:49]
	v_mfma_f32_16x16x32_bf16 v[38:41], v[164:167], v[196:199], v[38:41]
	v_mfma_f32_16x16x32_bf16 v[30:33], v[148:151], v[204:207], v[30:33]
	v_mfma_f32_16x16x32_bf16 v[22:25], v[164:167], v[204:207], v[22:25]
	v_mfma_f32_16x16x32_bf16 v[14:17], v[148:151], v[212:215], v[14:17]
	v_mfma_f32_16x16x32_bf16 v[6:9], v[164:167], v[212:215], v[6:9]
	v_mfma_f32_16x16x32_bf16 v[62:65], v[160:163], v[192:195], v[62:65]
	v_mfma_f32_16x16x32_bf16 v[54:57], v[168:171], v[192:195], v[54:57]
	v_mfma_f32_16x16x32_bf16 v[46:49], v[160:163], v[200:203], v[46:49]
	v_mfma_f32_16x16x32_bf16 v[38:41], v[168:171], v[200:203], v[38:41]
	v_mfma_f32_16x16x32_bf16 v[30:33], v[160:163], v[208:211], v[30:33]
	v_mfma_f32_16x16x32_bf16 v[22:25], v[168:171], v[208:211], v[22:25]
	v_mfma_f32_16x16x32_bf16 v[14:17], v[160:163], v[216:219], v[14:17]
	v_mfma_f32_16x16x32_bf16 v[6:9], v[168:171], v[216:219], v[6:9]
	s_setprio 0
	s_setprio 1
	v_mfma_f32_16x16x32_bf16 v[58:61], v[172:175], v[188:191], v[58:61]
	v_mfma_f32_16x16x32_bf16 v[50:53], v[180:183], v[188:191], v[50:53]
	v_mfma_f32_16x16x32_bf16 v[42:45], v[172:175], v[196:199], v[42:45]
	v_mfma_f32_16x16x32_bf16 v[34:37], v[180:183], v[196:199], v[34:37]
	v_mfma_f32_16x16x32_bf16 v[26:29], v[172:175], v[204:207], v[26:29]
	v_mfma_f32_16x16x32_bf16 v[18:21], v[180:183], v[204:207], v[18:21]
	v_mfma_f32_16x16x32_bf16 v[10:13], v[172:175], v[212:215], v[10:13]
	v_mfma_f32_16x16x32_bf16 v[2:5], v[180:183], v[212:215], v[2:5]
	v_mfma_f32_16x16x32_bf16 v[58:61], v[176:179], v[192:195], v[58:61]
	v_mfma_f32_16x16x32_bf16 v[50:53], v[184:187], v[192:195], v[50:53]
	v_mfma_f32_16x16x32_bf16 v[42:45], v[176:179], v[200:203], v[42:45]
	v_mfma_f32_16x16x32_bf16 v[34:37], v[184:187], v[200:203], v[34:37]
	s_barrier
	v_mfma_f32_16x16x32_bf16 v[26:29], v[176:179], v[208:211], v[26:29]
	v_mfma_f32_16x16x32_bf16 v[18:21], v[184:187], v[208:211], v[18:21]
	v_mfma_f32_16x16x32_bf16 v[10:13], v[176:179], v[216:219], v[10:13]
	v_mfma_f32_16x16x32_bf16 v[2:5], v[184:187], v[216:219], v[2:5]
	s_setprio 0
	s_add_i32 s51, 0, 0x18000
	v_add_u32_e32 v159, s51, v152
	s_add_i32 s68, 0, 0x1c000
	ds_read_b128 v[148:151], v159
	ds_read_b128 v[160:163], v159 offset:1024
	ds_read_b128 v[164:167], v159 offset:2048
	ds_read_b128 v[168:171], v159 offset:3072
	v_add_u32_e32 v159, s68, v152
	ds_read_b128 v[172:175], v159
	ds_read_b128 v[176:179], v159 offset:1024
	ds_read_b128 v[180:183], v159 offset:2048
	ds_read_b128 v[184:187], v159 offset:3072
	s_add_u32 s28, s28, 0x80000
	s_addc_u32 s29, s29, 0
	s_mov_b32 m0, s35
	v_lshl_add_u64 v[230:231], s[28:29], 0, v[138:139]
	ds_read_b128 v[188:191], v156 offset:32768
	ds_read_b128 v[192:195], v156 offset:33792
	ds_read_b128 v[196:199], v156 offset:34816
	ds_read_b128 v[200:203], v156 offset:35840
	ds_read_b128 v[204:207], v156 offset:36864
	ds_read_b128 v[208:211], v156 offset:37888
	ds_read_b128 v[212:215], v156 offset:38912
	ds_read_b128 v[216:219], v156 offset:39936
	global_load_lds_dwordx4 v[230:231], off
	v_lshl_add_u64 v[230:231], s[28:29], 0, v[134:135]
	s_mov_b32 m0, s36
	s_nop 0
	global_load_lds_dwordx4 v[230:231], off
	s_waitcnt vmcnt(8)
	s_waitcnt lgkmcnt(0)
	s_setprio 1
	s_barrier
	v_mfma_f32_16x16x32_bf16 v[126:129], v[148:151], v[188:191], v[126:129]
	v_mfma_f32_16x16x32_bf16 v[118:121], v[164:167], v[188:191], v[118:121]
	v_mfma_f32_16x16x32_bf16 v[110:113], v[148:151], v[196:199], v[110:113]
	v_mfma_f32_16x16x32_bf16 v[102:105], v[164:167], v[196:199], v[102:105]
	v_mfma_f32_16x16x32_bf16 v[94:97], v[148:151], v[204:207], v[94:97]
	v_mfma_f32_16x16x32_bf16 v[86:89], v[164:167], v[204:207], v[86:89]
	v_mfma_f32_16x16x32_bf16 v[78:81], v[148:151], v[212:215], v[78:81]
	v_mfma_f32_16x16x32_bf16 v[70:73], v[164:167], v[212:215], v[70:73]
	v_mfma_f32_16x16x32_bf16 v[126:129], v[160:163], v[192:195], v[126:129]
	v_mfma_f32_16x16x32_bf16 v[118:121], v[168:171], v[192:195], v[118:121]
	v_mfma_f32_16x16x32_bf16 v[110:113], v[160:163], v[200:203], v[110:113]
	v_mfma_f32_16x16x32_bf16 v[102:105], v[168:171], v[200:203], v[102:105]
	v_mfma_f32_16x16x32_bf16 v[94:97], v[160:163], v[208:211], v[94:97]
	v_mfma_f32_16x16x32_bf16 v[86:89], v[168:171], v[208:211], v[86:89]
	v_mfma_f32_16x16x32_bf16 v[78:81], v[160:163], v[216:219], v[78:81]
	v_mfma_f32_16x16x32_bf16 v[70:73], v[168:171], v[216:219], v[70:73]
	s_setprio 0
	s_setprio 1
	v_mfma_f32_16x16x32_bf16 v[122:125], v[172:175], v[188:191], v[122:125]
	v_mfma_f32_16x16x32_bf16 v[114:117], v[180:183], v[188:191], v[114:117]
	v_mfma_f32_16x16x32_bf16 v[106:109], v[172:175], v[196:199], v[106:109]
	v_mfma_f32_16x16x32_bf16 v[98:101], v[180:183], v[196:199], v[98:101]
	v_mfma_f32_16x16x32_bf16 v[90:93], v[172:175], v[204:207], v[90:93]
	v_mfma_f32_16x16x32_bf16 v[82:85], v[180:183], v[204:207], v[82:85]
	v_mfma_f32_16x16x32_bf16 v[74:77], v[172:175], v[212:215], v[74:77]
	v_mfma_f32_16x16x32_bf16 v[66:69], v[180:183], v[212:215], v[66:69]
	v_mfma_f32_16x16x32_bf16 v[122:125], v[176:179], v[192:195], v[122:125]
	v_mfma_f32_16x16x32_bf16 v[114:117], v[184:187], v[192:195], v[114:117]
	v_mfma_f32_16x16x32_bf16 v[106:109], v[176:179], v[200:203], v[106:109]
	v_mfma_f32_16x16x32_bf16 v[98:101], v[184:187], v[200:203], v[98:101]
	s_barrier
; #define PG8_STAGE(bufoff, gbase, voff) do { _Pragma("unroll") for (int _i = 0; _i < 2; ++_i) \
;         __builtin_amdgcn_global_load_lds((const unsigned*)((const char*)(gbase) + (voff)[_i]), (PG8_LAS unsigned*)(lds + (bufoff) + ldsw + _i * 8192), 16, 0, 0); } while (0)
; #define PG8_WAIT_V(n) asm volatile("s_waitcnt vmcnt(" #n ")" ::: "memory")
; #define PG8_WAIT_L(n) asm volatile("s_waitcnt lgkmcnt(" #n ")" ::: "memory")
; #define PG8_BAR __builtin_amdgcn_s_barrier()
; #define PG8_SCHED __builtin_amdgcn_sched_barrier(0)
; template <class Epi, class Sched, bool ALIGN_EPI = true, bool SP2 = true>
; __device__ __forceinline__ void gemm_phase(PG8_LAS unsigned char* lds, const int K  , const Sched& S, const Epi& E) {
;     ...
;             PG8_WAIT_V(8); PG8_WAIT_L(0); PG8_BAR; PG8_MMA(0, 0, At, B0); PG8_MMA(0, 1, At, B1); PG8_BAR; PG8_SCHED;
;             PG8_LDA(At, 1, 1); PG8_STAGE(PG8_SB(1, 0), b3, voffB); PG8_STAGE(PG8_SB(1, 1), b3 + hstep, voffB); PG8_STAGE(PG8_SA(1, 0), a3, voffA);
;             PG8_WAIT_V(8); PG8_WAIT_L(0); PG8_BAR; PG8_MMA(1, 0, At, B0); PG8_MMA(1, 1, At, B1); PG8_BAR; PG8_SCHED;
	v_mfma_f32_16x16x32_bf16 v[90:93], v[176:179], v[208:211], v[90:93]
	v_mfma_f32_16x16x32_bf16 v[82:85], v[184:187], v[208:211], v[82:85]
	v_mfma_f32_16x16x32_bf16 v[74:77], v[176:179], v[216:219], v[74:77]
	v_mfma_f32_16x16x32_bf16 v[66:69], v[184:187], v[216:219], v[66:69]
	s_setprio 0
	s_add_i32 s28, s51, s31
	v_lshl_add_u64 v[220:221], v[220:221], 0, s[4:5]
	s_mov_b32 m0, s28
	ds_read_b128 v[188:191], v156 offset:49152
	ds_read_b128 v[192:195], v156 offset:50176
	ds_read_b128 v[196:199], v156 offset:51200
	ds_read_b128 v[200:203], v156 offset:52224
	ds_read_b128 v[204:207], v156 offset:53248
	ds_read_b128 v[208:211], v156 offset:54272
	ds_read_b128 v[212:215], v156 offset:55296
	ds_read_b128 v[216:219], v156 offset:56320
	global_load_lds_dwordx4 v[220:221], off
	s_add_i32 m0, s28, 0x2000
	s_add_u32 s26, s26, 0x80080
	v_lshl_add_u64 v[220:221], v[222:223], 0, s[4:5]
	s_addc_u32 s27, s27, 0
	s_add_i32 s28, s68, s31
	global_load_lds_dwordx4 v[220:221], off
	v_lshl_add_u64 v[220:221], s[26:27], 0, v[136:137]
	s_mov_b32 m0, s28
	s_nop 0
	global_load_lds_dwordx4 v[220:221], off
	v_lshl_add_u64 v[220:221], s[26:27], 0, v[132:133]
	s_add_i32 m0, s28, 0x2000
	s_nop 0
	global_load_lds_dwordx4 v[220:221], off
	v_lshl_add_u64 v[220:221], v[224:225], 0, s[4:5]
	s_mov_b32 m0, s38
	s_nop 0
	global_load_lds_dwordx4 v[220:221], off
	v_lshl_add_u64 v[220:221], v[226:227], 0, s[4:5]
	s_mov_b32 m0, s39
	s_nop 0
	global_load_lds_dwordx4 v[220:221], off
	s_waitcnt vmcnt(8)
	s_waitcnt lgkmcnt(0)
	s_setprio 1
	s_barrier
	v_mfma_f32_16x16x32_bf16 v[62:65], v[148:151], v[188:191], v[62:65]
	v_mfma_f32_16x16x32_bf16 v[54:57], v[164:167], v[188:191], v[54:57]
	v_mfma_f32_16x16x32_bf16 v[46:49], v[148:151], v[196:199], v[46:49]
	v_mfma_f32_16x16x32_bf16 v[38:41], v[164:167], v[196:199], v[38:41]
	v_mfma_f32_16x16x32_bf16 v[30:33], v[148:151], v[204:207], v[30:33]
	v_mfma_f32_16x16x32_bf16 v[22:25], v[164:167], v[204:207], v[22:25]
	v_mfma_f32_16x16x32_bf16 v[14:17], v[148:151], v[212:215], v[14:17]
	v_mfma_f32_16x16x32_bf16 v[6:9], v[164:167], v[212:215], v[6:9]
	v_mfma_f32_16x16x32_bf16 v[62:65], v[160:163], v[192:195], v[62:65]
	v_mfma_f32_16x16x32_bf16 v[54:57], v[168:171], v[192:195], v[54:57]
	v_mfma_f32_16x16x32_bf16 v[46:49], v[160:163], v[200:203], v[46:49]
	v_mfma_f32_16x16x32_bf16 v[38:41], v[168:171], v[200:203], v[38:41]
	v_mfma_f32_16x16x32_bf16 v[30:33], v[160:163], v[208:211], v[30:33]
	v_mfma_f32_16x16x32_bf16 v[22:25], v[168:171], v[208:211], v[22:25]
	v_mfma_f32_16x16x32_bf16 v[14:17], v[160:163], v[216:219], v[14:17]
	v_mfma_f32_16x16x32_bf16 v[6:9], v[168:171], v[216:219], v[6:9]
	s_setprio 0
	s_setprio 1
	v_mfma_f32_16x16x32_bf16 v[58:61], v[172:175], v[188:191], v[58:61]
	v_mfma_f32_16x16x32_bf16 v[50:53], v[180:183], v[188:191], v[50:53]
	v_mfma_f32_16x16x32_bf16 v[42:45], v[172:175], v[196:199], v[42:45]
	v_mfma_f32_16x16x32_bf16 v[34:37], v[180:183], v[196:199], v[34:37]
	v_mfma_f32_16x16x32_bf16 v[26:29], v[172:175], v[204:207], v[26:29]
	v_mfma_f32_16x16x32_bf16 v[18:21], v[180:183], v[204:207], v[18:21]
	v_mfma_f32_16x16x32_bf16 v[10:13], v[172:175], v[212:215], v[10:13]
	v_mfma_f32_16x16x32_bf16 v[2:5], v[180:183], v[212:215], v[2:5]
	v_mfma_f32_16x16x32_bf16 v[58:61], v[176:179], v[192:195], v[58:61]
	v_mfma_f32_16x16x32_bf16 v[50:53], v[184:187], v[192:195], v[50:53]
	v_mfma_f32_16x16x32_bf16 v[42:45], v[176:179], v[200:203], v[42:45]
	v_mfma_f32_16x16x32_bf16 v[34:37], v[184:187], v[200:203], v[34:37]
	s_barrier
	v_mfma_f32_16x16x32_bf16 v[26:29], v[176:179], v[208:211], v[26:29]
	v_mfma_f32_16x16x32_bf16 v[18:21], v[184:187], v[208:211], v[18:21]
	v_mfma_f32_16x16x32_bf16 v[10:13], v[176:179], v[216:219], v[10:13]
	v_mfma_f32_16x16x32_bf16 v[2:5], v[184:187], v[216:219], v[2:5]
	s_setprio 0
	s_add_i32 s50, s50, 2
	s_add_u32 s24, s24, 0x100
	s_addc_u32 s25, s25, 0
	s_add_u32 s48, s48, 0x100
	s_addc_u32 s49, s49, 0
	s_cmp_gt_u32 s50, 29
	s_cbranch_scc0 .LBB0_1448
	s_and_b64 vcc, exec, s[8:9]
	s_cbranch_vccz .LBB0_1451
	s_barrier

; #define PG8_STAGE(bufoff, gbase, voff) do { _Pragma("unroll") for (int _i = 0; _i < 2; ++_i) \
;         __builtin_amdgcn_global_load_lds((const unsigned*)((const char*)(gbase) + (voff)[_i]), (PG8_LAS unsigned*)(lds + (bufoff) + ldsw + _i * 8192), 16, 0, 0); } while (0)
; #define PG8_WAIT_V(n) asm volatile("s_waitcnt vmcnt(" #n ")" ::: "memory")
; #define PG8_WAIT_L(n) asm volatile("s_waitcnt lgkmcnt(" #n ")" ::: "memory")
; #define PG8_BAR __builtin_amdgcn_s_barrier()
; #define PG8_SCHED __builtin_amdgcn_sched_barrier(0)
; template <class Epi, class Sched, bool ALIGN_EPI = true, bool SP2 = true>
; __device__ __forceinline__ void gemm_phase(PG8_LAS unsigned char* lds, const int K  , const Sched& S, const Epi& E) {
;     ...
;             const char* a1 = cA + (size_t)(t + 1) * kstep;
;             const char* a2 = last ? nA : cA + (size_t)(t + 2) * kstep; const char* b2 = last ? nB : cB + (size_t)(t + 2) * kstep;
;             const char* a3 = a2 + kstep; const char* b3 = b2 + kstep;
;             if constexpr (SP2) {
;             PG8_LDB(B0, 0, 0); PG8_LDB(B1, 0, 1); PG8_SCHED; PG8_LDA(At, 0, 0); PG8_STAGE(PG8_SA(1, 1), a1 + hstep, voffA);
;             PG8_WAIT_V(8); PG8_WAIT_L(0); PG8_BAR; PG8_MMA(0, 0, At, B0); PG8_MMA(0, 1, At, B1); PG8_BAR; PG8_SCHED;
;             PG8_LDA(At, 0, 1); PG8_STAGE(PG8_SB(0, 0), b2, voffB); PG8_STAGE(PG8_SB(0, 1), b2 + hstep, voffB); PG8_STAGE(PG8_SA(0, 0), a2, voffA);
;             PG8_WAIT_V(8); PG8_WAIT_L(0); PG8_BAR; PG8_MMA(1, 0, At, B0); PG8_MMA(1, 1, At, B1); PG8_BAR; PG8_SCHED;
.LBB0_1695:
	ds_read_b128 v[18:21], v233
	ds_read_b128 v[22:25], v233 offset:1024
	ds_read_b128 v[26:29], v233 offset:2048
	ds_read_b128 v[30:33], v233 offset:3072
	ds_read_b128 v[2:5], v234
	ds_read_b128 v[6:9], v234 offset:1024
	ds_read_b128 v[10:13], v234 offset:2048
	ds_read_b128 v[14:17], v234 offset:3072
	s_add_i32 s74, s24, 2
	s_add_u32 s22, s20, 0xfff50080
	s_addc_u32 s23, s21, -1
	s_cmp_eq_u32 s71, s24
	s_cselect_b32 s24, s16, s22
	s_cselect_b32 s25, s17, s23
	s_cselect_b32 s23, s19, s73
	s_cselect_b32 s22, s18, s72
	v_lshl_add_u64 v[186:187], s[20:21], 0, v[198:199]
	s_add_i32 m0, s28, 0xc000
	ds_read_b128 v[162:165], v235
	ds_read_b128 v[166:169], v235 offset:1024
	ds_read_b128 v[170:173], v235 offset:2048
	ds_read_b128 v[174:177], v235 offset:3072
	ds_read_b128 v[178:181], v235 offset:4096
	ds_read_b128 v[182:185], v235 offset:5120
	ds_read_b128 v[206:209], v235 offset:6144
	ds_read_b128 v[210:213], v235 offset:7168
	global_load_lds_dwordx4 v[186:187], off
	v_lshl_add_u64 v[186:187], s[20:21], 0, v[200:201]
	s_add_i32 m0, s28, 0xe000
	s_nop 0
	global_load_lds_dwordx4 v[186:187], off
	s_waitcnt vmcnt(8)
	s_waitcnt lgkmcnt(0)
	s_setprio 1
	s_barrier
	v_mfma_scale_f32_16x16x128_f8f6f4 v[158:161], v[18:25], v[162:169], v[158:161], v229, v229 op_sel_hi:[0,0,0]
	v_mfma_scale_f32_16x16x128_f8f6f4 v[154:157], v[26:33], v[162:169], v[154:157], v229, v229 op_sel_hi:[0,0,0]
	v_mfma_scale_f32_16x16x128_f8f6f4 v[150:153], v[18:25], v[170:177], v[150:153], v229, v229 op_sel_hi:[0,0,0]
	v_mfma_scale_f32_16x16x128_f8f6f4 v[142:145], v[26:33], v[170:177], v[142:145], v229, v229 op_sel_hi:[0,0,0]
	v_mfma_scale_f32_16x16x128_f8f6f4 v[134:137], v[18:25], v[178:185], v[134:137], v229, v229 op_sel_hi:[0,0,0]
	v_mfma_scale_f32_16x16x128_f8f6f4 v[126:129], v[26:33], v[178:185], v[126:129], v229, v229 op_sel_hi:[0,0,0]
	v_mfma_scale_f32_16x16x128_f8f6f4 v[118:121], v[18:25], v[206:213], v[118:121], v229, v229 op_sel_hi:[0,0,0]
	v_mfma_scale_f32_16x16x128_f8f6f4 v[110:113], v[26:33], v[206:213], v[110:113], v229, v229 op_sel_hi:[0,0,0]
	s_setprio 0
	s_setprio 1
	v_mfma_scale_f32_16x16x128_f8f6f4 v[146:149], v[2:9], v[162:169], v[146:149], v229, v229 op_sel_hi:[0,0,0]
	v_mfma_scale_f32_16x16x128_f8f6f4 v[138:141], v[10:17], v[162:169], v[138:141], v229, v229 op_sel_hi:[0,0,0]
	v_mfma_scale_f32_16x16x128_f8f6f4 v[130:133], v[2:9], v[170:177], v[130:133], v229, v229 op_sel_hi:[0,0,0]
	v_mfma_scale_f32_16x16x128_f8f6f4 v[122:125], v[10:17], v[170:177], v[122:125], v229, v229 op_sel_hi:[0,0,0]
	v_mfma_scale_f32_16x16x128_f8f6f4 v[114:117], v[2:9], v[178:185], v[114:117], v229, v229 op_sel_hi:[0,0,0]
	v_mfma_scale_f32_16x16x128_f8f6f4 v[106:109], v[10:17], v[178:185], v[106:109], v229, v229 op_sel_hi:[0,0,0]
	s_barrier
	v_mfma_scale_f32_16x16x128_f8f6f4 v[102:105], v[2:9], v[206:213], v[102:105], v229, v229 op_sel_hi:[0,0,0]
	v_mfma_scale_f32_16x16x128_f8f6f4 v[98:101], v[10:17], v[206:213], v[98:101], v229, v229 op_sel_hi:[0,0,0]
	s_setprio 0
	s_add_i32 s75, s40, s27
	v_lshl_add_u64 v[162:163], s[22:23], 0, v[192:193]
	s_mov_b32 m0, s75
	ds_read_b128 v[170:173], v235 offset:16384
	ds_read_b128 v[174:177], v235 offset:17408
	ds_read_b128 v[178:181], v235 offset:18432
	ds_read_b128 v[182:185], v235 offset:19456
	ds_read_b128 v[206:209], v235 offset:20480
	ds_read_b128 v[210:213], v235 offset:21504
	ds_read_b128 v[214:217], v235 offset:22528
	ds_read_b128 v[218:221], v235 offset:23552
	global_load_lds_dwordx4 v[162:163], off
	s_add_i32 m0, s75, 0x2000
	s_add_u32 s78, s22, 0xb0000
	v_lshl_add_u64 v[164:165], s[22:23], 0, v[196:197]
	s_addc_u32 s79, s23, 0
	s_add_i32 s75, s41, s27
	global_load_lds_dwordx4 v[164:165], off
	v_lshl_add_u64 v[166:167], s[78:79], 0, v[192:193]
	s_mov_b32 m0, s75
	v_lshl_add_u64 v[168:169], s[24:25], 0, v[194:195]
	global_load_lds_dwordx4 v[166:167], off
	v_lshl_add_u64 v[166:167], s[78:79], 0, v[196:197]
	s_add_i32 m0, s75, 0x2000
	s_nop 0
	global_load_lds_dwordx4 v[166:167], off
	v_lshl_add_u64 v[166:167], s[24:25], 0, v[190:191]
	s_mov_b32 m0, s28
	s_nop 0
	global_load_lds_dwordx4 v[166:167], off
	s_mov_b32 m0, s29
	s_nop 0
	global_load_lds_dwordx4 v[168:169], off
	s_waitcnt vmcnt(8)
	s_waitcnt lgkmcnt(0)
	s_setprio 1
	s_barrier
	v_mfma_scale_f32_16x16x128_f8f6f4 v[94:97], v[18:25], v[170:177], v[94:97], v229, v229 op_sel_hi:[0,0,0]
	v_mfma_scale_f32_16x16x128_f8f6f4 v[90:93], v[26:33], v[170:177], v[90:93], v229, v229 op_sel_hi:[0,0,0]
	v_mfma_scale_f32_16x16x128_f8f6f4 v[86:89], v[18:25], v[178:185], v[86:89], v229, v229 op_sel_hi:[0,0,0]
	v_mfma_scale_f32_16x16x128_f8f6f4 v[78:81], v[26:33], v[178:185], v[78:81], v229, v229 op_sel_hi:[0,0,0]
	v_mfma_scale_f32_16x16x128_f8f6f4 v[70:73], v[18:25], v[206:213], v[70:73], v229, v229 op_sel_hi:[0,0,0]
	v_mfma_scale_f32_16x16x128_f8f6f4 v[62:65], v[26:33], v[206:213], v[62:65], v229, v229 op_sel_hi:[0,0,0]
	v_mfma_scale_f32_16x16x128_f8f6f4 v[54:57], v[18:25], v[214:221], v[54:57], v229, v229 op_sel_hi:[0,0,0]
	v_mfma_scale_f32_16x16x128_f8f6f4 v[46:49], v[26:33], v[214:221], v[46:49], v229, v229 op_sel_hi:[0,0,0]
	s_setprio 0
	s_setprio 1
	v_mfma_scale_f32_16x16x128_f8f6f4 v[82:85], v[2:9], v[170:177], v[82:85], v229, v229 op_sel_hi:[0,0,0]
	v_mfma_scale_f32_16x16x128_f8f6f4 v[74:77], v[10:17], v[170:177], v[74:77], v229, v229 op_sel_hi:[0,0,0]
	v_mfma_scale_f32_16x16x128_f8f6f4 v[66:69], v[2:9], v[178:185], v[66:69], v229, v229 op_sel_hi:[0,0,0]
	v_mfma_scale_f32_16x16x128_f8f6f4 v[58:61], v[10:17], v[178:185], v[58:61], v229, v229 op_sel_hi:[0,0,0]
	v_mfma_scale_f32_16x16x128_f8f6f4 v[50:53], v[2:9], v[206:213], v[50:53], v229, v229 op_sel_hi:[0,0,0]
	v_mfma_scale_f32_16x16x128_f8f6f4 v[42:45], v[10:17], v[206:213], v[42:45], v229, v229 op_sel_hi:[0,0,0]
	s_barrier
; #define PG8_STAGE(bufoff, gbase, voff) do { _Pragma("unroll") for (int _i = 0; _i < 2; ++_i) \
;         __builtin_amdgcn_global_load_lds((const unsigned*)((const char*)(gbase) + (voff)[_i]), (PG8_LAS unsigned*)(lds + (bufoff) + ldsw + _i * 8192), 16, 0, 0); } while (0)
; #define PG8_WAIT_V(n) asm volatile("s_waitcnt vmcnt(" #n ")" ::: "memory")
; #define PG8_WAIT_L(n) asm volatile("s_waitcnt lgkmcnt(" #n ")" ::: "memory")
; #define PG8_BAR __builtin_amdgcn_s_barrier()
; #define PG8_SCHED __builtin_amdgcn_sched_barrier(0)
; template <class Epi, class Sched, bool ALIGN_EPI = true, bool SP2 = true>
; __device__ __forceinline__ void gemm_phase(PG8_LAS unsigned char* lds, const int K  , const Sched& S, const Epi& E) {
;     ...
;             PG8_LDB(B0, 1, 0); PG8_LDB(B1, 1, 1); PG8_SCHED; PG8_LDA(At, 1, 0); PG8_STAGE(PG8_SA(0, 1), a2 + hstep, voffA);
;             PG8_WAIT_V(8); PG8_WAIT_L(0); PG8_BAR; PG8_MMA(0, 0, At, B0); PG8_MMA(0, 1, At, B1); PG8_BAR; PG8_SCHED;
;             PG8_LDA(At, 1, 1); PG8_STAGE(PG8_SB(1, 0), b3, voffB); PG8_STAGE(PG8_SB(1, 1), b3 + hstep, voffB); PG8_STAGE(PG8_SA(1, 0), a3, voffA);
;             PG8_WAIT_V(8); PG8_WAIT_L(0); PG8_BAR; PG8_MMA(1, 0, At, B0); PG8_MMA(1, 1, At, B1); PG8_BAR; PG8_SCHED;
;     ...
;         if constexpr (Epi::FP8) asm volatile("s_nop 15\n\ts_nop 15\n\ts_nop 15\n\ts_nop 15\n\ts_nop 15" ::: "memory");
;         if constexpr (ALIGN_EPI) { if (wr == 0) PG8_BAR; }
	v_mfma_scale_f32_16x16x128_f8f6f4 v[38:41], v[2:9], v[214:221], v[38:41], v229, v229 op_sel_hi:[0,0,0]
	v_mfma_scale_f32_16x16x128_f8f6f4 v[34:37], v[10:17], v[214:221], v[34:37], v229, v229 op_sel_hi:[0,0,0]
	s_setprio 0
	s_add_i32 s75, 0, 0x18000
	s_add_i32 s78, 0, 0x1c000
	v_add_u32_e32 v14, s75, v231
	v_add_u32_e32 v30, s78, v231
	ds_read_b128 v[2:5], v14
	ds_read_b128 v[6:9], v14 offset:1024
	ds_read_b128 v[10:13], v14 offset:2048
	ds_read_b128 v[14:17], v14 offset:3072
	ds_read_b128 v[18:21], v30
	ds_read_b128 v[22:25], v30 offset:1024
	ds_read_b128 v[26:29], v30 offset:2048
	ds_read_b128 v[30:33], v30 offset:3072
	s_add_u32 s24, s24, 0xb0000
	s_addc_u32 s25, s25, 0
	s_mov_b32 m0, s30
	v_lshl_add_u64 v[186:187], s[24:25], 0, v[190:191]
	ds_read_b128 v[170:173], v235 offset:32768
	ds_read_b128 v[174:177], v235 offset:33792
	ds_read_b128 v[178:181], v235 offset:34816
	ds_read_b128 v[182:185], v235 offset:35840
	ds_read_b128 v[206:209], v235 offset:36864
	ds_read_b128 v[210:213], v235 offset:37888
	ds_read_b128 v[214:217], v235 offset:38912
	ds_read_b128 v[218:221], v235 offset:39936
	global_load_lds_dwordx4 v[186:187], off
	v_lshl_add_u64 v[186:187], s[24:25], 0, v[194:195]
	s_mov_b32 m0, s31
	s_nop 0
	global_load_lds_dwordx4 v[186:187], off
	s_waitcnt vmcnt(8)
	s_waitcnt lgkmcnt(0)
	s_setprio 1
	s_barrier
	v_mfma_scale_f32_16x16x128_f8f6f4 v[158:161], v[2:9], v[170:177], v[158:161], v229, v229 op_sel_hi:[0,0,0]
	v_mfma_scale_f32_16x16x128_f8f6f4 v[154:157], v[10:17], v[170:177], v[154:157], v229, v229 op_sel_hi:[0,0,0]
	v_mfma_scale_f32_16x16x128_f8f6f4 v[150:153], v[2:9], v[178:185], v[150:153], v229, v229 op_sel_hi:[0,0,0]
	v_mfma_scale_f32_16x16x128_f8f6f4 v[142:145], v[10:17], v[178:185], v[142:145], v229, v229 op_sel_hi:[0,0,0]
	v_mfma_scale_f32_16x16x128_f8f6f4 v[134:137], v[2:9], v[206:213], v[134:137], v229, v229 op_sel_hi:[0,0,0]
	v_mfma_scale_f32_16x16x128_f8f6f4 v[126:129], v[10:17], v[206:213], v[126:129], v229, v229 op_sel_hi:[0,0,0]
	v_mfma_scale_f32_16x16x128_f8f6f4 v[118:121], v[2:9], v[214:221], v[118:121], v229, v229 op_sel_hi:[0,0,0]
	v_mfma_scale_f32_16x16x128_f8f6f4 v[110:113], v[10:17], v[214:221], v[110:113], v229, v229 op_sel_hi:[0,0,0]
	s_setprio 0
	s_setprio 1
	v_mfma_scale_f32_16x16x128_f8f6f4 v[146:149], v[18:25], v[170:177], v[146:149], v229, v229 op_sel_hi:[0,0,0]
	v_mfma_scale_f32_16x16x128_f8f6f4 v[138:141], v[26:33], v[170:177], v[138:141], v229, v229 op_sel_hi:[0,0,0]
	v_mfma_scale_f32_16x16x128_f8f6f4 v[130:133], v[18:25], v[178:185], v[130:133], v229, v229 op_sel_hi:[0,0,0]
	v_mfma_scale_f32_16x16x128_f8f6f4 v[122:125], v[26:33], v[178:185], v[122:125], v229, v229 op_sel_hi:[0,0,0]
	v_mfma_scale_f32_16x16x128_f8f6f4 v[114:117], v[18:25], v[206:213], v[114:117], v229, v229 op_sel_hi:[0,0,0]
	v_mfma_scale_f32_16x16x128_f8f6f4 v[106:109], v[26:33], v[206:213], v[106:109], v229, v229 op_sel_hi:[0,0,0]
	s_barrier
	v_mfma_scale_f32_16x16x128_f8f6f4 v[102:105], v[18:25], v[214:221], v[102:105], v229, v229 op_sel_hi:[0,0,0]
	v_mfma_scale_f32_16x16x128_f8f6f4 v[98:101], v[26:33], v[214:221], v[98:101], v229, v229 op_sel_hi:[0,0,0]
	s_setprio 0
	s_add_i32 s24, s75, s27
	v_lshl_add_u64 v[162:163], v[162:163], 0, s[10:11]
	s_mov_b32 m0, s24
	ds_read_b128 v[170:173], v235 offset:49152
	ds_read_b128 v[174:177], v235 offset:50176
	ds_read_b128 v[178:181], v235 offset:51200
	ds_read_b128 v[182:185], v235 offset:52224
	ds_read_b128 v[206:209], v235 offset:53248
	ds_read_b128 v[210:213], v235 offset:54272
	ds_read_b128 v[214:217], v235 offset:55296
	ds_read_b128 v[218:221], v235 offset:56320
	global_load_lds_dwordx4 v[162:163], off
	s_add_i32 m0, s24, 0x2000
	s_add_u32 s22, s22, 0xb0080
	v_lshl_add_u64 v[162:163], v[164:165], 0, s[10:11]
	s_addc_u32 s23, s23, 0
	s_add_i32 s24, s78, s27
	global_load_lds_dwordx4 v[162:163], off
	v_lshl_add_u64 v[162:163], s[22:23], 0, v[192:193]
	s_mov_b32 m0, s24
	s_nop 0
	global_load_lds_dwordx4 v[162:163], off
	v_lshl_add_u64 v[162:163], s[22:23], 0, v[196:197]
	s_add_i32 m0, s24, 0x2000
	s_nop 0
	global_load_lds_dwordx4 v[162:163], off
	v_lshl_add_u64 v[162:163], v[166:167], 0, s[10:11]
	s_mov_b32 m0, s36
	s_nop 0
	global_load_lds_dwordx4 v[162:163], off
	v_lshl_add_u64 v[162:163], v[168:169], 0, s[10:11]
	s_mov_b32 m0, s37
	s_nop 0
	global_load_lds_dwordx4 v[162:163], off
	s_waitcnt vmcnt(8)
	s_waitcnt lgkmcnt(0)
	s_setprio 1
	s_barrier
	v_mfma_scale_f32_16x16x128_f8f6f4 v[94:97], v[2:9], v[170:177], v[94:97], v229, v229 op_sel_hi:[0,0,0]
	v_mfma_scale_f32_16x16x128_f8f6f4 v[90:93], v[10:17], v[170:177], v[90:93], v229, v229 op_sel_hi:[0,0,0]
	v_mfma_scale_f32_16x16x128_f8f6f4 v[86:89], v[2:9], v[178:185], v[86:89], v229, v229 op_sel_hi:[0,0,0]
	v_mfma_scale_f32_16x16x128_f8f6f4 v[78:81], v[10:17], v[178:185], v[78:81], v229, v229 op_sel_hi:[0,0,0]
	v_mfma_scale_f32_16x16x128_f8f6f4 v[70:73], v[2:9], v[206:213], v[70:73], v229, v229 op_sel_hi:[0,0,0]
	v_mfma_scale_f32_16x16x128_f8f6f4 v[62:65], v[10:17], v[206:213], v[62:65], v229, v229 op_sel_hi:[0,0,0]
	v_mfma_scale_f32_16x16x128_f8f6f4 v[54:57], v[2:9], v[214:221], v[54:57], v229, v229 op_sel_hi:[0,0,0]
	v_mfma_scale_f32_16x16x128_f8f6f4 v[46:49], v[10:17], v[214:221], v[46:49], v229, v229 op_sel_hi:[0,0,0]
	s_setprio 0
	s_setprio 1
	v_mfma_scale_f32_16x16x128_f8f6f4 v[82:85], v[18:25], v[170:177], v[82:85], v229, v229 op_sel_hi:[0,0,0]
	v_mfma_scale_f32_16x16x128_f8f6f4 v[74:77], v[26:33], v[170:177], v[74:77], v229, v229 op_sel_hi:[0,0,0]
	v_mfma_scale_f32_16x16x128_f8f6f4 v[66:69], v[18:25], v[178:185], v[66:69], v229, v229 op_sel_hi:[0,0,0]
	v_mfma_scale_f32_16x16x128_f8f6f4 v[58:61], v[26:33], v[178:185], v[58:61], v229, v229 op_sel_hi:[0,0,0]
	v_mfma_scale_f32_16x16x128_f8f6f4 v[50:53], v[18:25], v[206:213], v[50:53], v229, v229 op_sel_hi:[0,0,0]
	v_mfma_scale_f32_16x16x128_f8f6f4 v[42:45], v[26:33], v[206:213], v[42:45], v229, v229 op_sel_hi:[0,0,0]
	s_barrier
	v_mfma_scale_f32_16x16x128_f8f6f4 v[38:41], v[18:25], v[214:221], v[38:41], v229, v229 op_sel_hi:[0,0,0]
	v_mfma_scale_f32_16x16x128_f8f6f4 v[34:37], v[26:33], v[214:221], v[34:37], v229, v229 op_sel_hi:[0,0,0]
	s_setprio 0
	s_add_u32 s20, s20, 0x100
	s_addc_u32 s21, s21, 0
	s_add_u32 s72, s72, 0x100
	s_addc_u32 s73, s73, 0
	s_cmp_ge_u32 s74, s4
	s_mov_b32 s24, s74
	s_cbranch_scc0 .LBB0_1695
	s_nop 15
	s_nop 15
	s_nop 15
	s_nop 15
	s_nop 15
	s_and_b64 vcc, exec, s[12:13]
	s_cbranch_vccz .LBB0_1698
	s_barrier

; #define PG8_STAGE(bufoff, gbase, voff) do { _Pragma("unroll") for (int _i = 0; _i < 2; ++_i) \
;         __builtin_amdgcn_global_load_lds((const unsigned*)((const char*)(gbase) + (voff)[_i]), (PG8_LAS unsigned*)(lds + (bufoff) + ldsw + _i * 8192), 16, 0, 0); } while (0)
; #define PG8_WAIT_V(n) asm volatile("s_waitcnt vmcnt(" #n ")" ::: "memory")
; #define PG8_WAIT_L(n) asm volatile("s_waitcnt lgkmcnt(" #n ")" ::: "memory")
; #define PG8_BAR __builtin_amdgcn_s_barrier()
; #define PG8_SCHED __builtin_amdgcn_sched_barrier(0)
; template <class Epi, class Sched, bool ALIGN_EPI = true, bool SP2 = true>
; __device__ __forceinline__ void gemm_phase(PG8_LAS unsigned char* lds, const int K  , const Sched& S, const Epi& E) {
;     ...
;             const char* a1 = cA + (size_t)(t + 1) * kstep;
;             const char* a2 = last ? nA : cA + (size_t)(t + 2) * kstep; const char* b2 = last ? nB : cB + (size_t)(t + 2) * kstep;
;             const char* a3 = a2 + kstep; const char* b3 = b2 + kstep;
;             if constexpr (SP2) {
;             PG8_LDB(B0, 0, 0); PG8_LDB(B1, 0, 1); PG8_SCHED; PG8_LDA(At, 0, 0); PG8_STAGE(PG8_SA(1, 1), a1 + hstep, voffA);
;             PG8_WAIT_V(8); PG8_WAIT_L(0); PG8_BAR; PG8_MMA(0, 0, At, B0); PG8_MMA(0, 1, At, B1); PG8_BAR; PG8_SCHED;
;             PG8_LDA(At, 0, 1); PG8_STAGE(PG8_SB(0, 0), b2, voffB); PG8_STAGE(PG8_SB(0, 1), b2 + hstep, voffB); PG8_STAGE(PG8_SA(0, 0), a2, voffA);
;             PG8_WAIT_V(8); PG8_WAIT_L(0); PG8_BAR; PG8_MMA(1, 0, At, B0); PG8_MMA(1, 1, At, B1); PG8_BAR; PG8_SCHED;
.LBB0_1847:
	ds_read_b128 v[130:133], v176
	ds_read_b128 v[134:137], v176 offset:1024
	ds_read_b128 v[138:141], v176 offset:2048
	ds_read_b128 v[142:145], v176 offset:3072
	ds_read_b128 v[168:171], v177
	ds_read_b128 v[184:187], v177 offset:1024
	ds_read_b128 v[188:191], v177 offset:2048
	ds_read_b128 v[192:195], v177 offset:3072
	s_add_u32 s22, s0, 0xfff80080
	s_addc_u32 s23, s1, -1
	s_cmp_eq_u32 s51, 28
	s_cselect_b32 s25, s7, s23
	s_cselect_b32 s24, s47, s22
	s_cselect_b32 s23, s11, s50
	s_cselect_b32 s22, s48, s49
	v_lshl_add_u64 v[230:231], s[0:1], 0, v[160:161]
	s_add_i32 m0, s27, 0xc000
	ds_read_b128 v[196:199], v178
	ds_read_b128 v[200:203], v178 offset:1024
	ds_read_b128 v[204:207], v178 offset:2048
	ds_read_b128 v[208:211], v178 offset:3072
	ds_read_b128 v[212:215], v178 offset:4096
	ds_read_b128 v[216:219], v178 offset:5120
	ds_read_b128 v[220:223], v178 offset:6144
	ds_read_b128 v[224:227], v178 offset:7168
	global_load_lds_dwordx4 v[230:231], off
	v_lshl_add_u64 v[230:231], s[0:1], 0, v[162:163]
	s_add_i32 m0, s27, 0xe000
	s_nop 0
	global_load_lds_dwordx4 v[230:231], off
	s_waitcnt vmcnt(8)
	s_waitcnt lgkmcnt(0)
	s_setprio 1
	s_barrier
	v_mfma_f32_16x16x32_bf16 v[126:129], v[130:133], v[196:199], v[126:129]
	v_mfma_f32_16x16x32_bf16 v[122:125], v[138:141], v[196:199], v[122:125]
	v_mfma_f32_16x16x32_bf16 v[110:113], v[130:133], v[204:207], v[110:113]
	v_mfma_f32_16x16x32_bf16 v[106:109], v[138:141], v[204:207], v[106:109]
	v_mfma_f32_16x16x32_bf16 v[94:97], v[130:133], v[212:215], v[94:97]
	v_mfma_f32_16x16x32_bf16 v[90:93], v[138:141], v[212:215], v[90:93]
	v_mfma_f32_16x16x32_bf16 v[78:81], v[130:133], v[220:223], v[78:81]
	v_mfma_f32_16x16x32_bf16 v[74:77], v[138:141], v[220:223], v[74:77]
	v_mfma_f32_16x16x32_bf16 v[126:129], v[134:137], v[200:203], v[126:129]
	v_mfma_f32_16x16x32_bf16 v[122:125], v[142:145], v[200:203], v[122:125]
	v_mfma_f32_16x16x32_bf16 v[110:113], v[134:137], v[208:211], v[110:113]
	v_mfma_f32_16x16x32_bf16 v[106:109], v[142:145], v[208:211], v[106:109]
	v_mfma_f32_16x16x32_bf16 v[94:97], v[134:137], v[216:219], v[94:97]
	v_mfma_f32_16x16x32_bf16 v[90:93], v[142:145], v[216:219], v[90:93]
	v_mfma_f32_16x16x32_bf16 v[78:81], v[134:137], v[224:227], v[78:81]
	v_mfma_f32_16x16x32_bf16 v[74:77], v[142:145], v[224:227], v[74:77]
	s_setprio 0
	s_setprio 1
	v_mfma_f32_16x16x32_bf16 v[118:121], v[168:171], v[196:199], v[118:121]
	v_mfma_f32_16x16x32_bf16 v[114:117], v[188:191], v[196:199], v[114:117]
	v_mfma_f32_16x16x32_bf16 v[102:105], v[168:171], v[204:207], v[102:105]
	v_mfma_f32_16x16x32_bf16 v[98:101], v[188:191], v[204:207], v[98:101]
	v_mfma_f32_16x16x32_bf16 v[86:89], v[168:171], v[212:215], v[86:89]
	v_mfma_f32_16x16x32_bf16 v[82:85], v[188:191], v[212:215], v[82:85]
	v_mfma_f32_16x16x32_bf16 v[70:73], v[168:171], v[220:223], v[70:73]
	v_mfma_f32_16x16x32_bf16 v[66:69], v[188:191], v[220:223], v[66:69]
	v_mfma_f32_16x16x32_bf16 v[118:121], v[184:187], v[200:203], v[118:121]
	v_mfma_f32_16x16x32_bf16 v[114:117], v[192:195], v[200:203], v[114:117]
	v_mfma_f32_16x16x32_bf16 v[102:105], v[184:187], v[208:211], v[102:105]
	v_mfma_f32_16x16x32_bf16 v[98:101], v[192:195], v[208:211], v[98:101]
	s_barrier
	v_mfma_f32_16x16x32_bf16 v[86:89], v[184:187], v[216:219], v[86:89]
	v_mfma_f32_16x16x32_bf16 v[82:85], v[192:195], v[216:219], v[82:85]
	v_mfma_f32_16x16x32_bf16 v[70:73], v[184:187], v[224:227], v[70:73]
	v_mfma_f32_16x16x32_bf16 v[66:69], v[192:195], v[224:227], v[66:69]
	s_setprio 0
	s_add_i32 s68, s39, s26
	v_lshl_add_u64 v[230:231], s[22:23], 0, v[150:151]
	s_mov_b32 m0, s68
	ds_read_b128 v[196:199], v178 offset:16384
	ds_read_b128 v[200:203], v178 offset:17408
	ds_read_b128 v[204:207], v178 offset:18432
	ds_read_b128 v[208:211], v178 offset:19456
	ds_read_b128 v[212:215], v178 offset:20480
	ds_read_b128 v[216:219], v178 offset:21504
	ds_read_b128 v[220:223], v178 offset:22528
	ds_read_b128 v[224:227], v178 offset:23552
	global_load_lds_dwordx4 v[230:231], off
	s_add_i32 m0, s68, 0x2000
	s_add_u32 s68, s22, 0x80000
	v_lshl_add_u64 v[232:233], s[22:23], 0, v[154:155]
	s_addc_u32 s69, s23, 0
	s_add_i32 s70, s40, s26
	global_load_lds_dwordx4 v[232:233], off
	v_lshl_add_u64 v[234:235], s[68:69], 0, v[150:151]
	s_mov_b32 m0, s70
	v_lshl_add_u64 v[236:237], s[24:25], 0, v[152:153]
	global_load_lds_dwordx4 v[234:235], off
	v_lshl_add_u64 v[234:235], s[68:69], 0, v[154:155]
	s_add_i32 m0, s70, 0x2000
	s_nop 0
	global_load_lds_dwordx4 v[234:235], off
	v_lshl_add_u64 v[234:235], s[24:25], 0, v[148:149]
	s_mov_b32 m0, s27
	s_nop 0
	global_load_lds_dwordx4 v[234:235], off
	s_mov_b32 m0, s28
	s_nop 0
	global_load_lds_dwordx4 v[236:237], off
	s_waitcnt vmcnt(8)
	s_waitcnt lgkmcnt(0)
	s_setprio 1
	s_barrier
; #define PG8_STAGE(bufoff, gbase, voff) do { _Pragma("unroll") for (int _i = 0; _i < 2; ++_i) \
;         __builtin_amdgcn_global_load_lds((const unsigned*)((const char*)(gbase) + (voff)[_i]), (PG8_LAS unsigned*)(lds + (bufoff) + ldsw + _i * 8192), 16, 0, 0); } while (0)
; #define PG8_WAIT_V(n) asm volatile("s_waitcnt vmcnt(" #n ")" ::: "memory")
; #define PG8_WAIT_L(n) asm volatile("s_waitcnt lgkmcnt(" #n ")" ::: "memory")
; #define PG8_BAR __builtin_amdgcn_s_barrier()
; #define PG8_SCHED __builtin_amdgcn_sched_barrier(0)
; template <class Epi, class Sched, bool ALIGN_EPI = true, bool SP2 = true>
; __device__ __forceinline__ void gemm_phase(PG8_LAS unsigned char* lds, const int K  , const Sched& S, const Epi& E) {
;     ...
;             PG8_WAIT_V(8); PG8_WAIT_L(0); PG8_BAR; PG8_MMA(1, 0, At, B0); PG8_MMA(1, 1, At, B1); PG8_BAR; PG8_SCHED;
;             PG8_LDB(B0, 1, 0); PG8_LDB(B1, 1, 1); PG8_SCHED; PG8_LDA(At, 1, 0); PG8_STAGE(PG8_SA(0, 1), a2 + hstep, voffA);
;             PG8_WAIT_V(8); PG8_WAIT_L(0); PG8_BAR; PG8_MMA(0, 0, At, B0); PG8_MMA(0, 1, At, B1); PG8_BAR; PG8_SCHED;
	v_mfma_f32_16x16x32_bf16 v[62:65], v[130:133], v[196:199], v[62:65]
	v_mfma_f32_16x16x32_bf16 v[58:61], v[138:141], v[196:199], v[58:61]
	v_mfma_f32_16x16x32_bf16 v[46:49], v[130:133], v[204:207], v[46:49]
	v_mfma_f32_16x16x32_bf16 v[42:45], v[138:141], v[204:207], v[42:45]
	v_mfma_f32_16x16x32_bf16 v[30:33], v[130:133], v[212:215], v[30:33]
	v_mfma_f32_16x16x32_bf16 v[26:29], v[138:141], v[212:215], v[26:29]
	v_mfma_f32_16x16x32_bf16 v[14:17], v[130:133], v[220:223], v[14:17]
	v_mfma_f32_16x16x32_bf16 v[10:13], v[138:141], v[220:223], v[10:13]
	v_mfma_f32_16x16x32_bf16 v[62:65], v[134:137], v[200:203], v[62:65]
	v_mfma_f32_16x16x32_bf16 v[58:61], v[142:145], v[200:203], v[58:61]
	v_mfma_f32_16x16x32_bf16 v[46:49], v[134:137], v[208:211], v[46:49]
	v_mfma_f32_16x16x32_bf16 v[42:45], v[142:145], v[208:211], v[42:45]
	v_mfma_f32_16x16x32_bf16 v[30:33], v[134:137], v[216:219], v[30:33]
	v_mfma_f32_16x16x32_bf16 v[26:29], v[142:145], v[216:219], v[26:29]
	v_mfma_f32_16x16x32_bf16 v[14:17], v[134:137], v[224:227], v[14:17]
	v_mfma_f32_16x16x32_bf16 v[10:13], v[142:145], v[224:227], v[10:13]
	s_setprio 0
	s_setprio 1
	v_mfma_f32_16x16x32_bf16 v[54:57], v[168:171], v[196:199], v[54:57]
	v_mfma_f32_16x16x32_bf16 v[50:53], v[188:191], v[196:199], v[50:53]
	v_mfma_f32_16x16x32_bf16 v[38:41], v[168:171], v[204:207], v[38:41]
	v_mfma_f32_16x16x32_bf16 v[34:37], v[188:191], v[204:207], v[34:37]
	v_mfma_f32_16x16x32_bf16 v[22:25], v[168:171], v[212:215], v[22:25]
	v_mfma_f32_16x16x32_bf16 v[18:21], v[188:191], v[212:215], v[18:21]
	v_mfma_f32_16x16x32_bf16 v[6:9], v[168:171], v[220:223], v[6:9]
	v_mfma_f32_16x16x32_bf16 v[2:5], v[188:191], v[220:223], v[2:5]
	v_mfma_f32_16x16x32_bf16 v[54:57], v[184:187], v[200:203], v[54:57]
	v_mfma_f32_16x16x32_bf16 v[50:53], v[192:195], v[200:203], v[50:53]
	v_mfma_f32_16x16x32_bf16 v[38:41], v[184:187], v[208:211], v[38:41]
	v_mfma_f32_16x16x32_bf16 v[34:37], v[192:195], v[208:211], v[34:37]
	s_barrier
	v_mfma_f32_16x16x32_bf16 v[22:25], v[184:187], v[216:219], v[22:25]
	v_mfma_f32_16x16x32_bf16 v[18:21], v[192:195], v[216:219], v[18:21]
	v_mfma_f32_16x16x32_bf16 v[6:9], v[184:187], v[224:227], v[6:9]
	v_mfma_f32_16x16x32_bf16 v[2:5], v[192:195], v[224:227], v[2:5]
	s_setprio 0
	s_add_i32 s68, 0, 0x18000
	s_add_i32 s69, 0, 0x1c000
	v_add_u32_e32 v142, s68, v172
	v_add_u32_e32 v192, s69, v172
	ds_read_b128 v[130:133], v142
	ds_read_b128 v[134:137], v142 offset:1024
	ds_read_b128 v[138:141], v142 offset:2048
	ds_read_b128 v[142:145], v142 offset:3072
	ds_read_b128 v[168:171], v192
	ds_read_b128 v[184:187], v192 offset:1024
	ds_read_b128 v[188:191], v192 offset:2048
	ds_read_b128 v[192:195], v192 offset:3072
	s_add_u32 s24, s24, 0x80000
	s_addc_u32 s25, s25, 0
	s_mov_b32 m0, s29
	v_lshl_add_u64 v[238:239], s[24:25], 0, v[148:149]
	ds_read_b128 v[196:199], v178 offset:32768
	ds_read_b128 v[200:203], v178 offset:33792
	ds_read_b128 v[204:207], v178 offset:34816
	ds_read_b128 v[208:211], v178 offset:35840
	ds_read_b128 v[212:215], v178 offset:36864
	ds_read_b128 v[216:219], v178 offset:37888
	ds_read_b128 v[220:223], v178 offset:38912
	ds_read_b128 v[224:227], v178 offset:39936
	global_load_lds_dwordx4 v[238:239], off
	v_lshl_add_u64 v[238:239], s[24:25], 0, v[152:153]
	s_mov_b32 m0, s30
	s_nop 0
	global_load_lds_dwordx4 v[238:239], off
	s_waitcnt vmcnt(8)
	s_waitcnt lgkmcnt(0)
	s_setprio 1
	s_barrier
	v_mfma_f32_16x16x32_bf16 v[126:129], v[130:133], v[196:199], v[126:129]
	v_mfma_f32_16x16x32_bf16 v[122:125], v[138:141], v[196:199], v[122:125]
	v_mfma_f32_16x16x32_bf16 v[110:113], v[130:133], v[204:207], v[110:113]
	v_mfma_f32_16x16x32_bf16 v[106:109], v[138:141], v[204:207], v[106:109]
	v_mfma_f32_16x16x32_bf16 v[94:97], v[130:133], v[212:215], v[94:97]
	v_mfma_f32_16x16x32_bf16 v[90:93], v[138:141], v[212:215], v[90:93]
	v_mfma_f32_16x16x32_bf16 v[78:81], v[130:133], v[220:223], v[78:81]
	v_mfma_f32_16x16x32_bf16 v[74:77], v[138:141], v[220:223], v[74:77]
	v_mfma_f32_16x16x32_bf16 v[126:129], v[134:137], v[200:203], v[126:129]
	v_mfma_f32_16x16x32_bf16 v[122:125], v[142:145], v[200:203], v[122:125]
	v_mfma_f32_16x16x32_bf16 v[110:113], v[134:137], v[208:211], v[110:113]
	v_mfma_f32_16x16x32_bf16 v[106:109], v[142:145], v[208:211], v[106:109]
	v_mfma_f32_16x16x32_bf16 v[94:97], v[134:137], v[216:219], v[94:97]
	v_mfma_f32_16x16x32_bf16 v[90:93], v[142:145], v[216:219], v[90:93]
	v_mfma_f32_16x16x32_bf16 v[78:81], v[134:137], v[224:227], v[78:81]
	v_mfma_f32_16x16x32_bf16 v[74:77], v[142:145], v[224:227], v[74:77]
	s_setprio 0
	s_setprio 1
	v_mfma_f32_16x16x32_bf16 v[118:121], v[168:171], v[196:199], v[118:121]
	v_mfma_f32_16x16x32_bf16 v[114:117], v[188:191], v[196:199], v[114:117]
	v_mfma_f32_16x16x32_bf16 v[102:105], v[168:171], v[204:207], v[102:105]
	v_mfma_f32_16x16x32_bf16 v[98:101], v[188:191], v[204:207], v[98:101]
	v_mfma_f32_16x16x32_bf16 v[86:89], v[168:171], v[212:215], v[86:89]
	v_mfma_f32_16x16x32_bf16 v[82:85], v[188:191], v[212:215], v[82:85]
	v_mfma_f32_16x16x32_bf16 v[70:73], v[168:171], v[220:223], v[70:73]
	v_mfma_f32_16x16x32_bf16 v[66:69], v[188:191], v[220:223], v[66:69]
	v_mfma_f32_16x16x32_bf16 v[118:121], v[184:187], v[200:203], v[118:121]
	v_mfma_f32_16x16x32_bf16 v[114:117], v[192:195], v[200:203], v[114:117]
	v_mfma_f32_16x16x32_bf16 v[102:105], v[184:187], v[208:211], v[102:105]
	v_mfma_f32_16x16x32_bf16 v[98:101], v[192:195], v[208:211], v[98:101]
	s_barrier
; #define PG8_STAGE(bufoff, gbase, voff) do { _Pragma("unroll") for (int _i = 0; _i < 2; ++_i) \
;         __builtin_amdgcn_global_load_lds((const unsigned*)((const char*)(gbase) + (voff)[_i]), (PG8_LAS unsigned*)(lds + (bufoff) + ldsw + _i * 8192), 16, 0, 0); } while (0)
; #define PG8_WAIT_V(n) asm volatile("s_waitcnt vmcnt(" #n ")" ::: "memory")
; #define PG8_WAIT_L(n) asm volatile("s_waitcnt lgkmcnt(" #n ")" ::: "memory")
; #define PG8_BAR __builtin_amdgcn_s_barrier()
; #define PG8_SCHED __builtin_amdgcn_sched_barrier(0)
; template <class Epi, class Sched, bool ALIGN_EPI = true, bool SP2 = true>
; __device__ __forceinline__ void gemm_phase(PG8_LAS unsigned char* lds, const int K  , const Sched& S, const Epi& E) {
;     ...
;             PG8_WAIT_V(8); PG8_WAIT_L(0); PG8_BAR; PG8_MMA(0, 0, At, B0); PG8_MMA(0, 1, At, B1); PG8_BAR; PG8_SCHED;
;             PG8_LDA(At, 1, 1); PG8_STAGE(PG8_SB(1, 0), b3, voffB); PG8_STAGE(PG8_SB(1, 1), b3 + hstep, voffB); PG8_STAGE(PG8_SA(1, 0), a3, voffA);
;             PG8_WAIT_V(8); PG8_WAIT_L(0); PG8_BAR; PG8_MMA(1, 0, At, B0); PG8_MMA(1, 1, At, B1); PG8_BAR; PG8_SCHED;
	v_mfma_f32_16x16x32_bf16 v[86:89], v[184:187], v[216:219], v[86:89]
	v_mfma_f32_16x16x32_bf16 v[82:85], v[192:195], v[216:219], v[82:85]
	v_mfma_f32_16x16x32_bf16 v[70:73], v[184:187], v[224:227], v[70:73]
	v_mfma_f32_16x16x32_bf16 v[66:69], v[192:195], v[224:227], v[66:69]
	s_setprio 0
	s_add_i32 s24, s68, s26
	v_lshl_add_u64 v[230:231], v[230:231], 0, s[4:5]
	s_mov_b32 m0, s24
	ds_read_b128 v[196:199], v178 offset:49152
	ds_read_b128 v[200:203], v178 offset:50176
	ds_read_b128 v[204:207], v178 offset:51200
	ds_read_b128 v[208:211], v178 offset:52224
	ds_read_b128 v[212:215], v178 offset:53248
	ds_read_b128 v[216:219], v178 offset:54272
	ds_read_b128 v[220:223], v178 offset:55296
	ds_read_b128 v[224:227], v178 offset:56320
	global_load_lds_dwordx4 v[230:231], off
	s_add_i32 m0, s24, 0x2000
	s_add_u32 s22, s22, 0x80080
	v_lshl_add_u64 v[230:231], v[232:233], 0, s[4:5]
	s_addc_u32 s23, s23, 0
	s_add_i32 s24, s69, s26
	global_load_lds_dwordx4 v[230:231], off
	v_lshl_add_u64 v[230:231], s[22:23], 0, v[150:151]
	s_mov_b32 m0, s24
	s_nop 0
	global_load_lds_dwordx4 v[230:231], off
	v_lshl_add_u64 v[230:231], s[22:23], 0, v[154:155]
	s_add_i32 m0, s24, 0x2000
	s_nop 0
	global_load_lds_dwordx4 v[230:231], off
	v_lshl_add_u64 v[230:231], v[234:235], 0, s[4:5]
	s_mov_b32 m0, s35
	s_nop 0
	global_load_lds_dwordx4 v[230:231], off
	v_lshl_add_u64 v[230:231], v[236:237], 0, s[4:5]
	s_mov_b32 m0, s36
	s_nop 0
	global_load_lds_dwordx4 v[230:231], off
	s_waitcnt vmcnt(8)
	s_waitcnt lgkmcnt(0)
	s_setprio 1
	s_barrier
	v_mfma_f32_16x16x32_bf16 v[62:65], v[130:133], v[196:199], v[62:65]
	v_mfma_f32_16x16x32_bf16 v[58:61], v[138:141], v[196:199], v[58:61]
	v_mfma_f32_16x16x32_bf16 v[46:49], v[130:133], v[204:207], v[46:49]
	v_mfma_f32_16x16x32_bf16 v[42:45], v[138:141], v[204:207], v[42:45]
	v_mfma_f32_16x16x32_bf16 v[30:33], v[130:133], v[212:215], v[30:33]
	v_mfma_f32_16x16x32_bf16 v[26:29], v[138:141], v[212:215], v[26:29]
	v_mfma_f32_16x16x32_bf16 v[14:17], v[130:133], v[220:223], v[14:17]
	v_mfma_f32_16x16x32_bf16 v[10:13], v[138:141], v[220:223], v[10:13]
	v_mfma_f32_16x16x32_bf16 v[62:65], v[134:137], v[200:203], v[62:65]
	v_mfma_f32_16x16x32_bf16 v[58:61], v[142:145], v[200:203], v[58:61]
	v_mfma_f32_16x16x32_bf16 v[46:49], v[134:137], v[208:211], v[46:49]
	v_mfma_f32_16x16x32_bf16 v[42:45], v[142:145], v[208:211], v[42:45]
	v_mfma_f32_16x16x32_bf16 v[30:33], v[134:137], v[216:219], v[30:33]
	v_mfma_f32_16x16x32_bf16 v[26:29], v[142:145], v[216:219], v[26:29]
	v_mfma_f32_16x16x32_bf16 v[14:17], v[134:137], v[224:227], v[14:17]
	v_mfma_f32_16x16x32_bf16 v[10:13], v[142:145], v[224:227], v[10:13]
	s_setprio 0
	s_setprio 1
	v_mfma_f32_16x16x32_bf16 v[54:57], v[168:171], v[196:199], v[54:57]
	v_mfma_f32_16x16x32_bf16 v[50:53], v[188:191], v[196:199], v[50:53]
	v_mfma_f32_16x16x32_bf16 v[38:41], v[168:171], v[204:207], v[38:41]
	v_mfma_f32_16x16x32_bf16 v[34:37], v[188:191], v[204:207], v[34:37]
	v_mfma_f32_16x16x32_bf16 v[22:25], v[168:171], v[212:215], v[22:25]
	v_mfma_f32_16x16x32_bf16 v[18:21], v[188:191], v[212:215], v[18:21]
	v_mfma_f32_16x16x32_bf16 v[6:9], v[168:171], v[220:223], v[6:9]
	v_mfma_f32_16x16x32_bf16 v[2:5], v[188:191], v[220:223], v[2:5]
	v_mfma_f32_16x16x32_bf16 v[54:57], v[184:187], v[200:203], v[54:57]
	v_mfma_f32_16x16x32_bf16 v[50:53], v[192:195], v[200:203], v[50:53]
	v_mfma_f32_16x16x32_bf16 v[38:41], v[184:187], v[208:211], v[38:41]
	v_mfma_f32_16x16x32_bf16 v[34:37], v[192:195], v[208:211], v[34:37]
	s_barrier
	v_mfma_f32_16x16x32_bf16 v[22:25], v[184:187], v[216:219], v[22:25]
	v_mfma_f32_16x16x32_bf16 v[18:21], v[192:195], v[216:219], v[18:21]
	v_mfma_f32_16x16x32_bf16 v[6:9], v[184:187], v[224:227], v[6:9]
	v_mfma_f32_16x16x32_bf16 v[2:5], v[192:195], v[224:227], v[2:5]
	s_setprio 0
	s_add_i32 s51, s51, 2
	s_add_u32 s0, s0, 0x100
	s_addc_u32 s1, s1, 0
	s_add_u32 s49, s49, 0x100
	s_addc_u32 s50, s50, 0
	s_cmp_gt_u32 s51, 29
	s_cbranch_scc0 .LBB0_1847
	s_and_b64 vcc, exec, s[8:9]
	s_cbranch_vccz .LBB0_1850
	s_barrier

; #define PG8_STAGE(bufoff, gbase, voff) do { _Pragma("unroll") for (int _i = 0; _i < 2; ++_i) \
;         __builtin_amdgcn_global_load_lds((const unsigned*)((const char*)(gbase) + (voff)[_i]), (PG8_LAS unsigned*)(lds + (bufoff) + ldsw + _i * 8192), 16, 0, 0); } while (0)
; #define PG8_WAIT_V(n) asm volatile("s_waitcnt vmcnt(" #n ")" ::: "memory")
; #define PG8_WAIT_L(n) asm volatile("s_waitcnt lgkmcnt(" #n ")" ::: "memory")
; #define PG8_BAR __builtin_amdgcn_s_barrier()
; #define PG8_SCHED __builtin_amdgcn_sched_barrier(0)
; template <class Epi, class Sched, bool ALIGN_EPI = true, bool SP2 = true>
; __device__ __forceinline__ void gemm_phase(PG8_LAS unsigned char* lds, const int K  , const Sched& S, const Epi& E) {
;     ...
;             const char* a1 = cA + (size_t)(t + 1) * kstep;
;             const char* a2 = last ? nA : cA + (size_t)(t + 2) * kstep; const char* b2 = last ? nB : cB + (size_t)(t + 2) * kstep;
;             const char* a3 = a2 + kstep; const char* b3 = b2 + kstep;
;             if constexpr (SP2) {
;             PG8_LDB(B0, 0, 0); PG8_LDB(B1, 0, 1); PG8_SCHED; PG8_LDA(At, 0, 0); PG8_STAGE(PG8_SA(1, 1), a1 + hstep, voffA);
;             PG8_WAIT_V(8); PG8_WAIT_L(0); PG8_BAR; PG8_MMA(0, 0, At, B0); PG8_MMA(0, 1, At, B1); PG8_BAR; PG8_SCHED;
;             PG8_LDA(At, 0, 1); PG8_STAGE(PG8_SB(0, 0), b2, voffB); PG8_STAGE(PG8_SB(0, 1), b2 + hstep, voffB); PG8_STAGE(PG8_SA(0, 0), a2, voffA);
;             PG8_WAIT_V(8); PG8_WAIT_L(0); PG8_BAR; PG8_MMA(1, 0, At, B0); PG8_MMA(1, 1, At, B1); PG8_BAR; PG8_SCHED;
.LBB0_2296:
	ds_read_b128 v[130:133], v203
	ds_read_b128 v[134:137], v203 offset:1024
	ds_read_b128 v[138:141], v203 offset:2048
	ds_read_b128 v[142:145], v203 offset:3072
	ds_read_b128 v[146:149], v204
	ds_read_b128 v[150:153], v204 offset:1024
	ds_read_b128 v[154:157], v204 offset:2048
	ds_read_b128 v[158:161], v204 offset:3072
	s_add_u32 s22, s20, 0xfff80080
	s_addc_u32 s23, s21, -1
	s_cmp_eq_u32 s54, 28
	s_cselect_b32 s25, s13, s23
	s_cselect_b32 s24, s50, s22
	s_cselect_b32 s23, s11, s53
	s_cselect_b32 s22, s51, s52
	v_lshl_add_u64 v[198:199], s[20:21], 0, v[190:191]
	s_add_i32 m0, s19, 0xc000
	ds_read_b128 v[162:165], v205
	ds_read_b128 v[166:169], v205 offset:1024
	ds_read_b128 v[170:173], v205 offset:2048
	ds_read_b128 v[174:177], v205 offset:3072
	ds_read_b128 v[178:181], v205 offset:4096
	ds_read_b128 v[206:209], v205 offset:5120
	ds_read_b128 v[210:213], v205 offset:6144
	ds_read_b128 v[214:217], v205 offset:7168
	global_load_lds_dwordx4 v[198:199], off
	v_lshl_add_u64 v[198:199], s[20:21], 0, v[192:193]
	s_add_i32 m0, s19, 0xe000
	s_nop 0
	global_load_lds_dwordx4 v[198:199], off
	s_waitcnt vmcnt(8)
	s_waitcnt lgkmcnt(0)
	s_setprio 1
	s_barrier
	v_mfma_f32_16x16x32_bf16 v[126:129], v[130:133], v[162:165], v[126:129]
	v_mfma_f32_16x16x32_bf16 v[122:125], v[138:141], v[162:165], v[122:125]
	v_mfma_f32_16x16x32_bf16 v[114:117], v[130:133], v[170:173], v[114:117]
	v_mfma_f32_16x16x32_bf16 v[106:109], v[138:141], v[170:173], v[106:109]
	v_mfma_f32_16x16x32_bf16 v[98:101], v[130:133], v[178:181], v[98:101]
	v_mfma_f32_16x16x32_bf16 v[90:93], v[138:141], v[178:181], v[90:93]
	v_mfma_f32_16x16x32_bf16 v[82:85], v[130:133], v[210:213], v[82:85]
	v_mfma_f32_16x16x32_bf16 v[74:77], v[138:141], v[210:213], v[74:77]
	v_mfma_f32_16x16x32_bf16 v[126:129], v[134:137], v[166:169], v[126:129]
	v_mfma_f32_16x16x32_bf16 v[122:125], v[142:145], v[166:169], v[122:125]
	v_mfma_f32_16x16x32_bf16 v[114:117], v[134:137], v[174:177], v[114:117]
	v_mfma_f32_16x16x32_bf16 v[106:109], v[142:145], v[174:177], v[106:109]
	v_mfma_f32_16x16x32_bf16 v[98:101], v[134:137], v[206:209], v[98:101]
	v_mfma_f32_16x16x32_bf16 v[90:93], v[142:145], v[206:209], v[90:93]
	v_mfma_f32_16x16x32_bf16 v[82:85], v[134:137], v[214:217], v[82:85]
	v_mfma_f32_16x16x32_bf16 v[74:77], v[142:145], v[214:217], v[74:77]
	s_setprio 0
	s_setprio 1
	v_mfma_f32_16x16x32_bf16 v[118:121], v[146:149], v[162:165], v[118:121]
	v_mfma_f32_16x16x32_bf16 v[110:113], v[154:157], v[162:165], v[110:113]
	v_mfma_f32_16x16x32_bf16 v[102:105], v[146:149], v[170:173], v[102:105]
	v_mfma_f32_16x16x32_bf16 v[94:97], v[154:157], v[170:173], v[94:97]
	v_mfma_f32_16x16x32_bf16 v[86:89], v[146:149], v[178:181], v[86:89]
	v_mfma_f32_16x16x32_bf16 v[78:81], v[154:157], v[178:181], v[78:81]
	v_mfma_f32_16x16x32_bf16 v[70:73], v[146:149], v[210:213], v[70:73]
	v_mfma_f32_16x16x32_bf16 v[66:69], v[154:157], v[210:213], v[66:69]
	v_mfma_f32_16x16x32_bf16 v[118:121], v[150:153], v[166:169], v[118:121]
	v_mfma_f32_16x16x32_bf16 v[110:113], v[158:161], v[166:169], v[110:113]
	v_mfma_f32_16x16x32_bf16 v[102:105], v[150:153], v[174:177], v[102:105]
	v_mfma_f32_16x16x32_bf16 v[94:97], v[158:161], v[174:177], v[94:97]
	s_barrier
	v_mfma_f32_16x16x32_bf16 v[86:89], v[150:153], v[206:209], v[86:89]
	v_mfma_f32_16x16x32_bf16 v[78:81], v[158:161], v[206:209], v[78:81]
	v_mfma_f32_16x16x32_bf16 v[70:73], v[150:153], v[214:217], v[70:73]
	v_mfma_f32_16x16x32_bf16 v[66:69], v[158:161], v[214:217], v[66:69]
	s_setprio 0
	s_add_i32 s55, s42, s29
	v_lshl_add_u64 v[198:199], s[22:23], 0, v[184:185]
	s_mov_b32 m0, s55
	ds_read_b128 v[162:165], v205 offset:16384
	ds_read_b128 v[166:169], v205 offset:17408
	ds_read_b128 v[170:173], v205 offset:18432
	ds_read_b128 v[174:177], v205 offset:19456
	ds_read_b128 v[178:181], v205 offset:20480
	ds_read_b128 v[206:209], v205 offset:21504
	ds_read_b128 v[210:213], v205 offset:22528
	ds_read_b128 v[214:217], v205 offset:23552
	global_load_lds_dwordx4 v[198:199], off
	s_add_i32 m0, s55, 0x2000
	s_add_u32 s56, s22, 0x80000
	v_lshl_add_u64 v[218:219], s[22:23], 0, v[188:189]
	s_addc_u32 s57, s23, 0
	s_add_i32 s55, s43, s29
	global_load_lds_dwordx4 v[218:219], off
	v_lshl_add_u64 v[220:221], s[56:57], 0, v[184:185]
	s_mov_b32 m0, s55
	v_lshl_add_u64 v[222:223], s[24:25], 0, v[186:187]
	global_load_lds_dwordx4 v[220:221], off
	v_lshl_add_u64 v[220:221], s[56:57], 0, v[188:189]
	s_add_i32 m0, s55, 0x2000
	s_nop 0
	global_load_lds_dwordx4 v[220:221], off
	v_lshl_add_u64 v[220:221], s[24:25], 0, v[182:183]
	s_mov_b32 m0, s19
	s_nop 0
	global_load_lds_dwordx4 v[220:221], off
	s_mov_b32 m0, s30
	s_nop 0
	global_load_lds_dwordx4 v[222:223], off
	s_waitcnt vmcnt(8)
	s_waitcnt lgkmcnt(0)
	s_setprio 1
	s_barrier
; #define PG8_STAGE(bufoff, gbase, voff) do { _Pragma("unroll") for (int _i = 0; _i < 2; ++_i) \
;         __builtin_amdgcn_global_load_lds((const unsigned*)((const char*)(gbase) + (voff)[_i]), (PG8_LAS unsigned*)(lds + (bufoff) + ldsw + _i * 8192), 16, 0, 0); } while (0)
; #define PG8_WAIT_V(n) asm volatile("s_waitcnt vmcnt(" #n ")" ::: "memory")
; #define PG8_WAIT_L(n) asm volatile("s_waitcnt lgkmcnt(" #n ")" ::: "memory")
; #define PG8_BAR __builtin_amdgcn_s_barrier()
; #define PG8_SCHED __builtin_amdgcn_sched_barrier(0)
; template <class Epi, class Sched, bool ALIGN_EPI = true, bool SP2 = true>
; __device__ __forceinline__ void gemm_phase(PG8_LAS unsigned char* lds, const int K  , const Sched& S, const Epi& E) {
;     ...
;             PG8_WAIT_V(8); PG8_WAIT_L(0); PG8_BAR; PG8_MMA(1, 0, At, B0); PG8_MMA(1, 1, At, B1); PG8_BAR; PG8_SCHED;
;             PG8_LDB(B0, 1, 0); PG8_LDB(B1, 1, 1); PG8_SCHED; PG8_LDA(At, 1, 0); PG8_STAGE(PG8_SA(0, 1), a2 + hstep, voffA);
;             PG8_WAIT_V(8); PG8_WAIT_L(0); PG8_BAR; PG8_MMA(0, 0, At, B0); PG8_MMA(0, 1, At, B1); PG8_BAR; PG8_SCHED;
	v_mfma_f32_16x16x32_bf16 v[62:65], v[130:133], v[162:165], v[62:65]
	v_mfma_f32_16x16x32_bf16 v[58:61], v[138:141], v[162:165], v[58:61]
	v_mfma_f32_16x16x32_bf16 v[50:53], v[130:133], v[170:173], v[50:53]
	v_mfma_f32_16x16x32_bf16 v[42:45], v[138:141], v[170:173], v[42:45]
	v_mfma_f32_16x16x32_bf16 v[34:37], v[130:133], v[178:181], v[34:37]
	v_mfma_f32_16x16x32_bf16 v[26:29], v[138:141], v[178:181], v[26:29]
	v_mfma_f32_16x16x32_bf16 v[18:21], v[130:133], v[210:213], v[18:21]
	v_mfma_f32_16x16x32_bf16 v[10:13], v[138:141], v[210:213], v[10:13]
	v_mfma_f32_16x16x32_bf16 v[62:65], v[134:137], v[166:169], v[62:65]
	v_mfma_f32_16x16x32_bf16 v[58:61], v[142:145], v[166:169], v[58:61]
	v_mfma_f32_16x16x32_bf16 v[50:53], v[134:137], v[174:177], v[50:53]
	v_mfma_f32_16x16x32_bf16 v[42:45], v[142:145], v[174:177], v[42:45]
	v_mfma_f32_16x16x32_bf16 v[34:37], v[134:137], v[206:209], v[34:37]
	v_mfma_f32_16x16x32_bf16 v[26:29], v[142:145], v[206:209], v[26:29]
	v_mfma_f32_16x16x32_bf16 v[18:21], v[134:137], v[214:217], v[18:21]
	v_mfma_f32_16x16x32_bf16 v[10:13], v[142:145], v[214:217], v[10:13]
	s_setprio 0
	s_setprio 1
	v_mfma_f32_16x16x32_bf16 v[54:57], v[146:149], v[162:165], v[54:57]
	v_mfma_f32_16x16x32_bf16 v[46:49], v[154:157], v[162:165], v[46:49]
	v_mfma_f32_16x16x32_bf16 v[38:41], v[146:149], v[170:173], v[38:41]
	v_mfma_f32_16x16x32_bf16 v[30:33], v[154:157], v[170:173], v[30:33]
	v_mfma_f32_16x16x32_bf16 v[22:25], v[146:149], v[178:181], v[22:25]
	v_mfma_f32_16x16x32_bf16 v[14:17], v[154:157], v[178:181], v[14:17]
	v_mfma_f32_16x16x32_bf16 v[6:9], v[146:149], v[210:213], v[6:9]
	v_mfma_f32_16x16x32_bf16 v[2:5], v[154:157], v[210:213], v[2:5]
	v_mfma_f32_16x16x32_bf16 v[54:57], v[150:153], v[166:169], v[54:57]
	v_mfma_f32_16x16x32_bf16 v[46:49], v[158:161], v[166:169], v[46:49]
	v_mfma_f32_16x16x32_bf16 v[38:41], v[150:153], v[174:177], v[38:41]
	v_mfma_f32_16x16x32_bf16 v[30:33], v[158:161], v[174:177], v[30:33]
	s_barrier
	v_mfma_f32_16x16x32_bf16 v[22:25], v[150:153], v[206:209], v[22:25]
	v_mfma_f32_16x16x32_bf16 v[14:17], v[158:161], v[206:209], v[14:17]
	v_mfma_f32_16x16x32_bf16 v[6:9], v[150:153], v[214:217], v[6:9]
	v_mfma_f32_16x16x32_bf16 v[2:5], v[158:161], v[214:217], v[2:5]
	s_setprio 0
	s_add_i32 s55, 0, 0x18000
	s_add_i32 s56, 0, 0x1c000
	v_add_u32_e32 v142, s55, v201
	v_add_u32_e32 v158, s56, v201
	ds_read_b128 v[130:133], v142
	ds_read_b128 v[134:137], v142 offset:1024
	ds_read_b128 v[138:141], v142 offset:2048
	ds_read_b128 v[142:145], v142 offset:3072
	ds_read_b128 v[146:149], v158
	ds_read_b128 v[150:153], v158 offset:1024
	ds_read_b128 v[154:157], v158 offset:2048
	ds_read_b128 v[158:161], v158 offset:3072
	s_add_u32 s24, s24, 0x80000
	s_addc_u32 s25, s25, 0
	s_mov_b32 m0, s31
	v_lshl_add_u64 v[224:225], s[24:25], 0, v[182:183]
	ds_read_b128 v[162:165], v205 offset:32768
	ds_read_b128 v[166:169], v205 offset:33792
	ds_read_b128 v[170:173], v205 offset:34816
	ds_read_b128 v[174:177], v205 offset:35840
	ds_read_b128 v[178:181], v205 offset:36864
	ds_read_b128 v[206:209], v205 offset:37888
	ds_read_b128 v[210:213], v205 offset:38912
	ds_read_b128 v[214:217], v205 offset:39936
	global_load_lds_dwordx4 v[224:225], off
	v_lshl_add_u64 v[224:225], s[24:25], 0, v[186:187]
	s_mov_b32 m0, s33
	s_nop 0
	global_load_lds_dwordx4 v[224:225], off
	s_waitcnt vmcnt(8)
	s_waitcnt lgkmcnt(0)
	s_setprio 1
	s_barrier
	v_mfma_f32_16x16x32_bf16 v[126:129], v[130:133], v[162:165], v[126:129]
	v_mfma_f32_16x16x32_bf16 v[122:125], v[138:141], v[162:165], v[122:125]
	v_mfma_f32_16x16x32_bf16 v[114:117], v[130:133], v[170:173], v[114:117]
	v_mfma_f32_16x16x32_bf16 v[106:109], v[138:141], v[170:173], v[106:109]
	v_mfma_f32_16x16x32_bf16 v[98:101], v[130:133], v[178:181], v[98:101]
	v_mfma_f32_16x16x32_bf16 v[90:93], v[138:141], v[178:181], v[90:93]
	v_mfma_f32_16x16x32_bf16 v[82:85], v[130:133], v[210:213], v[82:85]
	v_mfma_f32_16x16x32_bf16 v[74:77], v[138:141], v[210:213], v[74:77]
	v_mfma_f32_16x16x32_bf16 v[126:129], v[134:137], v[166:169], v[126:129]
	v_mfma_f32_16x16x32_bf16 v[122:125], v[142:145], v[166:169], v[122:125]
	v_mfma_f32_16x16x32_bf16 v[114:117], v[134:137], v[174:177], v[114:117]
	v_mfma_f32_16x16x32_bf16 v[106:109], v[142:145], v[174:177], v[106:109]
	v_mfma_f32_16x16x32_bf16 v[98:101], v[134:137], v[206:209], v[98:101]
	v_mfma_f32_16x16x32_bf16 v[90:93], v[142:145], v[206:209], v[90:93]
	v_mfma_f32_16x16x32_bf16 v[82:85], v[134:137], v[214:217], v[82:85]
	v_mfma_f32_16x16x32_bf16 v[74:77], v[142:145], v[214:217], v[74:77]
	s_setprio 0
	s_setprio 1
	v_mfma_f32_16x16x32_bf16 v[118:121], v[146:149], v[162:165], v[118:121]
	v_mfma_f32_16x16x32_bf16 v[110:113], v[154:157], v[162:165], v[110:113]
	v_mfma_f32_16x16x32_bf16 v[102:105], v[146:149], v[170:173], v[102:105]
	v_mfma_f32_16x16x32_bf16 v[94:97], v[154:157], v[170:173], v[94:97]
	v_mfma_f32_16x16x32_bf16 v[86:89], v[146:149], v[178:181], v[86:89]
	v_mfma_f32_16x16x32_bf16 v[78:81], v[154:157], v[178:181], v[78:81]
	v_mfma_f32_16x16x32_bf16 v[70:73], v[146:149], v[210:213], v[70:73]
	v_mfma_f32_16x16x32_bf16 v[66:69], v[154:157], v[210:213], v[66:69]
	v_mfma_f32_16x16x32_bf16 v[118:121], v[150:153], v[166:169], v[118:121]
	v_mfma_f32_16x16x32_bf16 v[110:113], v[158:161], v[166:169], v[110:113]
	v_mfma_f32_16x16x32_bf16 v[102:105], v[150:153], v[174:177], v[102:105]
	v_mfma_f32_16x16x32_bf16 v[94:97], v[158:161], v[174:177], v[94:97]
	s_barrier
; #define PG8_STAGE(bufoff, gbase, voff) do { _Pragma("unroll") for (int _i = 0; _i < 2; ++_i) \
;         __builtin_amdgcn_global_load_lds((const unsigned*)((const char*)(gbase) + (voff)[_i]), (PG8_LAS unsigned*)(lds + (bufoff) + ldsw + _i * 8192), 16, 0, 0); } while (0)
; #define PG8_WAIT_V(n) asm volatile("s_waitcnt vmcnt(" #n ")" ::: "memory")
; #define PG8_WAIT_L(n) asm volatile("s_waitcnt lgkmcnt(" #n ")" ::: "memory")
; #define PG8_BAR __builtin_amdgcn_s_barrier()
; #define PG8_SCHED __builtin_amdgcn_sched_barrier(0)
; template <class Epi, class Sched, bool ALIGN_EPI = true, bool SP2 = true>
; __device__ __forceinline__ void gemm_phase(PG8_LAS unsigned char* lds, const int K  , const Sched& S, const Epi& E) {
;     ...
;             PG8_WAIT_V(8); PG8_WAIT_L(0); PG8_BAR; PG8_MMA(0, 0, At, B0); PG8_MMA(0, 1, At, B1); PG8_BAR; PG8_SCHED;
;             PG8_LDA(At, 1, 1); PG8_STAGE(PG8_SB(1, 0), b3, voffB); PG8_STAGE(PG8_SB(1, 1), b3 + hstep, voffB); PG8_STAGE(PG8_SA(1, 0), a3, voffA);
;             PG8_WAIT_V(8); PG8_WAIT_L(0); PG8_BAR; PG8_MMA(1, 0, At, B0); PG8_MMA(1, 1, At, B1); PG8_BAR; PG8_SCHED;
	v_mfma_f32_16x16x32_bf16 v[86:89], v[150:153], v[206:209], v[86:89]
	v_mfma_f32_16x16x32_bf16 v[78:81], v[158:161], v[206:209], v[78:81]
	v_mfma_f32_16x16x32_bf16 v[70:73], v[150:153], v[214:217], v[70:73]
	v_mfma_f32_16x16x32_bf16 v[66:69], v[158:161], v[214:217], v[66:69]
	s_setprio 0
	s_add_i32 s24, s55, s29
	v_lshl_add_u64 v[198:199], v[198:199], 0, s[6:7]
	s_mov_b32 m0, s24
	ds_read_b128 v[162:165], v205 offset:49152
	ds_read_b128 v[166:169], v205 offset:50176
	ds_read_b128 v[170:173], v205 offset:51200
	ds_read_b128 v[174:177], v205 offset:52224
	ds_read_b128 v[178:181], v205 offset:53248
	ds_read_b128 v[206:209], v205 offset:54272
	ds_read_b128 v[210:213], v205 offset:55296
	ds_read_b128 v[214:217], v205 offset:56320
	global_load_lds_dwordx4 v[198:199], off
	s_add_i32 m0, s24, 0x2000
	s_add_u32 s22, s22, 0x80080
	v_lshl_add_u64 v[198:199], v[218:219], 0, s[6:7]
	s_addc_u32 s23, s23, 0
	s_add_i32 s24, s56, s29
	global_load_lds_dwordx4 v[198:199], off
	v_lshl_add_u64 v[198:199], s[22:23], 0, v[184:185]
	s_mov_b32 m0, s24
	s_nop 0
	global_load_lds_dwordx4 v[198:199], off
	v_lshl_add_u64 v[198:199], s[22:23], 0, v[188:189]
	s_add_i32 m0, s24, 0x2000
	s_nop 0
	global_load_lds_dwordx4 v[198:199], off
	v_lshl_add_u64 v[198:199], v[220:221], 0, s[6:7]
	s_mov_b32 m0, s38
	s_nop 0
	global_load_lds_dwordx4 v[198:199], off
	v_lshl_add_u64 v[198:199], v[222:223], 0, s[6:7]
	s_mov_b32 m0, s39
	s_nop 0
	global_load_lds_dwordx4 v[198:199], off
	s_waitcnt vmcnt(8)
	s_waitcnt lgkmcnt(0)
	s_setprio 1
	s_barrier
	v_mfma_f32_16x16x32_bf16 v[62:65], v[130:133], v[162:165], v[62:65]
	v_mfma_f32_16x16x32_bf16 v[58:61], v[138:141], v[162:165], v[58:61]
	v_mfma_f32_16x16x32_bf16 v[50:53], v[130:133], v[170:173], v[50:53]
	v_mfma_f32_16x16x32_bf16 v[42:45], v[138:141], v[170:173], v[42:45]
	v_mfma_f32_16x16x32_bf16 v[34:37], v[130:133], v[178:181], v[34:37]
	v_mfma_f32_16x16x32_bf16 v[26:29], v[138:141], v[178:181], v[26:29]
	v_mfma_f32_16x16x32_bf16 v[18:21], v[130:133], v[210:213], v[18:21]
	v_mfma_f32_16x16x32_bf16 v[10:13], v[138:141], v[210:213], v[10:13]
	v_mfma_f32_16x16x32_bf16 v[62:65], v[134:137], v[166:169], v[62:65]
	v_mfma_f32_16x16x32_bf16 v[58:61], v[142:145], v[166:169], v[58:61]
	v_mfma_f32_16x16x32_bf16 v[50:53], v[134:137], v[174:177], v[50:53]
	v_mfma_f32_16x16x32_bf16 v[42:45], v[142:145], v[174:177], v[42:45]
	v_mfma_f32_16x16x32_bf16 v[34:37], v[134:137], v[206:209], v[34:37]
	v_mfma_f32_16x16x32_bf16 v[26:29], v[142:145], v[206:209], v[26:29]
	v_mfma_f32_16x16x32_bf16 v[18:21], v[134:137], v[214:217], v[18:21]
	v_mfma_f32_16x16x32_bf16 v[10:13], v[142:145], v[214:217], v[10:13]
	s_setprio 0
	s_setprio 1
	v_mfma_f32_16x16x32_bf16 v[54:57], v[146:149], v[162:165], v[54:57]
	v_mfma_f32_16x16x32_bf16 v[46:49], v[154:157], v[162:165], v[46:49]
	v_mfma_f32_16x16x32_bf16 v[38:41], v[146:149], v[170:173], v[38:41]
	v_mfma_f32_16x16x32_bf16 v[30:33], v[154:157], v[170:173], v[30:33]
	v_mfma_f32_16x16x32_bf16 v[22:25], v[146:149], v[178:181], v[22:25]
	v_mfma_f32_16x16x32_bf16 v[14:17], v[154:157], v[178:181], v[14:17]
	v_mfma_f32_16x16x32_bf16 v[6:9], v[146:149], v[210:213], v[6:9]
	v_mfma_f32_16x16x32_bf16 v[2:5], v[154:157], v[210:213], v[2:5]
	v_mfma_f32_16x16x32_bf16 v[54:57], v[150:153], v[166:169], v[54:57]
	v_mfma_f32_16x16x32_bf16 v[46:49], v[158:161], v[166:169], v[46:49]
	v_mfma_f32_16x16x32_bf16 v[38:41], v[150:153], v[174:177], v[38:41]
	v_mfma_f32_16x16x32_bf16 v[30:33], v[158:161], v[174:177], v[30:33]
	s_barrier
	v_mfma_f32_16x16x32_bf16 v[22:25], v[150:153], v[206:209], v[22:25]
	v_mfma_f32_16x16x32_bf16 v[14:17], v[158:161], v[206:209], v[14:17]
	v_mfma_f32_16x16x32_bf16 v[6:9], v[150:153], v[214:217], v[6:9]
	v_mfma_f32_16x16x32_bf16 v[2:5], v[158:161], v[214:217], v[2:5]
	s_setprio 0
	s_add_i32 s54, s54, 2
	s_add_u32 s20, s20, 0x100
	s_addc_u32 s21, s21, 0
	s_add_u32 s52, s52, 0x100
	s_addc_u32 s53, s53, 0
	s_cmp_gt_u32 s54, 29
	s_cbranch_scc0 .LBB0_2296
	s_and_b64 vcc, exec, s[8:9]
	s_cbranch_vccz .LBB0_2299
	s_barrier

; #define PG8_STAGE(bufoff, gbase, voff) do { _Pragma("unroll") for (int _i = 0; _i < 2; ++_i) \
;         __builtin_amdgcn_global_load_lds((const unsigned*)((const char*)(gbase) + (voff)[_i]), (PG8_LAS unsigned*)(lds + (bufoff) + ldsw + _i * 8192), 16, 0, 0); } while (0)
; #define PG8_WAIT_V(n) asm volatile("s_waitcnt vmcnt(" #n ")" ::: "memory")
; #define PG8_WAIT_L(n) asm volatile("s_waitcnt lgkmcnt(" #n ")" ::: "memory")
; #define PG8_BAR __builtin_amdgcn_s_barrier()
; #define PG8_SCHED __builtin_amdgcn_sched_barrier(0)
; template <class Epi, class Sched, bool ALIGN_EPI = true, bool SP2 = true>
; __device__ __forceinline__ void gemm_phase(PG8_LAS unsigned char* lds, const int K  , const Sched& S, const Epi& E) {
;     ...
;             const char* a1 = cA + (size_t)(t + 1) * kstep;
;             const char* a2 = last ? nA : cA + (size_t)(t + 2) * kstep; const char* b2 = last ? nB : cB + (size_t)(t + 2) * kstep;
;             const char* a3 = a2 + kstep; const char* b3 = b2 + kstep;
;             if constexpr (SP2) {
;             PG8_LDB(B0, 0, 0); PG8_LDB(B1, 0, 1); PG8_SCHED; PG8_LDA(At, 0, 0); PG8_STAGE(PG8_SA(1, 1), a1 + hstep, voffA);
;             PG8_WAIT_V(8); PG8_WAIT_L(0); PG8_BAR; PG8_MMA(0, 0, At, B0); PG8_MMA(0, 1, At, B1); PG8_BAR; PG8_SCHED;
;             PG8_LDA(At, 0, 1); PG8_STAGE(PG8_SB(0, 0), b2, voffB); PG8_STAGE(PG8_SB(0, 1), b2 + hstep, voffB); PG8_STAGE(PG8_SA(0, 0), a2, voffA);
;             PG8_WAIT_V(8); PG8_WAIT_L(0); PG8_BAR; PG8_MMA(1, 0, At, B0); PG8_MMA(1, 1, At, B1); PG8_BAR; PG8_SCHED;
.LBB0_2433:
	ds_read_b128 v[146:149], v152
	ds_read_b128 v[158:161], v152 offset:1024
	ds_read_b128 v[162:165], v152 offset:2048
	ds_read_b128 v[166:169], v152 offset:3072
	ds_read_b128 v[170:173], v153
	ds_read_b128 v[174:177], v153 offset:1024
	ds_read_b128 v[178:181], v153 offset:2048
	ds_read_b128 v[182:185], v153 offset:3072
	s_add_u32 s22, s20, 0xfff80080
	s_addc_u32 s23, s21, -1
	s_cmp_eq_u32 s48, 28
	s_cselect_b32 s25, s13, s23
	s_cselect_b32 s24, s44, s22
	s_cselect_b32 s23, s11, s47
	s_cselect_b32 s22, s45, s46
	v_lshl_add_u64 v[218:219], s[20:21], 0, v[138:139]
	s_add_i32 m0, s19, 0xc000
	ds_read_b128 v[186:189], v154
	ds_read_b128 v[190:193], v154 offset:1024
	ds_read_b128 v[194:197], v154 offset:2048
	ds_read_b128 v[198:201], v154 offset:3072
	ds_read_b128 v[202:205], v154 offset:4096
	ds_read_b128 v[206:209], v154 offset:5120
	ds_read_b128 v[210:213], v154 offset:6144
	ds_read_b128 v[214:217], v154 offset:7168
	global_load_lds_dwordx4 v[218:219], off
	v_lshl_add_u64 v[218:219], s[20:21], 0, v[140:141]
	s_add_i32 m0, s19, 0xe000
	s_nop 0
	global_load_lds_dwordx4 v[218:219], off
	s_waitcnt vmcnt(8)
	s_waitcnt lgkmcnt(0)
	s_setprio 1
	s_barrier
	v_mfma_f32_16x16x32_bf16 v[126:129], v[146:149], v[186:189], v[126:129]
	v_mfma_f32_16x16x32_bf16 v[118:121], v[162:165], v[186:189], v[118:121]
	v_mfma_f32_16x16x32_bf16 v[110:113], v[146:149], v[194:197], v[110:113]
	v_mfma_f32_16x16x32_bf16 v[102:105], v[162:165], v[194:197], v[102:105]
	v_mfma_f32_16x16x32_bf16 v[94:97], v[146:149], v[202:205], v[94:97]
	v_mfma_f32_16x16x32_bf16 v[86:89], v[162:165], v[202:205], v[86:89]
	v_mfma_f32_16x16x32_bf16 v[78:81], v[146:149], v[210:213], v[78:81]
	v_mfma_f32_16x16x32_bf16 v[70:73], v[162:165], v[210:213], v[70:73]
	v_mfma_f32_16x16x32_bf16 v[126:129], v[158:161], v[190:193], v[126:129]
	v_mfma_f32_16x16x32_bf16 v[118:121], v[166:169], v[190:193], v[118:121]
	v_mfma_f32_16x16x32_bf16 v[110:113], v[158:161], v[198:201], v[110:113]
	v_mfma_f32_16x16x32_bf16 v[102:105], v[166:169], v[198:201], v[102:105]
	v_mfma_f32_16x16x32_bf16 v[94:97], v[158:161], v[206:209], v[94:97]
	v_mfma_f32_16x16x32_bf16 v[86:89], v[166:169], v[206:209], v[86:89]
	v_mfma_f32_16x16x32_bf16 v[78:81], v[158:161], v[214:217], v[78:81]
	v_mfma_f32_16x16x32_bf16 v[70:73], v[166:169], v[214:217], v[70:73]
	s_setprio 0
	s_setprio 1
	v_mfma_f32_16x16x32_bf16 v[122:125], v[170:173], v[186:189], v[122:125]
	v_mfma_f32_16x16x32_bf16 v[114:117], v[178:181], v[186:189], v[114:117]
	v_mfma_f32_16x16x32_bf16 v[106:109], v[170:173], v[194:197], v[106:109]
	v_mfma_f32_16x16x32_bf16 v[98:101], v[178:181], v[194:197], v[98:101]
	v_mfma_f32_16x16x32_bf16 v[90:93], v[170:173], v[202:205], v[90:93]
	v_mfma_f32_16x16x32_bf16 v[82:85], v[178:181], v[202:205], v[82:85]
	v_mfma_f32_16x16x32_bf16 v[74:77], v[170:173], v[210:213], v[74:77]
	v_mfma_f32_16x16x32_bf16 v[66:69], v[178:181], v[210:213], v[66:69]
	v_mfma_f32_16x16x32_bf16 v[122:125], v[174:177], v[190:193], v[122:125]
	v_mfma_f32_16x16x32_bf16 v[114:117], v[182:185], v[190:193], v[114:117]
	v_mfma_f32_16x16x32_bf16 v[106:109], v[174:177], v[198:201], v[106:109]
	v_mfma_f32_16x16x32_bf16 v[98:101], v[182:185], v[198:201], v[98:101]
	s_barrier
	v_mfma_f32_16x16x32_bf16 v[90:93], v[174:177], v[206:209], v[90:93]
	v_mfma_f32_16x16x32_bf16 v[82:85], v[182:185], v[206:209], v[82:85]
	v_mfma_f32_16x16x32_bf16 v[74:77], v[174:177], v[214:217], v[74:77]
	v_mfma_f32_16x16x32_bf16 v[66:69], v[182:185], v[214:217], v[66:69]
	s_setprio 0
	s_add_i32 s49, s39, s28
	v_lshl_add_u64 v[218:219], s[22:23], 0, v[134:135]
	s_mov_b32 m0, s49
	ds_read_b128 v[186:189], v154 offset:16384
	ds_read_b128 v[190:193], v154 offset:17408
	ds_read_b128 v[194:197], v154 offset:18432
	ds_read_b128 v[198:201], v154 offset:19456
	ds_read_b128 v[202:205], v154 offset:20480
	ds_read_b128 v[206:209], v154 offset:21504
	ds_read_b128 v[210:213], v154 offset:22528
	ds_read_b128 v[214:217], v154 offset:23552
	global_load_lds_dwordx4 v[218:219], off
	s_add_i32 m0, s49, 0x2000
	s_add_u32 s50, s22, 0x80000
	v_lshl_add_u64 v[220:221], s[22:23], 0, v[130:131]
	s_addc_u32 s51, s23, 0
	s_add_i32 s49, s40, s28
	global_load_lds_dwordx4 v[220:221], off
	v_lshl_add_u64 v[222:223], s[50:51], 0, v[134:135]
	s_mov_b32 m0, s49
	v_lshl_add_u64 v[224:225], s[24:25], 0, v[132:133]
	global_load_lds_dwordx4 v[222:223], off
	v_lshl_add_u64 v[222:223], s[50:51], 0, v[130:131]
	s_add_i32 m0, s49, 0x2000
	s_nop 0
	global_load_lds_dwordx4 v[222:223], off
	v_lshl_add_u64 v[222:223], s[24:25], 0, v[136:137]
	s_mov_b32 m0, s19
	s_nop 0
	global_load_lds_dwordx4 v[222:223], off
	s_mov_b32 m0, s31
	s_nop 0
	global_load_lds_dwordx4 v[224:225], off
	s_waitcnt vmcnt(8)
	s_waitcnt lgkmcnt(0)
	s_setprio 1
	s_barrier
; #define PG8_STAGE(bufoff, gbase, voff) do { _Pragma("unroll") for (int _i = 0; _i < 2; ++_i) \
;         __builtin_amdgcn_global_load_lds((const unsigned*)((const char*)(gbase) + (voff)[_i]), (PG8_LAS unsigned*)(lds + (bufoff) + ldsw + _i * 8192), 16, 0, 0); } while (0)
; #define PG8_WAIT_V(n) asm volatile("s_waitcnt vmcnt(" #n ")" ::: "memory")
; #define PG8_WAIT_L(n) asm volatile("s_waitcnt lgkmcnt(" #n ")" ::: "memory")
; #define PG8_BAR __builtin_amdgcn_s_barrier()
; #define PG8_SCHED __builtin_amdgcn_sched_barrier(0)
; template <class Epi, class Sched, bool ALIGN_EPI = true, bool SP2 = true>
; __device__ __forceinline__ void gemm_phase(PG8_LAS unsigned char* lds, const int K  , const Sched& S, const Epi& E) {
;     ...
;             PG8_WAIT_V(8); PG8_WAIT_L(0); PG8_BAR; PG8_MMA(1, 0, At, B0); PG8_MMA(1, 1, At, B1); PG8_BAR; PG8_SCHED;
;             PG8_LDB(B0, 1, 0); PG8_LDB(B1, 1, 1); PG8_SCHED; PG8_LDA(At, 1, 0); PG8_STAGE(PG8_SA(0, 1), a2 + hstep, voffA);
;             PG8_WAIT_V(8); PG8_WAIT_L(0); PG8_BAR; PG8_MMA(0, 0, At, B0); PG8_MMA(0, 1, At, B1); PG8_BAR; PG8_SCHED;
	v_mfma_f32_16x16x32_bf16 v[62:65], v[146:149], v[186:189], v[62:65]
	v_mfma_f32_16x16x32_bf16 v[54:57], v[162:165], v[186:189], v[54:57]
	v_mfma_f32_16x16x32_bf16 v[46:49], v[146:149], v[194:197], v[46:49]
	v_mfma_f32_16x16x32_bf16 v[38:41], v[162:165], v[194:197], v[38:41]
	v_mfma_f32_16x16x32_bf16 v[30:33], v[146:149], v[202:205], v[30:33]
	v_mfma_f32_16x16x32_bf16 v[22:25], v[162:165], v[202:205], v[22:25]
	v_mfma_f32_16x16x32_bf16 v[14:17], v[146:149], v[210:213], v[14:17]
	v_mfma_f32_16x16x32_bf16 v[6:9], v[162:165], v[210:213], v[6:9]
	v_mfma_f32_16x16x32_bf16 v[62:65], v[158:161], v[190:193], v[62:65]
	v_mfma_f32_16x16x32_bf16 v[54:57], v[166:169], v[190:193], v[54:57]
	v_mfma_f32_16x16x32_bf16 v[46:49], v[158:161], v[198:201], v[46:49]
	v_mfma_f32_16x16x32_bf16 v[38:41], v[166:169], v[198:201], v[38:41]
	v_mfma_f32_16x16x32_bf16 v[30:33], v[158:161], v[206:209], v[30:33]
	v_mfma_f32_16x16x32_bf16 v[22:25], v[166:169], v[206:209], v[22:25]
	v_mfma_f32_16x16x32_bf16 v[14:17], v[158:161], v[214:217], v[14:17]
	v_mfma_f32_16x16x32_bf16 v[6:9], v[166:169], v[214:217], v[6:9]
	s_setprio 0
	s_setprio 1
	v_mfma_f32_16x16x32_bf16 v[58:61], v[170:173], v[186:189], v[58:61]
	v_mfma_f32_16x16x32_bf16 v[50:53], v[178:181], v[186:189], v[50:53]
	v_mfma_f32_16x16x32_bf16 v[42:45], v[170:173], v[194:197], v[42:45]
	v_mfma_f32_16x16x32_bf16 v[34:37], v[178:181], v[194:197], v[34:37]
	v_mfma_f32_16x16x32_bf16 v[26:29], v[170:173], v[202:205], v[26:29]
	v_mfma_f32_16x16x32_bf16 v[18:21], v[178:181], v[202:205], v[18:21]
	v_mfma_f32_16x16x32_bf16 v[10:13], v[170:173], v[210:213], v[10:13]
	v_mfma_f32_16x16x32_bf16 v[2:5], v[178:181], v[210:213], v[2:5]
	v_mfma_f32_16x16x32_bf16 v[58:61], v[174:177], v[190:193], v[58:61]
	v_mfma_f32_16x16x32_bf16 v[50:53], v[182:185], v[190:193], v[50:53]
	v_mfma_f32_16x16x32_bf16 v[42:45], v[174:177], v[198:201], v[42:45]
	v_mfma_f32_16x16x32_bf16 v[34:37], v[182:185], v[198:201], v[34:37]
	s_barrier
	v_mfma_f32_16x16x32_bf16 v[26:29], v[174:177], v[206:209], v[26:29]
	v_mfma_f32_16x16x32_bf16 v[18:21], v[182:185], v[206:209], v[18:21]
	v_mfma_f32_16x16x32_bf16 v[10:13], v[174:177], v[214:217], v[10:13]
	v_mfma_f32_16x16x32_bf16 v[2:5], v[182:185], v[214:217], v[2:5]
	s_setprio 0
	s_add_i32 s49, 0, 0x18000
	v_add_u32_e32 v157, s49, v150
	s_add_i32 s50, 0, 0x1c000
	ds_read_b128 v[146:149], v157
	ds_read_b128 v[158:161], v157 offset:1024
	ds_read_b128 v[162:165], v157 offset:2048
	ds_read_b128 v[166:169], v157 offset:3072
	v_add_u32_e32 v157, s50, v150
	ds_read_b128 v[170:173], v157
	ds_read_b128 v[174:177], v157 offset:1024
	ds_read_b128 v[178:181], v157 offset:2048
	ds_read_b128 v[182:185], v157 offset:3072
	s_add_u32 s24, s24, 0x80000
	s_addc_u32 s25, s25, 0
	s_mov_b32 m0, s33
	v_lshl_add_u64 v[226:227], s[24:25], 0, v[136:137]
	ds_read_b128 v[186:189], v154 offset:32768
	ds_read_b128 v[190:193], v154 offset:33792
	ds_read_b128 v[194:197], v154 offset:34816
	ds_read_b128 v[198:201], v154 offset:35840
	ds_read_b128 v[202:205], v154 offset:36864
	ds_read_b128 v[206:209], v154 offset:37888
	ds_read_b128 v[210:213], v154 offset:38912
	ds_read_b128 v[214:217], v154 offset:39936
	global_load_lds_dwordx4 v[226:227], off
	v_lshl_add_u64 v[226:227], s[24:25], 0, v[132:133]
	s_mov_b32 m0, s34
	s_nop 0
	global_load_lds_dwordx4 v[226:227], off
	s_waitcnt vmcnt(8)
	s_waitcnt lgkmcnt(0)
	s_setprio 1
	s_barrier
	v_mfma_f32_16x16x32_bf16 v[126:129], v[146:149], v[186:189], v[126:129]
	v_mfma_f32_16x16x32_bf16 v[118:121], v[162:165], v[186:189], v[118:121]
	v_mfma_f32_16x16x32_bf16 v[110:113], v[146:149], v[194:197], v[110:113]
	v_mfma_f32_16x16x32_bf16 v[102:105], v[162:165], v[194:197], v[102:105]
	v_mfma_f32_16x16x32_bf16 v[94:97], v[146:149], v[202:205], v[94:97]
	v_mfma_f32_16x16x32_bf16 v[86:89], v[162:165], v[202:205], v[86:89]
	v_mfma_f32_16x16x32_bf16 v[78:81], v[146:149], v[210:213], v[78:81]
	v_mfma_f32_16x16x32_bf16 v[70:73], v[162:165], v[210:213], v[70:73]
	v_mfma_f32_16x16x32_bf16 v[126:129], v[158:161], v[190:193], v[126:129]
	v_mfma_f32_16x16x32_bf16 v[118:121], v[166:169], v[190:193], v[118:121]
	v_mfma_f32_16x16x32_bf16 v[110:113], v[158:161], v[198:201], v[110:113]
	v_mfma_f32_16x16x32_bf16 v[102:105], v[166:169], v[198:201], v[102:105]
	v_mfma_f32_16x16x32_bf16 v[94:97], v[158:161], v[206:209], v[94:97]
	v_mfma_f32_16x16x32_bf16 v[86:89], v[166:169], v[206:209], v[86:89]
	v_mfma_f32_16x16x32_bf16 v[78:81], v[158:161], v[214:217], v[78:81]
	v_mfma_f32_16x16x32_bf16 v[70:73], v[166:169], v[214:217], v[70:73]
	s_setprio 0
	s_setprio 1
	v_mfma_f32_16x16x32_bf16 v[122:125], v[170:173], v[186:189], v[122:125]
	v_mfma_f32_16x16x32_bf16 v[114:117], v[178:181], v[186:189], v[114:117]
	v_mfma_f32_16x16x32_bf16 v[106:109], v[170:173], v[194:197], v[106:109]
	v_mfma_f32_16x16x32_bf16 v[98:101], v[178:181], v[194:197], v[98:101]
	v_mfma_f32_16x16x32_bf16 v[90:93], v[170:173], v[202:205], v[90:93]
	v_mfma_f32_16x16x32_bf16 v[82:85], v[178:181], v[202:205], v[82:85]
	v_mfma_f32_16x16x32_bf16 v[74:77], v[170:173], v[210:213], v[74:77]
	v_mfma_f32_16x16x32_bf16 v[66:69], v[178:181], v[210:213], v[66:69]
	v_mfma_f32_16x16x32_bf16 v[122:125], v[174:177], v[190:193], v[122:125]
	v_mfma_f32_16x16x32_bf16 v[114:117], v[182:185], v[190:193], v[114:117]
	v_mfma_f32_16x16x32_bf16 v[106:109], v[174:177], v[198:201], v[106:109]
	v_mfma_f32_16x16x32_bf16 v[98:101], v[182:185], v[198:201], v[98:101]
	s_barrier
; #define PG8_STAGE(bufoff, gbase, voff) do { _Pragma("unroll") for (int _i = 0; _i < 2; ++_i) \
;         __builtin_amdgcn_global_load_lds((const unsigned*)((const char*)(gbase) + (voff)[_i]), (PG8_LAS unsigned*)(lds + (bufoff) + ldsw + _i * 8192), 16, 0, 0); } while (0)
; #define PG8_WAIT_V(n) asm volatile("s_waitcnt vmcnt(" #n ")" ::: "memory")
; #define PG8_WAIT_L(n) asm volatile("s_waitcnt lgkmcnt(" #n ")" ::: "memory")
; #define PG8_BAR __builtin_amdgcn_s_barrier()
; #define PG8_SCHED __builtin_amdgcn_sched_barrier(0)
; template <class Epi, class Sched, bool ALIGN_EPI = true, bool SP2 = true>
; __device__ __forceinline__ void gemm_phase(PG8_LAS unsigned char* lds, const int K  , const Sched& S, const Epi& E) {
;     ...
;             PG8_WAIT_V(8); PG8_WAIT_L(0); PG8_BAR; PG8_MMA(0, 0, At, B0); PG8_MMA(0, 1, At, B1); PG8_BAR; PG8_SCHED;
;             PG8_LDA(At, 1, 1); PG8_STAGE(PG8_SB(1, 0), b3, voffB); PG8_STAGE(PG8_SB(1, 1), b3 + hstep, voffB); PG8_STAGE(PG8_SA(1, 0), a3, voffA);
;             PG8_WAIT_V(8); PG8_WAIT_L(0); PG8_BAR; PG8_MMA(1, 0, At, B0); PG8_MMA(1, 1, At, B1); PG8_BAR; PG8_SCHED;
	v_mfma_f32_16x16x32_bf16 v[90:93], v[174:177], v[206:209], v[90:93]
	v_mfma_f32_16x16x32_bf16 v[82:85], v[182:185], v[206:209], v[82:85]
	v_mfma_f32_16x16x32_bf16 v[74:77], v[174:177], v[214:217], v[74:77]
	v_mfma_f32_16x16x32_bf16 v[66:69], v[182:185], v[214:217], v[66:69]
	s_setprio 0
	s_add_i32 s24, s49, s28
	v_lshl_add_u64 v[218:219], v[218:219], 0, s[6:7]
	s_mov_b32 m0, s24
	ds_read_b128 v[186:189], v154 offset:49152
	ds_read_b128 v[190:193], v154 offset:50176
	ds_read_b128 v[194:197], v154 offset:51200
	ds_read_b128 v[198:201], v154 offset:52224
	ds_read_b128 v[202:205], v154 offset:53248
	ds_read_b128 v[206:209], v154 offset:54272
	ds_read_b128 v[210:213], v154 offset:55296
	ds_read_b128 v[214:217], v154 offset:56320
	global_load_lds_dwordx4 v[218:219], off
	s_add_i32 m0, s24, 0x2000
	s_add_u32 s22, s22, 0x80080
	v_lshl_add_u64 v[218:219], v[220:221], 0, s[6:7]
	s_addc_u32 s23, s23, 0
	s_add_i32 s24, s50, s28
	global_load_lds_dwordx4 v[218:219], off
	v_lshl_add_u64 v[218:219], s[22:23], 0, v[134:135]
	s_mov_b32 m0, s24
	s_nop 0
	global_load_lds_dwordx4 v[218:219], off
	v_lshl_add_u64 v[218:219], s[22:23], 0, v[130:131]
	s_add_i32 m0, s24, 0x2000
	s_nop 0
	global_load_lds_dwordx4 v[218:219], off
	v_lshl_add_u64 v[218:219], v[222:223], 0, s[6:7]
	s_mov_b32 m0, s36
	s_nop 0
	global_load_lds_dwordx4 v[218:219], off
	v_lshl_add_u64 v[218:219], v[224:225], 0, s[6:7]
	s_mov_b32 m0, s37
	s_nop 0
	global_load_lds_dwordx4 v[218:219], off
	s_waitcnt vmcnt(8)
	s_waitcnt lgkmcnt(0)
	s_setprio 1
	s_barrier
	v_mfma_f32_16x16x32_bf16 v[62:65], v[146:149], v[186:189], v[62:65]
	v_mfma_f32_16x16x32_bf16 v[54:57], v[162:165], v[186:189], v[54:57]
	v_mfma_f32_16x16x32_bf16 v[46:49], v[146:149], v[194:197], v[46:49]
	v_mfma_f32_16x16x32_bf16 v[38:41], v[162:165], v[194:197], v[38:41]
	v_mfma_f32_16x16x32_bf16 v[30:33], v[146:149], v[202:205], v[30:33]
	v_mfma_f32_16x16x32_bf16 v[22:25], v[162:165], v[202:205], v[22:25]
	v_mfma_f32_16x16x32_bf16 v[14:17], v[146:149], v[210:213], v[14:17]
	v_mfma_f32_16x16x32_bf16 v[6:9], v[162:165], v[210:213], v[6:9]
	v_mfma_f32_16x16x32_bf16 v[62:65], v[158:161], v[190:193], v[62:65]
	v_mfma_f32_16x16x32_bf16 v[54:57], v[166:169], v[190:193], v[54:57]
	v_mfma_f32_16x16x32_bf16 v[46:49], v[158:161], v[198:201], v[46:49]
	v_mfma_f32_16x16x32_bf16 v[38:41], v[166:169], v[198:201], v[38:41]
	v_mfma_f32_16x16x32_bf16 v[30:33], v[158:161], v[206:209], v[30:33]
	v_mfma_f32_16x16x32_bf16 v[22:25], v[166:169], v[206:209], v[22:25]
	v_mfma_f32_16x16x32_bf16 v[14:17], v[158:161], v[214:217], v[14:17]
	v_mfma_f32_16x16x32_bf16 v[6:9], v[166:169], v[214:217], v[6:9]
	s_setprio 0
	s_setprio 1
	v_mfma_f32_16x16x32_bf16 v[58:61], v[170:173], v[186:189], v[58:61]
	v_mfma_f32_16x16x32_bf16 v[50:53], v[178:181], v[186:189], v[50:53]
	v_mfma_f32_16x16x32_bf16 v[42:45], v[170:173], v[194:197], v[42:45]
	v_mfma_f32_16x16x32_bf16 v[34:37], v[178:181], v[194:197], v[34:37]
	v_mfma_f32_16x16x32_bf16 v[26:29], v[170:173], v[202:205], v[26:29]
	v_mfma_f32_16x16x32_bf16 v[18:21], v[178:181], v[202:205], v[18:21]
	v_mfma_f32_16x16x32_bf16 v[10:13], v[170:173], v[210:213], v[10:13]
	v_mfma_f32_16x16x32_bf16 v[2:5], v[178:181], v[210:213], v[2:5]
	v_mfma_f32_16x16x32_bf16 v[58:61], v[174:177], v[190:193], v[58:61]
	v_mfma_f32_16x16x32_bf16 v[50:53], v[182:185], v[190:193], v[50:53]
	v_mfma_f32_16x16x32_bf16 v[42:45], v[174:177], v[198:201], v[42:45]
	v_mfma_f32_16x16x32_bf16 v[34:37], v[182:185], v[198:201], v[34:37]
	s_barrier
	v_mfma_f32_16x16x32_bf16 v[26:29], v[174:177], v[206:209], v[26:29]
	v_mfma_f32_16x16x32_bf16 v[18:21], v[182:185], v[206:209], v[18:21]
	v_mfma_f32_16x16x32_bf16 v[10:13], v[174:177], v[214:217], v[10:13]
	v_mfma_f32_16x16x32_bf16 v[2:5], v[182:185], v[214:217], v[2:5]
	s_setprio 0
	s_add_i32 s48, s48, 2
	s_add_u32 s20, s20, 0x100
	s_addc_u32 s21, s21, 0
	s_add_u32 s46, s46, 0x100
	s_addc_u32 s47, s47, 0
	s_cmp_gt_u32 s48, 29
	s_cbranch_scc0 .LBB0_2433
	s_and_b64 vcc, exec, s[8:9]
	s_cbranch_vccz .LBB0_2436
	s_barrier

; #define PG8_STAGE(bufoff, gbase, voff) do { _Pragma("unroll") for (int _i = 0; _i < 2; ++_i) \
;         __builtin_amdgcn_global_load_lds((const unsigned*)((const char*)(gbase) + (voff)[_i]), (PG8_LAS unsigned*)(lds + (bufoff) + ldsw + _i * 8192), 16, 0, 0); } while (0)
; #define PG8_WAIT_V(n) asm volatile("s_waitcnt vmcnt(" #n ")" ::: "memory")
; #define PG8_WAIT_L(n) asm volatile("s_waitcnt lgkmcnt(" #n ")" ::: "memory")
; #define PG8_BAR __builtin_amdgcn_s_barrier()
; #define PG8_SCHED __builtin_amdgcn_sched_barrier(0)
; template <class Epi, class Sched, bool ALIGN_EPI = true, bool SP2 = true>
; __device__ __forceinline__ void gemm_phase(PG8_LAS unsigned char* lds, const int K  , const Sched& S, const Epi& E) {
;     ...
;             const char* a1 = cA + (size_t)(t + 1) * kstep;
;             const char* a2 = last ? nA : cA + (size_t)(t + 2) * kstep; const char* b2 = last ? nB : cB + (size_t)(t + 2) * kstep;
;             const char* a3 = a2 + kstep; const char* b3 = b2 + kstep;
;             if constexpr (SP2) {
;             PG8_LDB(B0, 0, 0); PG8_LDB(B1, 0, 1); PG8_SCHED; PG8_LDA(At, 0, 0); PG8_STAGE(PG8_SA(1, 1), a1 + hstep, voffA);
;             PG8_WAIT_V(8); PG8_WAIT_L(0); PG8_BAR; PG8_MMA(0, 0, At, B0); PG8_MMA(0, 1, At, B1); PG8_BAR; PG8_SCHED;
;             PG8_LDA(At, 0, 1); PG8_STAGE(PG8_SB(0, 0), b2, voffB); PG8_STAGE(PG8_SB(0, 1), b2 + hstep, voffB); PG8_STAGE(PG8_SA(0, 0), a2, voffA);
;             PG8_WAIT_V(8); PG8_WAIT_L(0); PG8_BAR; PG8_MMA(1, 0, At, B0); PG8_MMA(1, 1, At, B1); PG8_BAR; PG8_SCHED;
.LBB0_2516:
	ds_read_b128 v[16:19], v206
	ds_read_b128 v[20:23], v206 offset:1024
	ds_read_b128 v[24:27], v206 offset:2048
	ds_read_b128 v[28:31], v206 offset:3072
	ds_read_b128 v[0:3], v207
	ds_read_b128 v[4:7], v207 offset:1024
	ds_read_b128 v[8:11], v207 offset:2048
	ds_read_b128 v[12:15], v207 offset:3072
	s_add_u32 s18, s16, 0xfff50080
	s_addc_u32 s19, s17, -1
	s_cmp_eq_u32 s57, 40
	s_cselect_b32 s21, s7, s19
	s_cselect_b32 s20, s6, s18
	s_cselect_b32 s19, s15, s56
	s_cselect_b32 s18, s14, s55
	v_lshl_add_u64 v[200:201], s[16:17], 0, v[176:177]
	s_add_i32 m0, s25, 0xc000
	ds_read_b128 v[160:163], v208
	ds_read_b128 v[164:167], v208 offset:1024
	ds_read_b128 v[184:187], v208 offset:2048
	ds_read_b128 v[188:191], v208 offset:3072
	ds_read_b128 v[192:195], v208 offset:4096
	ds_read_b128 v[196:199], v208 offset:5120
	ds_read_b128 v[210:213], v208 offset:6144
	ds_read_b128 v[214:217], v208 offset:7168
	global_load_lds_dwordx4 v[200:201], off
	v_lshl_add_u64 v[200:201], s[16:17], 0, v[178:179]
	s_add_i32 m0, s25, 0xe000
	s_nop 0
	global_load_lds_dwordx4 v[200:201], off
	s_waitcnt vmcnt(8)
	s_waitcnt lgkmcnt(0)
	s_setprio 1
	s_barrier
	v_mfma_scale_f32_16x16x128_f8f6f4 v[156:159], v[16:23], v[160:167], v[156:159], v202, v202 op_sel_hi:[0,0,0]
	v_mfma_scale_f32_16x16x128_f8f6f4 v[152:155], v[24:31], v[160:167], v[152:155], v202, v202 op_sel_hi:[0,0,0]
	v_mfma_scale_f32_16x16x128_f8f6f4 v[140:143], v[16:23], v[184:191], v[140:143], v202, v202 op_sel_hi:[0,0,0]
	v_mfma_scale_f32_16x16x128_f8f6f4 v[136:139], v[24:31], v[184:191], v[136:139], v202, v202 op_sel_hi:[0,0,0]
	v_mfma_scale_f32_16x16x128_f8f6f4 v[124:127], v[16:23], v[192:199], v[124:127], v202, v202 op_sel_hi:[0,0,0]
	v_mfma_scale_f32_16x16x128_f8f6f4 v[120:123], v[24:31], v[192:199], v[120:123], v202, v202 op_sel_hi:[0,0,0]
	v_mfma_scale_f32_16x16x128_f8f6f4 v[108:111], v[16:23], v[210:217], v[108:111], v202, v202 op_sel_hi:[0,0,0]
	v_mfma_scale_f32_16x16x128_f8f6f4 v[104:107], v[24:31], v[210:217], v[104:107], v202, v202 op_sel_hi:[0,0,0]
	s_setprio 0
	s_setprio 1
	v_mfma_scale_f32_16x16x128_f8f6f4 v[148:151], v[0:7], v[160:167], v[148:151], v202, v202 op_sel_hi:[0,0,0]
	v_mfma_scale_f32_16x16x128_f8f6f4 v[144:147], v[8:15], v[160:167], v[144:147], v202, v202 op_sel_hi:[0,0,0]
	v_mfma_scale_f32_16x16x128_f8f6f4 v[132:135], v[0:7], v[184:191], v[132:135], v202, v202 op_sel_hi:[0,0,0]
	v_mfma_scale_f32_16x16x128_f8f6f4 v[128:131], v[8:15], v[184:191], v[128:131], v202, v202 op_sel_hi:[0,0,0]
	v_mfma_scale_f32_16x16x128_f8f6f4 v[116:119], v[0:7], v[192:199], v[116:119], v202, v202 op_sel_hi:[0,0,0]
	v_mfma_scale_f32_16x16x128_f8f6f4 v[112:115], v[8:15], v[192:199], v[112:115], v202, v202 op_sel_hi:[0,0,0]
	s_barrier
	v_mfma_scale_f32_16x16x128_f8f6f4 v[100:103], v[0:7], v[210:217], v[100:103], v202, v202 op_sel_hi:[0,0,0]
	v_mfma_scale_f32_16x16x128_f8f6f4 v[96:99], v[8:15], v[210:217], v[96:99], v202, v202 op_sel_hi:[0,0,0]
	s_setprio 0
	s_add_i32 s58, s38, s24
	v_lshl_add_u64 v[160:161], s[18:19], 0, v[170:171]
	s_mov_b32 m0, s58
	ds_read_b128 v[184:187], v208 offset:16384
	ds_read_b128 v[188:191], v208 offset:17408
	ds_read_b128 v[192:195], v208 offset:18432
	ds_read_b128 v[196:199], v208 offset:19456
	ds_read_b128 v[210:213], v208 offset:20480
	ds_read_b128 v[214:217], v208 offset:21504
	ds_read_b128 v[218:221], v208 offset:22528
	ds_read_b128 v[222:225], v208 offset:23552
	global_load_lds_dwordx4 v[160:161], off
	s_add_i32 m0, s58, 0x2000
	s_add_u32 s58, s18, 0xb0000
	v_lshl_add_u64 v[162:163], s[18:19], 0, v[174:175]
	s_addc_u32 s59, s19, 0
	s_add_i32 s60, s39, s24
	global_load_lds_dwordx4 v[162:163], off
	v_lshl_add_u64 v[164:165], s[58:59], 0, v[170:171]
	s_mov_b32 m0, s60
	v_lshl_add_u64 v[166:167], s[20:21], 0, v[172:173]
	global_load_lds_dwordx4 v[164:165], off
	v_lshl_add_u64 v[164:165], s[58:59], 0, v[174:175]
	s_add_i32 m0, s60, 0x2000
	s_nop 0
	global_load_lds_dwordx4 v[164:165], off
	v_lshl_add_u64 v[164:165], s[20:21], 0, v[168:169]
	s_mov_b32 m0, s25
	s_nop 0
	global_load_lds_dwordx4 v[164:165], off
	s_mov_b32 m0, s26
	s_nop 0
	global_load_lds_dwordx4 v[166:167], off
	s_waitcnt vmcnt(8)
	s_waitcnt lgkmcnt(0)
	s_setprio 1
	s_barrier
	v_mfma_scale_f32_16x16x128_f8f6f4 v[92:95], v[16:23], v[184:191], v[92:95], v202, v202 op_sel_hi:[0,0,0]
	v_mfma_scale_f32_16x16x128_f8f6f4 v[88:91], v[24:31], v[184:191], v[88:91], v202, v202 op_sel_hi:[0,0,0]
	v_mfma_scale_f32_16x16x128_f8f6f4 v[76:79], v[16:23], v[192:199], v[76:79], v202, v202 op_sel_hi:[0,0,0]
	v_mfma_scale_f32_16x16x128_f8f6f4 v[72:75], v[24:31], v[192:199], v[72:75], v202, v202 op_sel_hi:[0,0,0]
	v_mfma_scale_f32_16x16x128_f8f6f4 v[60:63], v[16:23], v[210:217], v[60:63], v202, v202 op_sel_hi:[0,0,0]
	v_mfma_scale_f32_16x16x128_f8f6f4 v[56:59], v[24:31], v[210:217], v[56:59], v202, v202 op_sel_hi:[0,0,0]
	v_mfma_scale_f32_16x16x128_f8f6f4 v[44:47], v[16:23], v[218:225], v[44:47], v202, v202 op_sel_hi:[0,0,0]
	v_mfma_scale_f32_16x16x128_f8f6f4 v[40:43], v[24:31], v[218:225], v[40:43], v202, v202 op_sel_hi:[0,0,0]
	s_setprio 0
	s_setprio 1
	v_mfma_scale_f32_16x16x128_f8f6f4 v[84:87], v[0:7], v[184:191], v[84:87], v202, v202 op_sel_hi:[0,0,0]
	v_mfma_scale_f32_16x16x128_f8f6f4 v[80:83], v[8:15], v[184:191], v[80:83], v202, v202 op_sel_hi:[0,0,0]
	v_mfma_scale_f32_16x16x128_f8f6f4 v[68:71], v[0:7], v[192:199], v[68:71], v202, v202 op_sel_hi:[0,0,0]
	v_mfma_scale_f32_16x16x128_f8f6f4 v[64:67], v[8:15], v[192:199], v[64:67], v202, v202 op_sel_hi:[0,0,0]
	v_mfma_scale_f32_16x16x128_f8f6f4 v[52:55], v[0:7], v[210:217], v[52:55], v202, v202 op_sel_hi:[0,0,0]
	v_mfma_scale_f32_16x16x128_f8f6f4 v[48:51], v[8:15], v[210:217], v[48:51], v202, v202 op_sel_hi:[0,0,0]
	s_barrier
; #define PG8_STAGE(bufoff, gbase, voff) do { _Pragma("unroll") for (int _i = 0; _i < 2; ++_i) \
;         __builtin_amdgcn_global_load_lds((const unsigned*)((const char*)(gbase) + (voff)[_i]), (PG8_LAS unsigned*)(lds + (bufoff) + ldsw + _i * 8192), 16, 0, 0); } while (0)
; #define PG8_WAIT_V(n) asm volatile("s_waitcnt vmcnt(" #n ")" ::: "memory")
; #define PG8_WAIT_L(n) asm volatile("s_waitcnt lgkmcnt(" #n ")" ::: "memory")
; #define PG8_BAR __builtin_amdgcn_s_barrier()
; #define PG8_SCHED __builtin_amdgcn_sched_barrier(0)
; template <class Epi, class Sched, bool ALIGN_EPI = true, bool SP2 = true>
; __device__ __forceinline__ void gemm_phase(PG8_LAS unsigned char* lds, const int K  , const Sched& S, const Epi& E) {
;     ...
;             PG8_LDB(B0, 1, 0); PG8_LDB(B1, 1, 1); PG8_SCHED; PG8_LDA(At, 1, 0); PG8_STAGE(PG8_SA(0, 1), a2 + hstep, voffA);
;             PG8_WAIT_V(8); PG8_WAIT_L(0); PG8_BAR; PG8_MMA(0, 0, At, B0); PG8_MMA(0, 1, At, B1); PG8_BAR; PG8_SCHED;
;             PG8_LDA(At, 1, 1); PG8_STAGE(PG8_SB(1, 0), b3, voffB); PG8_STAGE(PG8_SB(1, 1), b3 + hstep, voffB); PG8_STAGE(PG8_SA(1, 0), a3, voffA);
;             PG8_WAIT_V(8); PG8_WAIT_L(0); PG8_BAR; PG8_MMA(1, 0, At, B0); PG8_MMA(1, 1, At, B1); PG8_BAR; PG8_SCHED;
;     ...
;         if constexpr (Epi::FP8) asm volatile("s_nop 15\n\ts_nop 15\n\ts_nop 15\n\ts_nop 15\n\ts_nop 15" ::: "memory");
;         if constexpr (ALIGN_EPI) { if (wr == 0) PG8_BAR; }
	v_mfma_scale_f32_16x16x128_f8f6f4 v[36:39], v[0:7], v[218:225], v[36:39], v202, v202 op_sel_hi:[0,0,0]
	v_mfma_scale_f32_16x16x128_f8f6f4 v[32:35], v[8:15], v[218:225], v[32:35], v202, v202 op_sel_hi:[0,0,0]
	s_setprio 0
	s_add_i32 s58, 0, 0x18000
	s_add_i32 s59, 0, 0x1c000
	v_add_u32_e32 v12, s58, v204
	v_add_u32_e32 v28, s59, v204
	ds_read_b128 v[0:3], v12
	ds_read_b128 v[4:7], v12 offset:1024
	ds_read_b128 v[8:11], v12 offset:2048
	ds_read_b128 v[12:15], v12 offset:3072
	ds_read_b128 v[16:19], v28
	ds_read_b128 v[20:23], v28 offset:1024
	ds_read_b128 v[24:27], v28 offset:2048
	ds_read_b128 v[28:31], v28 offset:3072
	s_add_u32 s20, s20, 0xb0000
	s_addc_u32 s21, s21, 0
	s_mov_b32 m0, s27
	v_lshl_add_u64 v[200:201], s[20:21], 0, v[168:169]
	ds_read_b128 v[184:187], v208 offset:32768
	ds_read_b128 v[188:191], v208 offset:33792
	ds_read_b128 v[192:195], v208 offset:34816
	ds_read_b128 v[196:199], v208 offset:35840
	ds_read_b128 v[210:213], v208 offset:36864
	ds_read_b128 v[214:217], v208 offset:37888
	ds_read_b128 v[218:221], v208 offset:38912
	ds_read_b128 v[222:225], v208 offset:39936
	global_load_lds_dwordx4 v[200:201], off
	v_lshl_add_u64 v[200:201], s[20:21], 0, v[172:173]
	s_mov_b32 m0, s28
	s_nop 0
	global_load_lds_dwordx4 v[200:201], off
	s_waitcnt vmcnt(8)
	s_waitcnt lgkmcnt(0)
	s_setprio 1
	s_barrier
	v_mfma_scale_f32_16x16x128_f8f6f4 v[156:159], v[0:7], v[184:191], v[156:159], v202, v202 op_sel_hi:[0,0,0]
	v_mfma_scale_f32_16x16x128_f8f6f4 v[152:155], v[8:15], v[184:191], v[152:155], v202, v202 op_sel_hi:[0,0,0]
	v_mfma_scale_f32_16x16x128_f8f6f4 v[140:143], v[0:7], v[192:199], v[140:143], v202, v202 op_sel_hi:[0,0,0]
	v_mfma_scale_f32_16x16x128_f8f6f4 v[136:139], v[8:15], v[192:199], v[136:139], v202, v202 op_sel_hi:[0,0,0]
	v_mfma_scale_f32_16x16x128_f8f6f4 v[124:127], v[0:7], v[210:217], v[124:127], v202, v202 op_sel_hi:[0,0,0]
	v_mfma_scale_f32_16x16x128_f8f6f4 v[120:123], v[8:15], v[210:217], v[120:123], v202, v202 op_sel_hi:[0,0,0]
	v_mfma_scale_f32_16x16x128_f8f6f4 v[108:111], v[0:7], v[218:225], v[108:111], v202, v202 op_sel_hi:[0,0,0]
	v_mfma_scale_f32_16x16x128_f8f6f4 v[104:107], v[8:15], v[218:225], v[104:107], v202, v202 op_sel_hi:[0,0,0]
	s_setprio 0
	s_setprio 1
	v_mfma_scale_f32_16x16x128_f8f6f4 v[148:151], v[16:23], v[184:191], v[148:151], v202, v202 op_sel_hi:[0,0,0]
	v_mfma_scale_f32_16x16x128_f8f6f4 v[144:147], v[24:31], v[184:191], v[144:147], v202, v202 op_sel_hi:[0,0,0]
	v_mfma_scale_f32_16x16x128_f8f6f4 v[132:135], v[16:23], v[192:199], v[132:135], v202, v202 op_sel_hi:[0,0,0]
	v_mfma_scale_f32_16x16x128_f8f6f4 v[128:131], v[24:31], v[192:199], v[128:131], v202, v202 op_sel_hi:[0,0,0]
	v_mfma_scale_f32_16x16x128_f8f6f4 v[116:119], v[16:23], v[210:217], v[116:119], v202, v202 op_sel_hi:[0,0,0]
	v_mfma_scale_f32_16x16x128_f8f6f4 v[112:115], v[24:31], v[210:217], v[112:115], v202, v202 op_sel_hi:[0,0,0]
	s_barrier
	v_mfma_scale_f32_16x16x128_f8f6f4 v[100:103], v[16:23], v[218:225], v[100:103], v202, v202 op_sel_hi:[0,0,0]
	v_mfma_scale_f32_16x16x128_f8f6f4 v[96:99], v[24:31], v[218:225], v[96:99], v202, v202 op_sel_hi:[0,0,0]
	s_setprio 0
	s_add_i32 s20, s58, s24
	v_lshl_add_u64 v[160:161], v[160:161], 0, s[8:9]
	s_mov_b32 m0, s20
	ds_read_b128 v[184:187], v208 offset:49152
	ds_read_b128 v[188:191], v208 offset:50176
	ds_read_b128 v[192:195], v208 offset:51200
	ds_read_b128 v[196:199], v208 offset:52224
	ds_read_b128 v[210:213], v208 offset:53248
	ds_read_b128 v[214:217], v208 offset:54272
	ds_read_b128 v[218:221], v208 offset:55296
	ds_read_b128 v[222:225], v208 offset:56320
	global_load_lds_dwordx4 v[160:161], off
	s_add_i32 m0, s20, 0x2000
	s_add_u32 s18, s18, 0xb0080
	v_lshl_add_u64 v[160:161], v[162:163], 0, s[8:9]
	s_addc_u32 s19, s19, 0
	s_add_i32 s20, s59, s24
	global_load_lds_dwordx4 v[160:161], off
	v_lshl_add_u64 v[160:161], s[18:19], 0, v[170:171]
	s_mov_b32 m0, s20
	s_nop 0
	global_load_lds_dwordx4 v[160:161], off
	v_lshl_add_u64 v[160:161], s[18:19], 0, v[174:175]
	s_add_i32 m0, s20, 0x2000
	s_nop 0
	global_load_lds_dwordx4 v[160:161], off
	v_lshl_add_u64 v[160:161], v[164:165], 0, s[8:9]
	s_mov_b32 m0, s35
	s_nop 0
	global_load_lds_dwordx4 v[160:161], off
	v_lshl_add_u64 v[160:161], v[166:167], 0, s[8:9]
	s_mov_b32 m0, s36
	s_nop 0
	global_load_lds_dwordx4 v[160:161], off
	s_waitcnt vmcnt(8)
	s_waitcnt lgkmcnt(0)
	s_setprio 1
	s_barrier
	v_mfma_scale_f32_16x16x128_f8f6f4 v[92:95], v[0:7], v[184:191], v[92:95], v202, v202 op_sel_hi:[0,0,0]
	v_mfma_scale_f32_16x16x128_f8f6f4 v[88:91], v[8:15], v[184:191], v[88:91], v202, v202 op_sel_hi:[0,0,0]
	v_mfma_scale_f32_16x16x128_f8f6f4 v[76:79], v[0:7], v[192:199], v[76:79], v202, v202 op_sel_hi:[0,0,0]
	v_mfma_scale_f32_16x16x128_f8f6f4 v[72:75], v[8:15], v[192:199], v[72:75], v202, v202 op_sel_hi:[0,0,0]
	v_mfma_scale_f32_16x16x128_f8f6f4 v[60:63], v[0:7], v[210:217], v[60:63], v202, v202 op_sel_hi:[0,0,0]
	v_mfma_scale_f32_16x16x128_f8f6f4 v[56:59], v[8:15], v[210:217], v[56:59], v202, v202 op_sel_hi:[0,0,0]
	v_mfma_scale_f32_16x16x128_f8f6f4 v[44:47], v[0:7], v[218:225], v[44:47], v202, v202 op_sel_hi:[0,0,0]
	v_mfma_scale_f32_16x16x128_f8f6f4 v[40:43], v[8:15], v[218:225], v[40:43], v202, v202 op_sel_hi:[0,0,0]
	s_setprio 0
	s_setprio 1
	v_mfma_scale_f32_16x16x128_f8f6f4 v[84:87], v[16:23], v[184:191], v[84:87], v202, v202 op_sel_hi:[0,0,0]
	v_mfma_scale_f32_16x16x128_f8f6f4 v[80:83], v[24:31], v[184:191], v[80:83], v202, v202 op_sel_hi:[0,0,0]
	v_mfma_scale_f32_16x16x128_f8f6f4 v[68:71], v[16:23], v[192:199], v[68:71], v202, v202 op_sel_hi:[0,0,0]
	v_mfma_scale_f32_16x16x128_f8f6f4 v[64:67], v[24:31], v[192:199], v[64:67], v202, v202 op_sel_hi:[0,0,0]
	v_mfma_scale_f32_16x16x128_f8f6f4 v[52:55], v[16:23], v[210:217], v[52:55], v202, v202 op_sel_hi:[0,0,0]
	v_mfma_scale_f32_16x16x128_f8f6f4 v[48:51], v[24:31], v[210:217], v[48:51], v202, v202 op_sel_hi:[0,0,0]
	s_barrier
	v_mfma_scale_f32_16x16x128_f8f6f4 v[36:39], v[16:23], v[218:225], v[36:39], v202, v202 op_sel_hi:[0,0,0]
	v_mfma_scale_f32_16x16x128_f8f6f4 v[32:35], v[24:31], v[218:225], v[32:35], v202, v202 op_sel_hi:[0,0,0]
	s_setprio 0
	s_add_i32 s57, s57, 2
	s_add_u32 s16, s16, 0x100
	s_addc_u32 s17, s17, 0
	s_add_u32 s55, s55, 0x100
	s_addc_u32 s56, s56, 0
	s_cmp_gt_u32 s57, 41
	s_cbranch_scc0 .LBB0_2516
	s_nop 15
	s_nop 15
	s_nop 15
	s_nop 15
	s_nop 15
	s_and_b64 vcc, exec, s[10:11]
	s_cbranch_vccz .LBB0_2519
	s_barrier
